# v23 + GEMM k-loops: per-phase s_setprio flips deleted, one static s_setprio 1 for waves 4-7 during each unit's k-loop (cleared at loop exit)
# speedup vs baseline: 1.0136x; 1.0095x over previous
.LBB0_211:
	s_cmp_ge_u32 s53, 0x1000
	s_cbranch_scc0 .Lprio_done_3
	s_setprio 1
.Lprio_done_3:
	s_add_i32 s60, s60, 1
	s_mov_b64 s[36:37], s[18:19]
	s_mul_i32 s18, s60, s26
	s_add_i32 s38, s18, s2
	s_cmpk_gt_i32 s38, 0x1ff
	s_cselect_b64 s[44:45], -1, 0
	s_lshl_b32 s18, s38, 3
	s_and_b32 s18, s18, 56
	s_bfe_u32 s19, s38, 0x30003
	s_mov_b32 s27, s61
	s_or_b32 s61, s18, s19
	s_mov_b32 s3, s42
	s_ashr_i32 s42, s38, 6
	s_lshl_b32 s18, s61, 19
	s_mov_b64 s[4:5], s[20:21]
	s_add_u32 s20, s14, s18
	s_addc_u32 s21, s15, 0
	s_ashr_i32 s43, s42, 31
	s_lshl_b64 s[18:19], s[42:43], 19
	s_add_u32 s18, s16, s18
	s_addc_u32 s19, s17, s19
	s_cmpk_lt_i32 s38, 0x200
	s_cselect_b32 s38, s21, s5
	s_cselect_b32 s43, s20, s4
	s_cselect_b32 s62, s19, s37
	s_cselect_b32 s63, s18, s36
	s_add_u32 s64, s36, 0x100
	s_addc_u32 s65, s37, 0
	s_mov_b32 s66, -2
	s_waitcnt lgkmcnt(0)
	s_add_u32 s36, s4, 0x100
	s_addc_u32 s37, s5, 0
	s_add_i32 s67, 0, 0x10000
	v_add_u32_e32 v1, s67, v191
	ds_read_b128 v[34:37], v1
	ds_read_b128 v[38:41], v1 offset:1024
	ds_read_b128 v[42:45], v1 offset:2048
	ds_read_b128 v[46:49], v1 offset:3072
	s_cmp_eq_u32 s66, 12
	s_cselect_b32 s49, s38, s37
	s_cselect_b32 s48, s43, s36
	s_cselect_b32 s47, s62, s65
	s_cselect_b32 s46, s63, s64
	v_lshl_add_u64 v[186:187], s[4:5], 0, v[168:169]
	s_add_i32 m0, s53, 0xc000
	ds_read_b128 v[50:53], v206
	ds_read_b128 v[58:61], v206 offset:1024
	ds_read_b128 v[62:65], v206 offset:2048
	ds_read_b128 v[66:69], v206 offset:3072
	ds_read_b128 v[170:173], v206 offset:4096
	ds_read_b128 v[174:177], v206 offset:5120
	ds_read_b128 v[178:181], v206 offset:6144
	ds_read_b128 v[182:185], v206 offset:7168
	global_load_lds_dwordx4 v[186:187], off
	v_lshl_add_u64 v[186:187], s[4:5], 0, v[166:167]
	s_add_i32 m0, s53, 0xe000
	s_nop 0
	global_load_lds_dwordx4 v[186:187], off
	s_waitcnt lgkmcnt(8)
	s_barrier
	s_waitcnt lgkmcnt(0)
	s_waitcnt lgkmcnt(0)
	v_mfma_f32_16x16x32_bf16 v[158:161], v[34:37], v[50:53], 0
	v_mfma_f32_16x16x32_bf16 v[154:157], v[42:45], v[50:53], 0
	v_mfma_f32_16x16x32_bf16 v[142:145], v[34:37], v[62:65], 0
	v_mfma_f32_16x16x32_bf16 v[138:141], v[42:45], v[62:65], 0
	v_mfma_f32_16x16x32_bf16 v[126:129], v[34:37], v[170:173], 0
	v_mfma_f32_16x16x32_bf16 v[122:125], v[42:45], v[170:173], 0
	v_mfma_f32_16x16x32_bf16 v[110:113], v[34:37], v[178:181], 0
	v_mfma_f32_16x16x32_bf16 v[106:109], v[42:45], v[178:181], 0
	v_mfma_f32_16x16x32_bf16 v[158:161], v[38:41], v[58:61], v[158:161]
	v_mfma_f32_16x16x32_bf16 v[154:157], v[46:49], v[58:61], v[154:157]
	v_mfma_f32_16x16x32_bf16 v[142:145], v[38:41], v[66:69], v[142:145]
	v_mfma_f32_16x16x32_bf16 v[138:141], v[46:49], v[66:69], v[138:141]
	v_mfma_f32_16x16x32_bf16 v[126:129], v[38:41], v[174:177], v[126:129]
	v_mfma_f32_16x16x32_bf16 v[122:125], v[46:49], v[174:177], v[122:125]
	v_mfma_f32_16x16x32_bf16 v[110:113], v[38:41], v[182:185], v[110:113]
	v_mfma_f32_16x16x32_bf16 v[106:109], v[46:49], v[182:185], v[106:109]
	s_barrier
	v_mbcnt_lo_u32_b32 v250, -1, 0
	v_mbcnt_hi_u32_b32 v250, -1, v250
	v_lshlrev_b32_e32 v250, 4, v250
	s_lshl_b32 s32, s3, 10
	s_add_u32 s90, s8, s32
	s_addc_u32 s91, s9, 0
	s_add_u32 s92, s10, s32
	s_addc_u32 s93, s11, 0
	s_mov_b32 m0, 0x20840
	s_nop 0
	global_load_lds_dwordx4 v250, s[90:91]
	s_mov_b32 m0, 0x20c40
	s_nop 0
	global_load_lds_dwordx4 v250, s[92:93]
	s_add_i32 s68, 0, 0x14000
	s_add_i32 s4, s67, s52
	v_add_u32_e32 v1, s68, v191
	v_lshl_add_u64 v[214:215], s[46:47], 0, v[164:165]
	s_mov_b32 m0, s4
	ds_read_b128 v[186:189], v1
	ds_read_b128 v[208:211], v1 offset:1024
	ds_read_b128 v[222:225], v1 offset:2048
	ds_read_b128 v[226:229], v1 offset:3072
	global_load_lds_dwordx4 v[214:215], off
	v_lshl_add_u64 v[238:239], s[46:47], 0, v[162:163]
	s_add_i32 m0, s4, 0x2000
	s_nop 0
	global_load_lds_dwordx4 v[238:239], off
	s_barrier
	s_waitcnt lgkmcnt(0)
	s_waitcnt lgkmcnt(0)
	v_mfma_f32_16x16x32_bf16 v[150:153], v[186:189], v[50:53], 0
	v_mfma_f32_16x16x32_bf16 v[50:53], v[222:225], v[50:53], 0
	v_mfma_f32_16x16x32_bf16 v[150:153], v[208:211], v[58:61], v[150:153]
	v_mfma_f32_16x16x32_bf16 v[50:53], v[226:229], v[58:61], v[50:53]
	v_mfma_f32_16x16x32_bf16 v[58:61], v[186:189], v[62:65], 0
	v_mfma_f32_16x16x32_bf16 v[62:65], v[222:225], v[62:65], 0
	v_mfma_f32_16x16x32_bf16 v[114:117], v[222:225], v[170:173], 0
	v_mfma_f32_16x16x32_bf16 v[102:105], v[186:189], v[178:181], 0
	v_mfma_f32_16x16x32_bf16 v[98:101], v[222:225], v[178:181], 0
	v_mfma_f32_16x16x32_bf16 v[58:61], v[208:211], v[66:69], v[58:61]
	v_mfma_f32_16x16x32_bf16 v[62:65], v[226:229], v[66:69], v[62:65]
	v_mfma_f32_16x16x32_bf16 v[66:69], v[186:189], v[170:173], 0
	v_mfma_f32_16x16x32_bf16 v[114:117], v[226:229], v[174:177], v[114:117]
	v_mfma_f32_16x16x32_bf16 v[102:105], v[208:211], v[182:185], v[102:105]
	v_mfma_f32_16x16x32_bf16 v[98:101], v[226:229], v[182:185], v[98:101]
	v_mfma_f32_16x16x32_bf16 v[66:69], v[208:211], v[174:177], v[66:69]
	s_mov_b32 m0, s53
	v_lshl_add_u64 v[240:241], s[48:49], 0, v[164:165]
	s_barrier
	ds_read_b128 v[118:121], v206 offset:16384
	ds_read_b128 v[130:133], v206 offset:17408
	ds_read_b128 v[134:137], v206 offset:18432
	ds_read_b128 v[146:149], v206 offset:19456
	ds_read_b128 v[170:173], v206 offset:20480
	ds_read_b128 v[174:177], v206 offset:21504
	ds_read_b128 v[178:181], v206 offset:22528
	ds_read_b128 v[182:185], v206 offset:23552
	global_load_lds_dwordx4 v[240:241], off
	v_lshl_add_u64 v[242:243], s[48:49], 0, v[162:163]
	s_mov_b32 m0, s54
	s_nop 0
	global_load_lds_dwordx4 v[242:243], off
	s_barrier
	s_waitcnt lgkmcnt(0)
	s_waitcnt lgkmcnt(0)
	v_mfma_f32_16x16x32_bf16 v[94:97], v[34:37], v[118:121], 0
	v_mfma_f32_16x16x32_bf16 v[90:93], v[42:45], v[118:121], 0
	v_mfma_f32_16x16x32_bf16 v[78:81], v[34:37], v[134:137], 0
	v_mfma_f32_16x16x32_bf16 v[74:77], v[42:45], v[134:137], 0
	v_mfma_f32_16x16x32_bf16 v[30:33], v[34:37], v[170:173], 0
	v_mfma_f32_16x16x32_bf16 v[26:29], v[42:45], v[170:173], 0
	v_mfma_f32_16x16x32_bf16 v[14:17], v[34:37], v[178:181], 0
	v_mfma_f32_16x16x32_bf16 v[10:13], v[42:45], v[178:181], 0
	v_mfma_f32_16x16x32_bf16 v[94:97], v[38:41], v[130:133], v[94:97]
	v_mfma_f32_16x16x32_bf16 v[90:93], v[46:49], v[130:133], v[90:93]
	v_mfma_f32_16x16x32_bf16 v[78:81], v[38:41], v[146:149], v[78:81]
	v_mfma_f32_16x16x32_bf16 v[74:77], v[46:49], v[146:149], v[74:77]
	v_mfma_f32_16x16x32_bf16 v[30:33], v[38:41], v[174:177], v[30:33]
	v_mfma_f32_16x16x32_bf16 v[26:29], v[46:49], v[174:177], v[26:29]
	v_mfma_f32_16x16x32_bf16 v[14:17], v[38:41], v[182:185], v[14:17]
	v_mfma_f32_16x16x32_bf16 v[10:13], v[46:49], v[182:185], v[10:13]
	s_barrier
	s_add_u32 s4, s46, 0x40000
	s_addc_u32 s5, s47, 0
	s_add_i32 s67, s68, s52
	v_lshl_add_u64 v[34:35], s[4:5], 0, v[164:165]
	s_mov_b32 m0, s67
	s_nop 0
	global_load_lds_dwordx4 v[34:35], off
	v_lshl_add_u64 v[34:35], s[4:5], 0, v[162:163]
	s_add_i32 m0, s67, 0x2000
	s_nop 0
	global_load_lds_dwordx4 v[34:35], off
	s_waitcnt vmcnt(6)
	s_barrier
	v_mfma_f32_16x16x32_bf16 v[22:25], v[186:189], v[170:173], 0
	v_mfma_f32_16x16x32_bf16 v[18:21], v[222:225], v[170:173], 0
	v_mfma_f32_16x16x32_bf16 v[6:9], v[186:189], v[178:181], 0
	v_mfma_f32_16x16x32_bf16 v[2:5], v[222:225], v[178:181], 0
	v_mfma_f32_16x16x32_bf16 v[34:37], v[186:189], v[118:121], 0
	v_mfma_f32_16x16x32_bf16 v[38:41], v[222:225], v[118:121], 0
	v_mfma_f32_16x16x32_bf16 v[42:45], v[186:189], v[134:137], 0
	v_mfma_f32_16x16x32_bf16 v[46:49], v[222:225], v[134:137], 0
	v_mfma_f32_16x16x32_bf16 v[22:25], v[208:211], v[174:177], v[22:25]
	v_mfma_f32_16x16x32_bf16 v[18:21], v[226:229], v[174:177], v[18:21]
	v_mfma_f32_16x16x32_bf16 v[6:9], v[208:211], v[182:185], v[6:9]
	v_mfma_f32_16x16x32_bf16 v[2:5], v[226:229], v[182:185], v[2:5]
	v_mfma_f32_16x16x32_bf16 v[34:37], v[208:211], v[130:133], v[34:37]
	v_mfma_f32_16x16x32_bf16 v[38:41], v[226:229], v[130:133], v[38:41]
	v_mfma_f32_16x16x32_bf16 v[42:45], v[208:211], v[146:149], v[42:45]
	v_mfma_f32_16x16x32_bf16 v[46:49], v[226:229], v[146:149], v[46:49]
	s_add_i32 s67, 0, 0x18000
	v_add_u32_e32 v1, s67, v191
	s_barrier
	ds_read_b128 v[54:57], v1
	ds_read_b128 v[70:73], v1 offset:1024
	ds_read_b128 v[82:85], v1 offset:2048
	ds_read_b128 v[86:89], v1 offset:3072
	s_add_u32 s4, s48, 0x40000
	s_addc_u32 s5, s49, 0
	s_mov_b32 m0, s55
	v_lshl_add_u64 v[134:135], s[4:5], 0, v[164:165]
	ds_read_b128 v[118:121], v206 offset:32768
	ds_read_b128 v[130:133], v206 offset:33792
	ds_read_b128 v[170:173], v206 offset:34816
	ds_read_b128 v[174:177], v206 offset:35840
	ds_read_b128 v[178:181], v206 offset:36864
	ds_read_b128 v[182:185], v206 offset:37888
	ds_read_b128 v[186:189], v206 offset:38912
	ds_read_b128 v[208:211], v206 offset:39936
	global_load_lds_dwordx4 v[134:135], off
	v_lshl_add_u64 v[134:135], s[4:5], 0, v[162:163]
	s_mov_b32 m0, s56
	s_nop 0
	global_load_lds_dwordx4 v[134:135], off
	s_waitcnt lgkmcnt(8)
	s_barrier
	s_waitcnt lgkmcnt(0)
	s_waitcnt lgkmcnt(0)
	v_mfma_f32_16x16x32_bf16 v[134:137], v[54:57], v[118:121], v[158:161]
	v_mfma_f32_16x16x32_bf16 v[158:161], v[70:73], v[130:133], v[134:137]
	v_mfma_f32_16x16x32_bf16 v[134:137], v[82:85], v[118:121], v[154:157]
	v_mfma_f32_16x16x32_bf16 v[154:157], v[86:89], v[130:133], v[134:137]
	v_mfma_f32_16x16x32_bf16 v[134:137], v[54:57], v[170:173], v[142:145]
	v_mfma_f32_16x16x32_bf16 v[142:145], v[70:73], v[174:177], v[134:137]
	v_mfma_f32_16x16x32_bf16 v[134:137], v[82:85], v[170:173], v[138:141]
	v_mfma_f32_16x16x32_bf16 v[126:129], v[54:57], v[178:181], v[126:129]
	v_mfma_f32_16x16x32_bf16 v[122:125], v[82:85], v[178:181], v[122:125]
	v_mfma_f32_16x16x32_bf16 v[110:113], v[54:57], v[186:189], v[110:113]
	v_mfma_f32_16x16x32_bf16 v[106:109], v[82:85], v[186:189], v[106:109]
	v_mfma_f32_16x16x32_bf16 v[138:141], v[86:89], v[174:177], v[134:137]
	v_mfma_f32_16x16x32_bf16 v[126:129], v[70:73], v[182:185], v[126:129]
	v_mfma_f32_16x16x32_bf16 v[122:125], v[86:89], v[182:185], v[122:125]
	v_mfma_f32_16x16x32_bf16 v[110:113], v[70:73], v[208:211], v[110:113]
	v_mfma_f32_16x16x32_bf16 v[106:109], v[86:89], v[208:211], v[106:109]
	s_barrier
	s_add_i32 s48, 0, 0x1c000
	s_add_i32 s4, s67, s52
	v_add_u32_e32 v1, s48, v191
	v_lshl_add_u64 v[134:135], v[214:215], 0, s[22:23]
	s_mov_b32 m0, s4
	ds_read_b128 v[222:225], v1
	ds_read_b128 v[226:229], v1 offset:1024
	ds_read_b128 v[230:233], v1 offset:2048
	ds_read_b128 v[234:237], v1 offset:3072
	global_load_lds_dwordx4 v[134:135], off
	v_lshl_add_u64 v[134:135], v[238:239], 0, s[22:23]
	s_add_i32 m0, s4, 0x2000
	s_nop 0
	global_load_lds_dwordx4 v[134:135], off
	s_barrier
	s_waitcnt lgkmcnt(0)
	s_waitcnt lgkmcnt(0)
	v_mfma_f32_16x16x32_bf16 v[50:53], v[230:233], v[118:121], v[50:53]
	v_mfma_f32_16x16x32_bf16 v[134:137], v[222:225], v[118:121], v[150:153]
	v_mfma_f32_16x16x32_bf16 v[146:149], v[234:237], v[130:133], v[50:53]
	v_mfma_f32_16x16x32_bf16 v[50:53], v[222:225], v[170:173], v[58:61]
	v_mfma_f32_16x16x32_bf16 v[150:153], v[226:229], v[130:133], v[134:137]
	v_mfma_f32_16x16x32_bf16 v[134:137], v[226:229], v[174:177], v[50:53]
	v_mfma_f32_16x16x32_bf16 v[50:53], v[230:233], v[170:173], v[62:65]
	v_mfma_f32_16x16x32_bf16 v[130:133], v[234:237], v[174:177], v[50:53]
	v_mfma_f32_16x16x32_bf16 v[50:53], v[222:225], v[178:181], v[66:69]
	v_mfma_f32_16x16x32_bf16 v[118:121], v[226:229], v[182:185], v[50:53]
	v_mfma_f32_16x16x32_bf16 v[50:53], v[230:233], v[178:181], v[114:117]
	v_mfma_f32_16x16x32_bf16 v[114:117], v[234:237], v[182:185], v[50:53]
	v_mfma_f32_16x16x32_bf16 v[50:53], v[222:225], v[186:189], v[102:105]
	v_mfma_f32_16x16x32_bf16 v[102:105], v[226:229], v[208:211], v[50:53]
	v_mfma_f32_16x16x32_bf16 v[50:53], v[230:233], v[186:189], v[98:101]
	v_mfma_f32_16x16x32_bf16 v[98:101], v[234:237], v[208:211], v[50:53]
	s_mov_b32 m0, s58
	v_lshl_add_u64 v[186:187], v[240:241], 0, s[22:23]
	s_barrier
	s_nop 2
	ds_read_b128 v[50:53], v206 offset:49152
	ds_read_b128 v[58:61], v206 offset:50176
	ds_read_b128 v[62:65], v206 offset:51200
	ds_read_b128 v[66:69], v206 offset:52224
	ds_read_b128 v[170:173], v206 offset:53248
	ds_read_b128 v[174:177], v206 offset:54272
	ds_read_b128 v[178:181], v206 offset:55296
	ds_read_b128 v[182:185], v206 offset:56320
	global_load_lds_dwordx4 v[186:187], off
	v_lshl_add_u64 v[186:187], v[242:243], 0, s[22:23]
	s_mov_b32 m0, s59
	s_nop 0
	global_load_lds_dwordx4 v[186:187], off
	s_barrier
	s_waitcnt lgkmcnt(0)
	s_waitcnt lgkmcnt(0)
	v_mfma_f32_16x16x32_bf16 v[94:97], v[54:57], v[50:53], v[94:97]
	v_mfma_f32_16x16x32_bf16 v[90:93], v[82:85], v[50:53], v[90:93]
	v_mfma_f32_16x16x32_bf16 v[78:81], v[54:57], v[62:65], v[78:81]
	v_mfma_f32_16x16x32_bf16 v[74:77], v[82:85], v[62:65], v[74:77]
	v_mfma_f32_16x16x32_bf16 v[30:33], v[54:57], v[170:173], v[30:33]
	v_mfma_f32_16x16x32_bf16 v[26:29], v[82:85], v[170:173], v[26:29]
	v_mfma_f32_16x16x32_bf16 v[14:17], v[54:57], v[178:181], v[14:17]
	v_mfma_f32_16x16x32_bf16 v[10:13], v[82:85], v[178:181], v[10:13]
	v_mfma_f32_16x16x32_bf16 v[94:97], v[70:73], v[58:61], v[94:97]
	v_mfma_f32_16x16x32_bf16 v[90:93], v[86:89], v[58:61], v[90:93]
	v_mfma_f32_16x16x32_bf16 v[78:81], v[70:73], v[66:69], v[78:81]
	v_mfma_f32_16x16x32_bf16 v[74:77], v[86:89], v[66:69], v[74:77]
	v_mfma_f32_16x16x32_bf16 v[30:33], v[70:73], v[174:177], v[30:33]
	v_mfma_f32_16x16x32_bf16 v[26:29], v[86:89], v[174:177], v[26:29]
	v_mfma_f32_16x16x32_bf16 v[14:17], v[70:73], v[182:185], v[14:17]
	v_mfma_f32_16x16x32_bf16 v[10:13], v[86:89], v[182:185], v[10:13]
	s_barrier
	s_add_u32 s4, s46, 0x40080
	s_addc_u32 s5, s47, 0
	s_add_i32 s46, s48, s52
	v_lshl_add_u64 v[54:55], s[4:5], 0, v[164:165]
	s_mov_b32 m0, s46
	s_nop 0
	global_load_lds_dwordx4 v[54:55], off
	v_lshl_add_u64 v[54:55], s[4:5], 0, v[162:163]
	s_add_i32 m0, s46, 0x2000
	s_nop 0
	global_load_lds_dwordx4 v[54:55], off
	s_waitcnt vmcnt(6)
	s_barrier
	v_mfma_f32_16x16x32_bf16 v[34:37], v[222:225], v[50:53], v[34:37]
	v_mfma_f32_16x16x32_bf16 v[86:89], v[226:229], v[58:61], v[34:37]
	v_mfma_f32_16x16x32_bf16 v[34:37], v[230:233], v[50:53], v[38:41]
	v_mfma_f32_16x16x32_bf16 v[82:85], v[234:237], v[58:61], v[34:37]
	v_mfma_f32_16x16x32_bf16 v[34:37], v[222:225], v[62:65], v[42:45]
	v_mfma_f32_16x16x32_bf16 v[70:73], v[226:229], v[66:69], v[34:37]
	v_mfma_f32_16x16x32_bf16 v[34:37], v[230:233], v[62:65], v[46:49]
	v_mfma_f32_16x16x32_bf16 v[22:25], v[222:225], v[170:173], v[22:25]
	v_mfma_f32_16x16x32_bf16 v[18:21], v[230:233], v[170:173], v[18:21]
	v_mfma_f32_16x16x32_bf16 v[6:9], v[222:225], v[178:181], v[6:9]
	v_mfma_f32_16x16x32_bf16 v[2:5], v[230:233], v[178:181], v[2:5]
	v_mfma_f32_16x16x32_bf16 v[54:57], v[234:237], v[66:69], v[34:37]
	v_mfma_f32_16x16x32_bf16 v[22:25], v[226:229], v[174:177], v[22:25]
	v_mfma_f32_16x16x32_bf16 v[18:21], v[234:237], v[174:177], v[18:21]
	v_mfma_f32_16x16x32_bf16 v[6:9], v[226:229], v[182:185], v[6:9]
	v_mfma_f32_16x16x32_bf16 v[2:5], v[234:237], v[182:185], v[2:5]
	s_add_i32 s66, s66, 2
	s_add_u32 s64, s64, 0x100
	s_addc_u32 s65, s65, 0
	s_cmp_gt_u32 s66, 13
	s_mov_b64 s[4:5], s[36:37]
	s_barrier
.LBB0_212:
	s_add_u32 s36, s4, 0x100
	s_addc_u32 s37, s5, 0
	s_add_i32 s67, 0, 0x10000
	v_add_u32_e32 v1, s67, v191
	ds_read_b128 v[34:37], v1
	ds_read_b128 v[38:41], v1 offset:1024
	ds_read_b128 v[42:45], v1 offset:2048
	ds_read_b128 v[46:49], v1 offset:3072
	s_cmp_eq_u32 s66, 12
	s_cselect_b32 s49, s38, s37
	s_cselect_b32 s48, s43, s36
	s_cselect_b32 s47, s62, s65
	s_cselect_b32 s46, s63, s64
	v_lshl_add_u64 v[186:187], s[4:5], 0, v[168:169]
	s_add_i32 m0, s53, 0xc000
	ds_read_b128 v[50:53], v206
	ds_read_b128 v[58:61], v206 offset:1024
	ds_read_b128 v[62:65], v206 offset:2048
	ds_read_b128 v[66:69], v206 offset:3072
	ds_read_b128 v[170:173], v206 offset:4096
	ds_read_b128 v[174:177], v206 offset:5120
	ds_read_b128 v[178:181], v206 offset:6144
	ds_read_b128 v[182:185], v206 offset:7168
	global_load_lds_dwordx4 v[186:187], off
	v_lshl_add_u64 v[186:187], s[4:5], 0, v[166:167]
	s_add_i32 m0, s53, 0xe000
	s_nop 0
	global_load_lds_dwordx4 v[186:187], off
	s_waitcnt lgkmcnt(8)
	s_barrier
	s_waitcnt lgkmcnt(0)
	s_waitcnt lgkmcnt(0)
	v_mfma_f32_16x16x32_bf16 v[158:161], v[34:37], v[50:53], v[158:161]
	v_mfma_f32_16x16x32_bf16 v[154:157], v[42:45], v[50:53], v[154:157]
	v_mfma_f32_16x16x32_bf16 v[142:145], v[34:37], v[62:65], v[142:145]
	v_mfma_f32_16x16x32_bf16 v[138:141], v[42:45], v[62:65], v[138:141]
	v_mfma_f32_16x16x32_bf16 v[126:129], v[34:37], v[170:173], v[126:129]
	v_mfma_f32_16x16x32_bf16 v[122:125], v[42:45], v[170:173], v[122:125]
	v_mfma_f32_16x16x32_bf16 v[110:113], v[34:37], v[178:181], v[110:113]
	v_mfma_f32_16x16x32_bf16 v[106:109], v[42:45], v[178:181], v[106:109]
	v_mfma_f32_16x16x32_bf16 v[158:161], v[38:41], v[58:61], v[158:161]
	v_mfma_f32_16x16x32_bf16 v[154:157], v[46:49], v[58:61], v[154:157]
	v_mfma_f32_16x16x32_bf16 v[142:145], v[38:41], v[66:69], v[142:145]
	v_mfma_f32_16x16x32_bf16 v[138:141], v[46:49], v[66:69], v[138:141]
	v_mfma_f32_16x16x32_bf16 v[126:129], v[38:41], v[174:177], v[126:129]
	v_mfma_f32_16x16x32_bf16 v[122:125], v[46:49], v[174:177], v[122:125]
	v_mfma_f32_16x16x32_bf16 v[110:113], v[38:41], v[182:185], v[110:113]
	v_mfma_f32_16x16x32_bf16 v[106:109], v[46:49], v[182:185], v[106:109]
	s_barrier
	s_add_i32 s68, 0, 0x14000
	s_add_i32 s4, s67, s52
	v_add_u32_e32 v1, s68, v191
	v_lshl_add_u64 v[214:215], s[46:47], 0, v[164:165]
	s_mov_b32 m0, s4
	ds_read_b128 v[186:189], v1
	ds_read_b128 v[208:211], v1 offset:1024
	ds_read_b128 v[222:225], v1 offset:2048
	ds_read_b128 v[226:229], v1 offset:3072
	global_load_lds_dwordx4 v[214:215], off
	v_lshl_add_u64 v[238:239], s[46:47], 0, v[162:163]
	s_add_i32 m0, s4, 0x2000
	s_nop 0
	global_load_lds_dwordx4 v[238:239], off
	s_barrier
	s_waitcnt lgkmcnt(0)
	s_waitcnt lgkmcnt(0)
	v_mfma_f32_16x16x32_bf16 v[150:153], v[186:189], v[50:53], v[150:153]
	v_mfma_f32_16x16x32_bf16 v[50:53], v[222:225], v[50:53], v[146:149]
	v_mfma_f32_16x16x32_bf16 v[150:153], v[208:211], v[58:61], v[150:153]
	v_mfma_f32_16x16x32_bf16 v[50:53], v[226:229], v[58:61], v[50:53]
	v_mfma_f32_16x16x32_bf16 v[58:61], v[186:189], v[62:65], v[134:137]
	v_mfma_f32_16x16x32_bf16 v[62:65], v[222:225], v[62:65], v[130:133]
	v_mfma_f32_16x16x32_bf16 v[114:117], v[222:225], v[170:173], v[114:117]
	v_mfma_f32_16x16x32_bf16 v[102:105], v[186:189], v[178:181], v[102:105]
	v_mfma_f32_16x16x32_bf16 v[98:101], v[222:225], v[178:181], v[98:101]
	v_mfma_f32_16x16x32_bf16 v[58:61], v[208:211], v[66:69], v[58:61]
	v_mfma_f32_16x16x32_bf16 v[62:65], v[226:229], v[66:69], v[62:65]
	v_mfma_f32_16x16x32_bf16 v[66:69], v[186:189], v[170:173], v[118:121]
	v_mfma_f32_16x16x32_bf16 v[114:117], v[226:229], v[174:177], v[114:117]
	v_mfma_f32_16x16x32_bf16 v[102:105], v[208:211], v[182:185], v[102:105]
	v_mfma_f32_16x16x32_bf16 v[98:101], v[226:229], v[182:185], v[98:101]
	v_mfma_f32_16x16x32_bf16 v[66:69], v[208:211], v[174:177], v[66:69]
	s_mov_b32 m0, s53
	v_lshl_add_u64 v[240:241], s[48:49], 0, v[164:165]
	s_barrier
	ds_read_b128 v[118:121], v206 offset:16384
	ds_read_b128 v[130:133], v206 offset:17408
	ds_read_b128 v[134:137], v206 offset:18432
	ds_read_b128 v[146:149], v206 offset:19456
	ds_read_b128 v[170:173], v206 offset:20480
	ds_read_b128 v[174:177], v206 offset:21504
	ds_read_b128 v[178:181], v206 offset:22528
	ds_read_b128 v[182:185], v206 offset:23552
	global_load_lds_dwordx4 v[240:241], off
	v_lshl_add_u64 v[242:243], s[48:49], 0, v[162:163]
	s_mov_b32 m0, s54
	s_nop 0
	global_load_lds_dwordx4 v[242:243], off
	s_barrier
	s_waitcnt lgkmcnt(0)
	s_waitcnt lgkmcnt(0)
	v_mfma_f32_16x16x32_bf16 v[94:97], v[34:37], v[118:121], v[94:97]
	v_mfma_f32_16x16x32_bf16 v[90:93], v[42:45], v[118:121], v[90:93]
	v_mfma_f32_16x16x32_bf16 v[78:81], v[34:37], v[134:137], v[78:81]
	v_mfma_f32_16x16x32_bf16 v[74:77], v[42:45], v[134:137], v[74:77]
	v_mfma_f32_16x16x32_bf16 v[30:33], v[34:37], v[170:173], v[30:33]
	v_mfma_f32_16x16x32_bf16 v[26:29], v[42:45], v[170:173], v[26:29]
	v_mfma_f32_16x16x32_bf16 v[14:17], v[34:37], v[178:181], v[14:17]
	v_mfma_f32_16x16x32_bf16 v[10:13], v[42:45], v[178:181], v[10:13]
	v_mfma_f32_16x16x32_bf16 v[94:97], v[38:41], v[130:133], v[94:97]
	v_mfma_f32_16x16x32_bf16 v[90:93], v[46:49], v[130:133], v[90:93]
	v_mfma_f32_16x16x32_bf16 v[78:81], v[38:41], v[146:149], v[78:81]
	v_mfma_f32_16x16x32_bf16 v[74:77], v[46:49], v[146:149], v[74:77]
	v_mfma_f32_16x16x32_bf16 v[30:33], v[38:41], v[174:177], v[30:33]
	v_mfma_f32_16x16x32_bf16 v[26:29], v[46:49], v[174:177], v[26:29]
	v_mfma_f32_16x16x32_bf16 v[14:17], v[38:41], v[182:185], v[14:17]
	v_mfma_f32_16x16x32_bf16 v[10:13], v[46:49], v[182:185], v[10:13]
	s_barrier
	s_add_u32 s4, s46, 0x40000
	s_addc_u32 s5, s47, 0
	s_add_i32 s67, s68, s52
	v_lshl_add_u64 v[34:35], s[4:5], 0, v[164:165]
	s_mov_b32 m0, s67
	s_nop 0
	global_load_lds_dwordx4 v[34:35], off
	v_lshl_add_u64 v[34:35], s[4:5], 0, v[162:163]
	s_add_i32 m0, s67, 0x2000
	s_nop 0
	global_load_lds_dwordx4 v[34:35], off
	s_waitcnt vmcnt(6)
	s_barrier
	v_mfma_f32_16x16x32_bf16 v[22:25], v[186:189], v[170:173], v[22:25]
	v_mfma_f32_16x16x32_bf16 v[18:21], v[222:225], v[170:173], v[18:21]
	v_mfma_f32_16x16x32_bf16 v[6:9], v[186:189], v[178:181], v[6:9]
	v_mfma_f32_16x16x32_bf16 v[2:5], v[222:225], v[178:181], v[2:5]
	v_mfma_f32_16x16x32_bf16 v[34:37], v[186:189], v[118:121], v[86:89]
	v_mfma_f32_16x16x32_bf16 v[38:41], v[222:225], v[118:121], v[82:85]
	v_mfma_f32_16x16x32_bf16 v[42:45], v[186:189], v[134:137], v[70:73]
	v_mfma_f32_16x16x32_bf16 v[46:49], v[222:225], v[134:137], v[54:57]
	v_mfma_f32_16x16x32_bf16 v[22:25], v[208:211], v[174:177], v[22:25]
	v_mfma_f32_16x16x32_bf16 v[18:21], v[226:229], v[174:177], v[18:21]
	v_mfma_f32_16x16x32_bf16 v[6:9], v[208:211], v[182:185], v[6:9]
	v_mfma_f32_16x16x32_bf16 v[2:5], v[226:229], v[182:185], v[2:5]
	v_mfma_f32_16x16x32_bf16 v[34:37], v[208:211], v[130:133], v[34:37]
	v_mfma_f32_16x16x32_bf16 v[38:41], v[226:229], v[130:133], v[38:41]
	v_mfma_f32_16x16x32_bf16 v[42:45], v[208:211], v[146:149], v[42:45]
	v_mfma_f32_16x16x32_bf16 v[46:49], v[226:229], v[146:149], v[46:49]
	s_add_i32 s67, 0, 0x18000
	v_add_u32_e32 v1, s67, v191
	s_barrier
	ds_read_b128 v[54:57], v1
	ds_read_b128 v[70:73], v1 offset:1024
	ds_read_b128 v[82:85], v1 offset:2048
	ds_read_b128 v[86:89], v1 offset:3072
	s_add_u32 s4, s48, 0x40000
	s_addc_u32 s5, s49, 0
	s_mov_b32 m0, s55
	v_lshl_add_u64 v[134:135], s[4:5], 0, v[164:165]
	ds_read_b128 v[118:121], v206 offset:32768
	ds_read_b128 v[130:133], v206 offset:33792
	ds_read_b128 v[170:173], v206 offset:34816
	ds_read_b128 v[174:177], v206 offset:35840
	ds_read_b128 v[178:181], v206 offset:36864
	ds_read_b128 v[182:185], v206 offset:37888
	ds_read_b128 v[186:189], v206 offset:38912
	ds_read_b128 v[208:211], v206 offset:39936
	global_load_lds_dwordx4 v[134:135], off
	v_lshl_add_u64 v[134:135], s[4:5], 0, v[162:163]
	s_mov_b32 m0, s56
	s_nop 0
	global_load_lds_dwordx4 v[134:135], off
	s_waitcnt lgkmcnt(8)
	s_barrier
	s_waitcnt lgkmcnt(0)
	s_waitcnt lgkmcnt(0)
	v_mfma_f32_16x16x32_bf16 v[134:137], v[54:57], v[118:121], v[158:161]
	v_mfma_f32_16x16x32_bf16 v[158:161], v[70:73], v[130:133], v[134:137]
	v_mfma_f32_16x16x32_bf16 v[134:137], v[82:85], v[118:121], v[154:157]
	v_mfma_f32_16x16x32_bf16 v[154:157], v[86:89], v[130:133], v[134:137]
	v_mfma_f32_16x16x32_bf16 v[134:137], v[54:57], v[170:173], v[142:145]
	v_mfma_f32_16x16x32_bf16 v[142:145], v[70:73], v[174:177], v[134:137]
	v_mfma_f32_16x16x32_bf16 v[134:137], v[82:85], v[170:173], v[138:141]
	v_mfma_f32_16x16x32_bf16 v[126:129], v[54:57], v[178:181], v[126:129]
	v_mfma_f32_16x16x32_bf16 v[122:125], v[82:85], v[178:181], v[122:125]
	v_mfma_f32_16x16x32_bf16 v[110:113], v[54:57], v[186:189], v[110:113]
	v_mfma_f32_16x16x32_bf16 v[106:109], v[82:85], v[186:189], v[106:109]
	v_mfma_f32_16x16x32_bf16 v[138:141], v[86:89], v[174:177], v[134:137]
	v_mfma_f32_16x16x32_bf16 v[126:129], v[70:73], v[182:185], v[126:129]
	v_mfma_f32_16x16x32_bf16 v[122:125], v[86:89], v[182:185], v[122:125]
	v_mfma_f32_16x16x32_bf16 v[110:113], v[70:73], v[208:211], v[110:113]
	v_mfma_f32_16x16x32_bf16 v[106:109], v[86:89], v[208:211], v[106:109]
	s_barrier
	s_add_i32 s48, 0, 0x1c000
	s_add_i32 s4, s67, s52
	v_add_u32_e32 v1, s48, v191
	v_lshl_add_u64 v[134:135], v[214:215], 0, s[22:23]
	s_mov_b32 m0, s4
	ds_read_b128 v[222:225], v1
	ds_read_b128 v[226:229], v1 offset:1024
	ds_read_b128 v[230:233], v1 offset:2048
	ds_read_b128 v[234:237], v1 offset:3072
	global_load_lds_dwordx4 v[134:135], off
	v_lshl_add_u64 v[134:135], v[238:239], 0, s[22:23]
	s_add_i32 m0, s4, 0x2000
	s_nop 0
	global_load_lds_dwordx4 v[134:135], off
	s_barrier
	s_waitcnt lgkmcnt(0)
	s_waitcnt lgkmcnt(0)
	v_mfma_f32_16x16x32_bf16 v[50:53], v[230:233], v[118:121], v[50:53]
	v_mfma_f32_16x16x32_bf16 v[134:137], v[222:225], v[118:121], v[150:153]
	v_mfma_f32_16x16x32_bf16 v[146:149], v[234:237], v[130:133], v[50:53]
	v_mfma_f32_16x16x32_bf16 v[50:53], v[222:225], v[170:173], v[58:61]
	v_mfma_f32_16x16x32_bf16 v[150:153], v[226:229], v[130:133], v[134:137]
	v_mfma_f32_16x16x32_bf16 v[134:137], v[226:229], v[174:177], v[50:53]
	v_mfma_f32_16x16x32_bf16 v[50:53], v[230:233], v[170:173], v[62:65]
	v_mfma_f32_16x16x32_bf16 v[130:133], v[234:237], v[174:177], v[50:53]
	v_mfma_f32_16x16x32_bf16 v[50:53], v[222:225], v[178:181], v[66:69]
	v_mfma_f32_16x16x32_bf16 v[118:121], v[226:229], v[182:185], v[50:53]
	v_mfma_f32_16x16x32_bf16 v[50:53], v[230:233], v[178:181], v[114:117]
	v_mfma_f32_16x16x32_bf16 v[114:117], v[234:237], v[182:185], v[50:53]
	v_mfma_f32_16x16x32_bf16 v[50:53], v[222:225], v[186:189], v[102:105]
	v_mfma_f32_16x16x32_bf16 v[102:105], v[226:229], v[208:211], v[50:53]
	v_mfma_f32_16x16x32_bf16 v[50:53], v[230:233], v[186:189], v[98:101]
	v_mfma_f32_16x16x32_bf16 v[98:101], v[234:237], v[208:211], v[50:53]
	s_mov_b32 m0, s58
	v_lshl_add_u64 v[186:187], v[240:241], 0, s[22:23]
	s_barrier
	s_nop 2
	ds_read_b128 v[50:53], v206 offset:49152
	ds_read_b128 v[58:61], v206 offset:50176
	ds_read_b128 v[62:65], v206 offset:51200
	ds_read_b128 v[66:69], v206 offset:52224
	ds_read_b128 v[170:173], v206 offset:53248
	ds_read_b128 v[174:177], v206 offset:54272
	ds_read_b128 v[178:181], v206 offset:55296
	ds_read_b128 v[182:185], v206 offset:56320
	global_load_lds_dwordx4 v[186:187], off
	v_lshl_add_u64 v[186:187], v[242:243], 0, s[22:23]
	s_mov_b32 m0, s59
	s_nop 0
	global_load_lds_dwordx4 v[186:187], off
	s_barrier
	s_waitcnt lgkmcnt(0)
	s_waitcnt lgkmcnt(0)
	v_mfma_f32_16x16x32_bf16 v[94:97], v[54:57], v[50:53], v[94:97]
	v_mfma_f32_16x16x32_bf16 v[90:93], v[82:85], v[50:53], v[90:93]
	v_mfma_f32_16x16x32_bf16 v[78:81], v[54:57], v[62:65], v[78:81]
	v_mfma_f32_16x16x32_bf16 v[74:77], v[82:85], v[62:65], v[74:77]
	v_mfma_f32_16x16x32_bf16 v[30:33], v[54:57], v[170:173], v[30:33]
	v_mfma_f32_16x16x32_bf16 v[26:29], v[82:85], v[170:173], v[26:29]
	v_mfma_f32_16x16x32_bf16 v[14:17], v[54:57], v[178:181], v[14:17]
	v_mfma_f32_16x16x32_bf16 v[10:13], v[82:85], v[178:181], v[10:13]
	v_mfma_f32_16x16x32_bf16 v[94:97], v[70:73], v[58:61], v[94:97]
	v_mfma_f32_16x16x32_bf16 v[90:93], v[86:89], v[58:61], v[90:93]
	v_mfma_f32_16x16x32_bf16 v[78:81], v[70:73], v[66:69], v[78:81]
	v_mfma_f32_16x16x32_bf16 v[74:77], v[86:89], v[66:69], v[74:77]
	v_mfma_f32_16x16x32_bf16 v[30:33], v[70:73], v[174:177], v[30:33]
	v_mfma_f32_16x16x32_bf16 v[26:29], v[86:89], v[174:177], v[26:29]
	v_mfma_f32_16x16x32_bf16 v[14:17], v[70:73], v[182:185], v[14:17]
	v_mfma_f32_16x16x32_bf16 v[10:13], v[86:89], v[182:185], v[10:13]
	s_barrier
	s_add_u32 s4, s46, 0x40080
	s_addc_u32 s5, s47, 0
	s_add_i32 s46, s48, s52
	v_lshl_add_u64 v[54:55], s[4:5], 0, v[164:165]
	s_mov_b32 m0, s46
	s_nop 0
	global_load_lds_dwordx4 v[54:55], off
	v_lshl_add_u64 v[54:55], s[4:5], 0, v[162:163]
	s_add_i32 m0, s46, 0x2000
	s_nop 0
	global_load_lds_dwordx4 v[54:55], off
	s_waitcnt vmcnt(6)
	s_barrier
	v_mfma_f32_16x16x32_bf16 v[34:37], v[222:225], v[50:53], v[34:37]
	v_mfma_f32_16x16x32_bf16 v[86:89], v[226:229], v[58:61], v[34:37]
	v_mfma_f32_16x16x32_bf16 v[34:37], v[230:233], v[50:53], v[38:41]
	v_mfma_f32_16x16x32_bf16 v[82:85], v[234:237], v[58:61], v[34:37]
	v_mfma_f32_16x16x32_bf16 v[34:37], v[222:225], v[62:65], v[42:45]
	v_mfma_f32_16x16x32_bf16 v[70:73], v[226:229], v[66:69], v[34:37]
	v_mfma_f32_16x16x32_bf16 v[34:37], v[230:233], v[62:65], v[46:49]
	v_mfma_f32_16x16x32_bf16 v[22:25], v[222:225], v[170:173], v[22:25]
	v_mfma_f32_16x16x32_bf16 v[18:21], v[230:233], v[170:173], v[18:21]
	v_mfma_f32_16x16x32_bf16 v[6:9], v[222:225], v[178:181], v[6:9]
	v_mfma_f32_16x16x32_bf16 v[2:5], v[230:233], v[178:181], v[2:5]
	v_mfma_f32_16x16x32_bf16 v[54:57], v[234:237], v[66:69], v[34:37]
	v_mfma_f32_16x16x32_bf16 v[22:25], v[226:229], v[174:177], v[22:25]
	v_mfma_f32_16x16x32_bf16 v[18:21], v[234:237], v[174:177], v[18:21]
	v_mfma_f32_16x16x32_bf16 v[6:9], v[226:229], v[182:185], v[6:9]
	v_mfma_f32_16x16x32_bf16 v[2:5], v[234:237], v[182:185], v[2:5]
	s_add_i32 s66, s66, 2
	s_add_u32 s64, s64, 0x100
	s_addc_u32 s65, s65, 0
	s_cmp_gt_u32 s66, 13
	s_mov_b64 s[4:5], s[36:37]
	s_barrier
	s_cbranch_scc0 .LBB0_212
	s_setprio 0
	v_lshl_or_b32 v208, s3, 8, v192
	v_mov_b32_e32 v1, v190
	v_ashrrev_i32_e32 v209, 31, v208
	v_lshlrev_b64 v[34:35], 2, v[208:209]
	v_lshl_add_u64 v[36:37], s[8:9], 0, v[34:35]
	v_lshlrev_b32_e32 v250, 2, v192
	v_add_u32_e32 v250, 0x20840, v250
	ds_read_b128 v[62:65], v250
	ds_read_b128 v[50:53], v250 offset:16
	v_lshl_add_u64 v[34:35], s[10:11], 0, v[34:35]
	ds_read_b128 v[66:69], v250 offset:1024
	ds_read_b128 v[42:45], v250 offset:1040
	ds_read_b128 v[58:61], v250 offset:512
	ds_read_b128 v[38:41], v250 offset:528
	ds_read_b128 v[46:49], v250 offset:1536
	s_nop 0
	ds_read_b128 v[34:37], v250 offset:1552
	s_lshl_b32 s37, s27, 8
	v_lshl_add_u32 v170, v1, 3, 0
	v_add_u32_e32 v170, 0x20040, v170
	ds_read_b64 v[188:189], v170
	s_mov_b32 s4, 0xbf3a00e3
	s_cmp_gt_i32 s3, 3
	v_mov_b64_e32 v[176:177], s[4:5]
	s_cselect_b64 s[4:5], -1, 0
	s_and_b64 s[46:47], s[40:41], s[4:5]
	s_mov_b32 s4, 0x3f07dc22
	s_mov_b32 s38, 0x3f35f0e3
	s_mov_b32 s48, 0xbe11a98e
	s_mov_b32 s62, 0x3e027906
	s_lshl_b32 s3, s3, 2
	s_and_b32 s36, s3, 12
	s_mov_b32 s3, 0x1020000
	v_add_u32_e32 v170, s37, v1
	v_lshlrev_b32_e32 v1, 10, v170
	s_waitcnt lgkmcnt(0)
	v_xor_b32_e32 v65, 0x80000000, v65
	v_xor_b32_e32 v64, 0x80000000, v64
	v_pk_fma_f32 v[158:159], v[62:63], v[188:189], v[158:159] op_sel_hi:[1,0,1] neg_lo:[1,0,0] neg_hi:[1,0,0]
	v_xor_b32_e32 v53, 0x80000000, v53
	v_xor_b32_e32 v52, 0x80000000, v52
	v_pk_fma_f32 v[154:155], v[50:51], v[188:189], v[154:155] op_sel_hi:[1,0,1] neg_lo:[1,0,0] neg_hi:[1,0,0]
	v_pk_fma_f32 v[160:161], v[64:65], v[188:189], v[160:161] op_sel_hi:[1,0,1]
	v_pk_fma_f32 v[158:159], v[188:189], v[158:159], v[66:67] op_sel:[1,0,0]
	v_pk_fma_f32 v[172:173], v[52:53], v[188:189], v[156:157] op_sel_hi:[1,0,1]
	v_pk_fma_f32 v[156:157], v[188:189], v[154:155], v[42:43] op_sel:[1,0,0]
	v_pk_fma_f32 v[154:155], v[188:189], v[160:161], v[68:69] op_sel:[1,0,0]
	v_fma_f32 v175, |v159|, s1, 1.0
	v_fma_f32 v171, |v158|, s1, 1.0
	v_pk_fma_f32 v[160:161], v[188:189], v[172:173], v[44:45] op_sel:[1,0,0]
	v_fma_f32 v172, |v156|, s1, 1.0
	v_rcp_f32_e32 v175, v175
	v_fma_f32 v187, |v155|, s1, 1.0
	v_mul_f32_e32 v174, v158, v158
	v_rcp_f32_e32 v182, v171
	v_rcp_f32_e32 v183, v172
	v_rcp_f32_e32 v215, v187
	v_mul_f32_e32 v173, v156, v156
	v_fma_f32 v179, |v157|, s1, 1.0
	v_mul_f32_e32 v180, v157, v157
	v_mul_f32_e32 v171, 0xbf38aa3b, v174
	v_mul_f32_e32 v186, v154, v154
	v_fma_f32 v181, |v154|, s1, 1.0
	v_mul_f32_e32 v172, 0xbf38aa3b, v173
	v_rcp_f32_e32 v185, v179
	v_mul_f32_e32 v173, 0xbf38aa3b, v180
	v_fma_f32 v179, |v160|, s1, 1.0
	v_mul_f32_e32 v209, v160, v160
	v_exp_f32_e32 v180, v171
	v_mul_f32_e32 v171, 0xbf38aa3b, v186
	v_fma_f32 v211, |v161|, s1, 1.0
	v_rcp_f32_e32 v184, v181
	v_exp_f32_e32 v181, v172
	v_rcp_f32_e32 v210, v179
	v_mul_f32_e32 v179, 0xbf38aa3b, v209
	v_exp_f32_e32 v172, v171
	v_fmamk_f32 v171, v175, 0x3f07dc22, v218
	v_rcp_f32_e32 v211, v211
	v_exp_f32_e32 v214, v179
	v_pk_fma_f32 v[186:187], v[182:183], s[4:5], v[176:177] op_sel_hi:[1,0,0]
	v_fmaak_f32 v171, v175, v171, 0x3f35f0e3
	v_fmamk_f32 v179, v215, 0x3f07dc22, v218
	v_pk_fma_f32 v[186:187], v[182:183], v[186:187], s[38:39] op_sel_hi:[1,1,0]
	v_fmaak_f32 v171, v175, v171, 0xbe11a98e
	v_fmaak_f32 v179, v215, v179, 0x3f35f0e3
	v_pk_fma_f32 v[186:187], v[182:183], v[186:187], s[48:49] op_sel_hi:[1,1,0]
	v_fmaak_f32 v171, v175, v171, 0x3e027906
	v_fmaak_f32 v179, v215, v179, 0xbe11a98e
	v_mul_f32_e32 v212, v161, v161
	v_pk_fma_f32 v[224:225], v[182:183], v[186:187], s[62:63] op_sel_hi:[1,1,0]
	v_mul_f32_e32 v186, v175, v171
	v_fmaak_f32 v171, v215, v179, 0x3e027906
	v_pk_fma_f32 v[222:223], v[184:185], s[4:5], v[176:177] op_sel_hi:[1,0,0]
	v_pk_mul_f32 v[224:225], v[182:183], v[224:225]
	v_mul_f32_e32 v182, v215, v171
	v_mul_f32_e32 v171, 0xbf38aa3b, v212
	v_pk_fma_f32 v[176:177], v[210:211], s[4:5], v[176:177] op_sel_hi:[1,0,0]
	v_exp_f32_e32 v215, v171
	v_pk_fma_f32 v[176:177], v[210:211], v[176:177], s[38:39] op_sel_hi:[1,1,0]
	v_cmp_gt_f32_e32 vcc, 0, v161
	v_pk_fma_f32 v[176:177], v[210:211], v[176:177], s[48:49] op_sel_hi:[1,1,0]
	v_pk_fma_f32 v[150:151], v[58:59], v[188:189], v[150:151] op_sel_hi:[1,0,1] neg_lo:[1,0,0] neg_hi:[1,0,0]
	v_pk_fma_f32 v[176:177], v[210:211], v[176:177], s[62:63] op_sel_hi:[1,1,0]
	v_pk_fma_f32 v[150:151], v[188:189], v[150:151], v[46:47] op_sel:[1,0,0]
	v_pk_mul_f32 v[176:177], v[210:211], v[176:177]
	v_fma_f32 v175, |v150|, s1, 1.0
	v_pk_mul_f32 v[176:177], v[214:215], v[176:177]
	v_rcp_f32_e32 v175, v175
	v_pk_mul_f32 v[210:211], v[160:161], v[176:177]
	v_pk_fma_f32 v[176:177], v[160:161], v[176:177], v[160:161] neg_lo:[1,0,0] neg_hi:[1,0,0]
	v_mul_f32_e32 v178, v159, v159
	v_cndmask_b32_e32 v177, v177, v211, vcc
	v_cmp_gt_f32_e32 vcc, 0, v160
	v_xor_b32_e32 v61, 0x80000000, v61
	v_xor_b32_e32 v60, 0x80000000, v60
	v_cndmask_b32_e32 v176, v176, v210, vcc
	v_mul_f32_e32 v160, v176, v176
	v_pk_fma_f32 v[160:161], v[176:177], v[176:177], v[160:161] op_sel_hi:[1,1,0]
	v_mul_f32_e32 v174, 0xbf38aa3b, v178
	v_lshrrev_b32_e32 v160, 10, v208
	v_mul_f32_e32 v207, v155, v155
	v_mul_lo_u32 v160, v160, s3
	s_movk_i32 s4, 0x3ff
	v_pk_fma_f32 v[152:153], v[60:61], v[188:189], v[152:153] op_sel_hi:[1,0,1]
	v_exp_f32_e32 v178, v174
	v_mul_f32_e32 v174, 0xbf38aa3b, v207
	v_and_or_b32 v207, v208, s4, v160
	v_add_u32_e32 v171, 0x80, v208
	v_pk_fma_f32 v[208:209], v[188:189], v[152:153], v[48:49] op_sel:[1,0,0]
	v_fmamk_f32 v152, v175, 0x3f07dc22, v218
	v_fmaak_f32 v152, v175, v152, 0x3f35f0e3
	v_mul_f32_e32 v153, v150, v150
	v_mul_f32_e32 v153, 0xbf38aa3b, v153
	v_fmaak_f32 v152, v175, v152, 0xbe11a98e
	v_exp_f32_e32 v153, v153
	v_fmaak_f32 v152, v175, v152, 0x3e027906
	v_mul_f32_e32 v152, v175, v152
	v_fma_f32 v175, |v151|, s1, 1.0
	v_rcp_f32_e32 v175, v175
	v_mul_f32_e32 v152, v153, v152
	v_mul_f32_e32 v153, v150, v152
	v_fma_f32 v152, -v150, v152, v150
	v_cmp_gt_f32_e32 vcc, 0, v150
	v_pk_fma_f32 v[146:147], v[38:39], v[188:189], v[146:147] op_sel_hi:[1,0,1] neg_lo:[1,0,0] neg_hi:[1,0,0]
	v_xor_b32_e32 v41, 0x80000000, v41
	v_cndmask_b32_e32 v150, v152, v153, vcc
	v_fmamk_f32 v152, v175, 0x3f07dc22, v218
	v_fmaak_f32 v152, v175, v152, 0x3f35f0e3
	v_mul_f32_e32 v153, v151, v151
	v_fmaak_f32 v152, v175, v152, 0xbe11a98e
	v_mul_f32_e32 v153, 0xbf38aa3b, v153
	v_fmaak_f32 v152, v175, v152, 0x3e027906
	v_exp_f32_e32 v153, v153
	v_mul_f32_e32 v152, v175, v152
	v_fma_f32 v175, |v208|, s1, 1.0
	v_rcp_f32_e32 v175, v175
	v_mul_f32_e32 v152, v153, v152
	v_mul_f32_e32 v153, v151, v152
	v_fma_f32 v152, -v151, v152, v151
	v_cmp_gt_f32_e32 vcc, 0, v151
	v_fmamk_f32 v151, v175, 0x3f07dc22, v218
	v_fmaak_f32 v151, v175, v151, 0x3f35f0e3
	v_cndmask_b32_e32 v152, v152, v153, vcc
	v_mul_f32_e32 v153, v208, v208
	v_mul_f32_e32 v153, 0xbf38aa3b, v153
	v_fmaak_f32 v151, v175, v151, 0xbe11a98e
	v_exp_f32_e32 v153, v153
	v_fmaak_f32 v151, v175, v151, 0x3e027906
	v_mul_f32_e32 v151, v175, v151
	v_fma_f32 v175, |v209|, s1, 1.0
	v_rcp_f32_e32 v175, v175
	v_mul_f32_e32 v151, v153, v151
	v_mul_f32_e32 v153, v208, v151
	v_fma_f32 v151, -v208, v151, v208
	v_cmp_gt_f32_e32 vcc, 0, v208
	v_pk_fma_f32 v[146:147], v[188:189], v[146:147], v[34:35] op_sel:[1,0,0]
	v_xor_b32_e32 v40, 0x80000000, v40
	v_cndmask_b32_e32 v208, v151, v153, vcc
	v_fmamk_f32 v151, v175, 0x3f07dc22, v218
	v_fmaak_f32 v151, v175, v151, 0x3f35f0e3
	v_fmaak_f32 v151, v175, v151, 0xbe11a98e
	v_fmaak_f32 v151, v175, v151, 0x3e027906
	v_mul_f32_e32 v151, v175, v151
	v_fma_f32 v175, |v146|, s1, 1.0
	v_rcp_f32_e32 v175, v175
	v_mul_f32_e32 v183, v146, v146
	v_mul_f32_e32 v153, v209, v209
	v_mul_f32_e32 v183, 0xbf38aa3b, v183
	v_fmamk_f32 v179, v175, 0x3f07dc22, v218
	v_mul_f32_e32 v153, 0xbf38aa3b, v153
	v_fmaak_f32 v179, v175, v179, 0x3f35f0e3
	v_exp_f32_e32 v183, v183
	v_exp_f32_e32 v153, v153
	v_fmaak_f32 v179, v175, v179, 0xbe11a98e
	v_fmaak_f32 v179, v175, v179, 0x3e027906
	v_mul_f32_e32 v175, v175, v179
	v_mul_f32_e32 v175, v183, v175
	v_fma_f32 v183, |v147|, s1, 1.0
	v_mul_f32_e32 v151, v153, v151
	v_rcp_f32_e32 v183, v183
	v_mul_f32_e32 v153, v209, v151
	v_fma_f32 v151, -v209, v151, v209
	v_cmp_gt_f32_e32 vcc, 0, v209
	v_mul_f32_e32 v179, v146, v175
	v_fma_f32 v175, -v146, v175, v146
	v_cndmask_b32_e32 v210, v151, v153, vcc
	v_cmp_gt_f32_e32 vcc, 0, v146
	v_pk_fma_f32 v[148:149], v[40:41], v[188:189], v[148:149] op_sel_hi:[1,0,1]
	v_fmamk_f32 v146, v183, 0x3f07dc22, v218
	v_cndmask_b32_e32 v214, v175, v179, vcc
	v_mul_f32_e32 v175, v147, v147
	v_mul_f32_e32 v175, 0xbf38aa3b, v175
	v_pk_fma_f32 v[148:149], v[188:189], v[148:149], v[36:37] op_sel:[1,0,0]
	v_fmaak_f32 v146, v183, v146, 0x3f35f0e3
	v_exp_f32_e32 v175, v175
	v_fmaak_f32 v146, v183, v146, 0xbe11a98e
	v_fma_f32 v179, |v148|, s1, 1.0
	v_fmaak_f32 v146, v183, v146, 0x3e027906
	v_rcp_f32_e32 v179, v179
	v_pk_fma_f32 v[222:223], v[184:185], v[222:223], s[38:39] op_sel_hi:[1,1,0]
	v_mul_f32_e32 v146, v183, v146
	v_pk_fma_f32 v[222:223], v[184:185], v[222:223], s[48:49] op_sel_hi:[1,1,0]
	v_mul_f32_e32 v146, v175, v146
	v_pk_fma_f32 v[222:223], v[184:185], v[222:223], s[62:63] op_sel_hi:[1,1,0]
	v_mul_f32_e32 v175, v147, v146
	v_fma_f32 v146, -v147, v146, v147
	v_cmp_gt_f32_e32 vcc, 0, v147
	v_mul_f32_e32 v147, v148, v148
	v_pk_mul_f32 v[184:185], v[184:185], v[222:223]
	v_cndmask_b32_e32 v222, v146, v175, vcc
	v_fmamk_f32 v146, v179, 0x3f07dc22, v218
	v_mul_f32_e32 v147, 0xbf38aa3b, v147
	v_fmaak_f32 v146, v179, v146, 0x3f35f0e3
	v_exp_f32_e32 v147, v147
	v_fmaak_f32 v146, v179, v146, 0xbe11a98e
	v_fmaak_f32 v146, v179, v146, 0x3e027906
	v_fma_f32 v175, |v149|, s1, 1.0
	v_mul_f32_e32 v146, v179, v146
	v_rcp_f32_e32 v175, v175
	v_mul_f32_e32 v146, v147, v146
	v_mul_f32_e32 v147, v148, v146
	v_fma_f32 v146, -v148, v146, v148
	v_cmp_gt_f32_e32 vcc, 0, v148
	v_exp_f32_e32 v173, v173
	v_exp_f32_e32 v174, v174
	v_cndmask_b32_e32 v226, v146, v147, vcc
	v_mul_f32_e32 v147, v149, v149
	v_fmamk_f32 v146, v175, 0x3f07dc22, v218
	v_mul_f32_e32 v147, 0xbf38aa3b, v147
	v_fmaak_f32 v146, v175, v146, 0x3f35f0e3
	v_exp_f32_e32 v147, v147
	v_fmaak_f32 v146, v175, v146, 0xbe11a98e
	v_fmaak_f32 v146, v175, v146, 0x3e027906
	v_mul_f32_e32 v146, v175, v146
	v_mul_f32_e32 v146, v147, v146
	v_mul_f32_e32 v147, v149, v146
	v_fma_f32 v146, -v149, v146, v149
	v_cmp_gt_f32_e32 vcc, 0, v149
	v_mov_b32_e32 v179, v181
	v_mov_b32_e32 v187, v225
	v_cndmask_b32_e32 v228, v146, v147, vcc
	v_lshrrev_b32_e32 v146, 10, v171
	v_mul_lo_u32 v146, v146, s3
	v_and_or_b32 v188, v171, s4, v146
	v_pk_mul_f32 v[146:147], v[180:181], v[224:225]
	v_pk_mul_f32 v[148:149], v[178:179], v[186:187]
	v_mov_b32_e32 v178, v158
	v_mov_b32_e32 v179, v156
	v_pk_mov_b32 v[186:187], v[158:159], v[156:157] op_sel:[1,0]
	v_pk_mul_f32 v[180:181], v[178:179], v[146:147]
	v_pk_mul_f32 v[224:225], v[186:187], v[148:149]
	v_pk_fma_f32 v[146:147], v[178:179], v[146:147], v[178:179] neg_lo:[1,0,0] neg_hi:[1,0,0]
	v_pk_fma_f32 v[148:149], v[186:187], v[148:149], v[186:187] neg_lo:[1,0,0] neg_hi:[1,0,0]
	v_cmp_gt_f32_e32 vcc, 0, v156
	v_cmp_gt_f32_e64 s[4:5], 0, v158
	v_mov_b32_e32 v175, v173
	v_cndmask_b32_e32 v179, v147, v181, vcc
	v_cndmask_b32_e32 v181, v149, v225, vcc
	v_cmp_gt_f32_e32 vcc, 0, v159
	v_mov_b32_e32 v183, v185
	v_cndmask_b32_e64 v178, v146, v180, s[4:5]
	v_cndmask_b32_e32 v180, v148, v224, vcc
	v_pk_mul_f32 v[148:149], v[172:173], v[184:185]
	v_pk_mul_f32 v[158:159], v[174:175], v[182:183]
	v_mov_b32_e32 v156, v154
	v_mov_b32_e32 v174, v155
	v_mov_b32_e32 v175, v157
	v_pk_mul_f32 v[172:173], v[156:157], v[148:149]
	v_pk_mul_f32 v[182:183], v[174:175], v[158:159]
	v_pk_fma_f32 v[148:149], v[156:157], v[148:149], v[156:157] neg_lo:[1,0,0] neg_hi:[1,0,0]
	v_pk_fma_f32 v[158:159], v[174:175], v[158:159], v[174:175] neg_lo:[1,0,0] neg_hi:[1,0,0]
	v_cmp_gt_f32_e32 vcc, 0, v157
	v_cmp_gt_f32_e64 s[4:5], 0, v154
	v_add_lshl_u32 v160, v1, v207, 1
	v_cndmask_b32_e32 v157, v149, v173, vcc
	v_cndmask_b32_e64 v156, v148, v172, s[4:5]
	v_cndmask_b32_e32 v159, v159, v183, vcc
	v_cmp_gt_f32_e32 vcc, 0, v155
	v_pk_mul_f32 v[174:175], v[156:157], v[156:157]
	v_mul_f32_e32 v151, v150, v150
	v_cndmask_b32_e32 v158, v158, v182, vcc
	v_mul_f32_e32 v153, v152, v152
	v_mul_f32_e32 v209, v208, v208
	v_mul_f32_e32 v211, v210, v210
	v_mul_f32_e32 v215, v214, v214
	v_mul_f32_e32 v223, v222, v222
	v_mul_f32_e32 v227, v226, v226
	v_mul_f32_e32 v229, v228, v228
	v_add_lshl_u32 v171, v1, v188, 1
	v_cvt_pk_bf16_f32 v146, v178, v180
	v_cvt_pk_bf16_f32 v147, v156, v158
	v_pk_mul_f32 v[154:155], v[178:179], v[178:179]
	v_pk_mul_f32 v[172:173], v[180:181], v[180:181]
	v_pk_mul_f32 v[182:183], v[158:159], v[158:159]
	v_pk_mov_b32 v[154:155], v[178:179], v[154:155] op_sel:[1,0]
	v_pk_mov_b32 v[172:173], v[156:157], v[172:173] op_sel:[1,0]
	v_cvt_pk_bf16_f32 v148, v179, v157
	v_mov_b32_e32 v1, v161
	v_pk_add_f32 v[154:155], v[154:155], v[172:173]
	v_mov_b32_e32 v172, v176
	v_mov_b32_e32 v173, v174
	v_pk_mov_b32 v[174:175], v[176:177], v[182:183] op_sel:[1,0]
	v_cvt_pk_bf16_f32 v149, v176, v177
	buffer_store_dwordx4 v[146:149], v160, s[28:31], 0 offen sc1
	v_pk_add_f32 v[172:173], v[172:173], v[174:175]
	v_pk_mul_f32 v[174:175], v[178:179], v[180:181]
	v_pk_add_f32 v[154:155], v[154:155], v[172:173]
	v_pk_add_f32 v[172:173], v[178:179], v[180:181]
	s_nop 0
	v_mov_b32_e32 v173, v175
	v_pk_add_f32 v[174:175], v[156:157], v[158:159]
	v_pk_mul_f32 v[156:157], v[156:157], v[158:159]
	s_nop 0
	v_mov_b32_e32 v175, v157
	v_pk_add_f32 v[156:157], v[172:173], v[174:175]
	s_nop 0
	v_pk_add_f32 v[156:157], v[156:157], v[0:1]
	s_nop 0
	v_pk_add_f32 v[154:155], v[154:155], v[156:157]
	v_cvt_pk_bf16_f32 v146, v150, v152
	v_pk_add_f32 v[148:149], v[150:151], v[152:153]
	v_pk_add_f32 v[150:151], v[208:209], v[210:211]
	v_cvt_pk_bf16_f32 v147, v208, v210
	s_nop 0
	v_pk_add_f32 v[148:149], v[148:149], v[150:151]
	s_nop 0
	v_pk_add_f32 v[150:151], v[148:149], v[154:155]
	v_pk_add_f32 v[152:153], v[214:215], v[222:223]
	v_pk_add_f32 v[154:155], v[226:227], v[228:229]
	v_cvt_pk_bf16_f32 v148, v214, v222
	v_cvt_pk_bf16_f32 v149, v226, v228
	buffer_store_dwordx4 v[146:149], v171, s[28:31], 0 offen sc1
	v_pk_add_f32 v[152:153], v[152:153], v[154:155]
	s_nop 0
	v_pk_add_f32 v[150:151], v[152:153], v[150:151]
	v_and_b32_e32 v146, 64, v216
	v_xor_b32_e32 v1, 16, v216
	v_add_u32_e32 v148, 64, v146
	v_cmp_lt_i32_e32 vcc, v1, v148
	s_nop 1
	v_cndmask_b32_e32 v1, v216, v1, vcc
	v_lshlrev_b32_e32 v174, 2, v1
	ds_bpermute_b32 v146, v174, v150
	ds_bpermute_b32 v147, v174, v151
	v_xor_b32_e32 v1, 32, v216
	v_cmp_lt_i32_e32 vcc, v1, v148
	s_waitcnt lgkmcnt(0)
	v_pk_add_f32 v[146:147], v[150:151], v[146:147]
	v_cndmask_b32_e32 v1, v216, v1, vcc
	v_lshlrev_b32_e32 v175, 2, v1
	ds_bpermute_b32 v148, v175, v146
	ds_bpermute_b32 v149, v175, v147
	s_and_saveexec_b64 s[4:5], s[46:47]
	s_cbranch_execz .LBB0_215
	v_ashrrev_i32_e32 v171, 31, v170
	v_lshlrev_b64 v[150:151], 7, v[170:171]
	v_lshl_add_u64 v[150:151], s[12:13], 0, v[150:151]
	s_lshl_b32 s38, s36, 3
	v_lshl_add_u64 v[150:151], v[150:151], 0, s[38:39]
	s_lshl_b32 s38, s57, 3
	v_lshl_add_u64 v[150:151], v[150:151], 0, s[38:39]
	s_waitcnt lgkmcnt(0)
	v_pk_add_f32 v[146:147], v[146:147], v[148:149]
	flat_store_dwordx2 v[150:151], v[146:147]

.LBB0_395:
	s_cmp_ge_u32 s60, 0x1000
	s_cbranch_scc0 .Lprio_done_0
	s_setprio 1
.Lprio_done_0:
	s_add_i32 s66, s66, 1
	s_mov_b64 s[36:37], s[20:21]
	s_mul_i32 s20, s66, s26
	s_add_i32 s42, s20, s2
	s_cmpk_gt_i32 s42, 0x3ff
	s_cselect_b64 s[52:53], -1, 0
	s_lshl_b32 s20, s42, 3
	s_and_b32 s20, s20, 56
	s_bfe_u32 s21, s42, 0x30003
	s_mov_b32 s3, s67
	s_or_b32 s67, s20, s21
	s_mov_b32 s27, s50
	s_ashr_i32 s50, s42, 6
	s_lshl_b32 s20, s67, 19
	s_mov_b64 s[4:5], s[48:49]
	s_add_u32 s48, s18, s20
	s_addc_u32 s49, s19, 0
	s_ashr_i32 s51, s50, 31
	s_lshl_b64 s[20:21], s[50:51], 19
	s_add_u32 s20, s16, s20
	s_addc_u32 s21, s17, s21
	s_cmpk_lt_i32 s42, 0x400
	s_cselect_b32 s46, s49, s5
	s_cselect_b32 s47, s48, s4
	s_cselect_b32 s51, s21, s37
	s_cselect_b32 s54, s20, s36
	s_add_u32 s55, s36, 0x100
	s_addc_u32 s56, s37, 0
	s_mov_b32 s57, -2
	s_add_u32 s36, s4, 0x100
	s_addc_u32 s37, s5, 0
	s_add_i32 s68, 0, 0x10000
	v_add_u32_e32 v30, s68, v204
	ds_read_b128 v[14:17], v30
	ds_read_b128 v[22:25], v30 offset:1024
	ds_read_b128 v[26:29], v30 offset:2048
	ds_read_b128 v[30:33], v30 offset:3072
	s_cmp_eq_u32 s57, 12
	s_cselect_b32 s45, s46, s37
	s_cselect_b32 s44, s47, s36
	s_cselect_b32 s43, s51, s56
	s_cselect_b32 s42, s54, s55
	v_lshl_add_u64 v[178:179], s[4:5], 0, v[188:189]
	s_add_i32 m0, s60, 0xc000
	ds_read_b128 v[38:41], v209
	ds_read_b128 v[42:45], v209 offset:1024
	ds_read_b128 v[46:49], v209 offset:2048
	ds_read_b128 v[54:57], v209 offset:3072
	ds_read_b128 v[58:61], v209 offset:4096
	ds_read_b128 v[62:65], v209 offset:5120
	ds_read_b128 v[66:69], v209 offset:6144
	ds_read_b128 v[70:73], v209 offset:7168
	global_load_lds_dwordx4 v[178:179], off
	v_lshl_add_u64 v[178:179], s[4:5], 0, v[186:187]
	s_add_i32 m0, s60, 0xe000
	s_nop 0
	global_load_lds_dwordx4 v[178:179], off
	s_waitcnt lgkmcnt(8)
	s_barrier
	s_waitcnt lgkmcnt(0)
	s_waitcnt lgkmcnt(0)
	v_mfma_f32_16x16x32_bf16 v[174:177], v[14:17], v[38:41], 0
	v_mfma_f32_16x16x32_bf16 v[170:173], v[26:29], v[38:41], 0
	v_mfma_f32_16x16x32_bf16 v[158:161], v[14:17], v[46:49], 0
	v_mfma_f32_16x16x32_bf16 v[154:157], v[26:29], v[46:49], 0
	v_mfma_f32_16x16x32_bf16 v[142:145], v[14:17], v[58:61], 0
	v_mfma_f32_16x16x32_bf16 v[138:141], v[26:29], v[58:61], 0
	v_mfma_f32_16x16x32_bf16 v[126:129], v[14:17], v[66:69], 0
	v_mfma_f32_16x16x32_bf16 v[122:125], v[26:29], v[66:69], 0
	v_mfma_f32_16x16x32_bf16 v[174:177], v[22:25], v[42:45], v[174:177]
	v_mfma_f32_16x16x32_bf16 v[170:173], v[30:33], v[42:45], v[170:173]
	v_mfma_f32_16x16x32_bf16 v[158:161], v[22:25], v[54:57], v[158:161]
	v_mfma_f32_16x16x32_bf16 v[154:157], v[30:33], v[54:57], v[154:157]
	v_mfma_f32_16x16x32_bf16 v[142:145], v[22:25], v[62:65], v[142:145]
	v_mfma_f32_16x16x32_bf16 v[138:141], v[30:33], v[62:65], v[138:141]
	v_mfma_f32_16x16x32_bf16 v[126:129], v[22:25], v[70:73], v[126:129]
	v_mfma_f32_16x16x32_bf16 v[122:125], v[30:33], v[70:73], v[122:125]
	s_barrier
	v_mbcnt_lo_u32_b32 v250, -1, 0
	v_mbcnt_hi_u32_b32 v250, -1, v250
	v_lshlrev_b32_e32 v250, 4, v250
	s_lshl_b32 s32, s27, 10
	s_add_u32 s90, s10, s32
	s_addc_u32 s91, s11, 0
	s_add_u32 s92, s12, s32
	s_addc_u32 s93, s13, 0
	s_and_b32 s32, s27, 3
	s_lshl_b32 s32, s32, 10
	s_add_u32 s98, s14, s32
	s_addc_u32 s99, s15, 0
	s_mov_b32 m0, 0x20840
	s_nop 0
	global_load_lds_dwordx4 v250, s[90:91]
	s_mov_b32 m0, 0x20c40
	s_nop 0
	global_load_lds_dwordx4 v250, s[92:93]
	s_mov_b32 m0, 0x21040
	s_nop 0
	global_load_lds_dwordx4 v250, s[98:99]
	s_add_i32 s69, 0, 0x14000
	v_add_u32_e32 v210, s69, v204
	s_add_i32 s4, s68, s59
	ds_read_b128 v[178:181], v210
	ds_read_b128 v[190:193], v210 offset:1024
	ds_read_b128 v[200:203], v210 offset:2048
	ds_read_b128 v[222:225], v210 offset:3072
	v_lshl_add_u64 v[210:211], s[42:43], 0, v[184:185]
	s_mov_b32 m0, s4
	v_lshl_add_u64 v[214:215], s[42:43], 0, v[182:183]
	global_load_lds_dwordx4 v[210:211], off
	s_add_i32 m0, s4, 0x2000
	s_nop 0
	global_load_lds_dwordx4 v[214:215], off
	s_barrier
	s_waitcnt lgkmcnt(0)
	s_waitcnt lgkmcnt(0)
	v_mfma_f32_16x16x32_bf16 v[166:169], v[178:181], v[38:41], 0
	v_mfma_f32_16x16x32_bf16 v[38:41], v[200:203], v[38:41], 0
	v_mfma_f32_16x16x32_bf16 v[166:169], v[190:193], v[42:45], v[166:169]
	v_mfma_f32_16x16x32_bf16 v[38:41], v[222:225], v[42:45], v[38:41]
	v_mfma_f32_16x16x32_bf16 v[42:45], v[178:181], v[46:49], 0
	v_mfma_f32_16x16x32_bf16 v[46:49], v[200:203], v[46:49], 0
	v_mfma_f32_16x16x32_bf16 v[42:45], v[190:193], v[54:57], v[42:45]
	v_mfma_f32_16x16x32_bf16 v[46:49], v[222:225], v[54:57], v[46:49]
	v_mfma_f32_16x16x32_bf16 v[54:57], v[178:181], v[58:61], 0
	v_mfma_f32_16x16x32_bf16 v[58:61], v[200:203], v[58:61], 0
	v_mfma_f32_16x16x32_bf16 v[54:57], v[190:193], v[62:65], v[54:57]
	v_mfma_f32_16x16x32_bf16 v[58:61], v[222:225], v[62:65], v[58:61]
	v_mfma_f32_16x16x32_bf16 v[62:65], v[178:181], v[66:69], 0
	v_mfma_f32_16x16x32_bf16 v[66:69], v[200:203], v[66:69], 0
	v_mfma_f32_16x16x32_bf16 v[62:65], v[190:193], v[70:73], v[62:65]
	v_mfma_f32_16x16x32_bf16 v[66:69], v[222:225], v[70:73], v[66:69]
	s_mov_b32 m0, s60
	v_lshl_add_u64 v[242:243], s[44:45], 0, v[184:185]
	s_barrier
	ds_read_b128 v[70:73], v209 offset:16384
	ds_read_b128 v[114:117], v209 offset:17408
	ds_read_b128 v[118:121], v209 offset:18432
	ds_read_b128 v[130:133], v209 offset:19456
	ds_read_b128 v[134:137], v209 offset:20480
	ds_read_b128 v[146:149], v209 offset:21504
	ds_read_b128 v[150:153], v209 offset:22528
	ds_read_b128 v[162:165], v209 offset:23552
	global_load_lds_dwordx4 v[242:243], off
	v_lshl_add_u64 v[244:245], s[44:45], 0, v[182:183]
	s_mov_b32 m0, s61
	s_nop 0
	global_load_lds_dwordx4 v[244:245], off
	s_barrier
	s_waitcnt lgkmcnt(0)
	s_waitcnt lgkmcnt(0)
	v_mfma_f32_16x16x32_bf16 v[110:113], v[14:17], v[70:73], 0
	v_mfma_f32_16x16x32_bf16 v[106:109], v[26:29], v[70:73], 0
	v_mfma_f32_16x16x32_bf16 v[94:97], v[14:17], v[118:121], 0
	v_mfma_f32_16x16x32_bf16 v[90:93], v[26:29], v[118:121], 0
	v_mfma_f32_16x16x32_bf16 v[78:81], v[14:17], v[134:137], 0
	v_mfma_f32_16x16x32_bf16 v[74:77], v[26:29], v[134:137], 0
	v_mfma_f32_16x16x32_bf16 v[10:13], v[26:29], v[150:153], 0
	v_mfma_f32_16x16x32_bf16 v[110:113], v[22:25], v[114:117], v[110:113]
	v_mfma_f32_16x16x32_bf16 v[106:109], v[30:33], v[114:117], v[106:109]
	v_mfma_f32_16x16x32_bf16 v[94:97], v[22:25], v[130:133], v[94:97]
	v_mfma_f32_16x16x32_bf16 v[90:93], v[30:33], v[130:133], v[90:93]
	v_mfma_f32_16x16x32_bf16 v[78:81], v[22:25], v[146:149], v[78:81]
	v_mfma_f32_16x16x32_bf16 v[74:77], v[30:33], v[146:149], v[74:77]
	v_mfma_f32_16x16x32_bf16 v[14:17], v[14:17], v[150:153], 0
	v_mfma_f32_16x16x32_bf16 v[10:13], v[30:33], v[162:165], v[10:13]
	v_mfma_f32_16x16x32_bf16 v[14:17], v[22:25], v[162:165], v[14:17]
	s_barrier
	s_add_u32 s4, s42, 0x40000
	s_addc_u32 s5, s43, 0
	s_add_i32 s68, s69, s59
	v_lshl_add_u64 v[18:19], s[4:5], 0, v[184:185]
	s_mov_b32 m0, s68
	s_nop 0
	global_load_lds_dwordx4 v[18:19], off
	v_lshl_add_u64 v[18:19], s[4:5], 0, v[182:183]
	s_add_i32 m0, s68, 0x2000
	s_nop 0
	global_load_lds_dwordx4 v[18:19], off
	s_waitcnt vmcnt(6)
	s_barrier
	v_mfma_f32_16x16x32_bf16 v[18:21], v[178:181], v[70:73], 0
	v_mfma_f32_16x16x32_bf16 v[22:25], v[190:193], v[114:117], v[18:21]
	v_mfma_f32_16x16x32_bf16 v[18:21], v[200:203], v[70:73], 0
	v_mfma_f32_16x16x32_bf16 v[26:29], v[222:225], v[114:117], v[18:21]
	v_mfma_f32_16x16x32_bf16 v[18:21], v[178:181], v[118:121], 0
	v_mfma_f32_16x16x32_bf16 v[30:33], v[190:193], v[130:133], v[18:21]
	v_mfma_f32_16x16x32_bf16 v[18:21], v[200:203], v[118:121], 0
	v_mfma_f32_16x16x32_bf16 v[70:73], v[222:225], v[130:133], v[18:21]
	v_mfma_f32_16x16x32_bf16 v[18:21], v[178:181], v[134:137], 0
	v_mfma_f32_16x16x32_bf16 v[50:53], v[190:193], v[146:149], v[18:21]
	v_mfma_f32_16x16x32_bf16 v[18:21], v[200:203], v[134:137], 0
	v_mfma_f32_16x16x32_bf16 v[6:9], v[178:181], v[150:153], 0
	v_mfma_f32_16x16x32_bf16 v[2:5], v[200:203], v[150:153], 0
	v_mfma_f32_16x16x32_bf16 v[34:37], v[222:225], v[146:149], v[18:21]
	v_mfma_f32_16x16x32_bf16 v[6:9], v[190:193], v[162:165], v[6:9]
	v_mfma_f32_16x16x32_bf16 v[2:5], v[222:225], v[162:165], v[2:5]
	s_add_i32 s68, 0, 0x18000
	v_add_u32_e32 v98, s68, v204
	s_barrier
	ds_read_b128 v[18:21], v98
	ds_read_b128 v[82:85], v98 offset:1024
	ds_read_b128 v[86:89], v98 offset:2048
	ds_read_b128 v[98:101], v98 offset:3072
	s_add_u32 s4, s44, 0x40000
	s_addc_u32 s5, s45, 0
	s_mov_b32 m0, s62
	v_lshl_add_u64 v[134:135], s[4:5], 0, v[184:185]
	ds_read_b128 v[102:105], v209 offset:32768
	ds_read_b128 v[114:117], v209 offset:33792
	ds_read_b128 v[118:121], v209 offset:34816
	ds_read_b128 v[130:133], v209 offset:35840
	ds_read_b128 v[178:181], v209 offset:36864
	ds_read_b128 v[190:193], v209 offset:37888
	ds_read_b128 v[200:203], v209 offset:38912
	ds_read_b128 v[222:225], v209 offset:39936
	global_load_lds_dwordx4 v[134:135], off
	v_lshl_add_u64 v[134:135], s[4:5], 0, v[182:183]
	s_mov_b32 m0, s63
	s_nop 0
	global_load_lds_dwordx4 v[134:135], off
	s_waitcnt lgkmcnt(8)
	s_barrier
	s_waitcnt lgkmcnt(0)
	s_waitcnt lgkmcnt(0)
	v_mfma_f32_16x16x32_bf16 v[134:137], v[18:21], v[102:105], v[174:177]
	v_mfma_f32_16x16x32_bf16 v[174:177], v[82:85], v[114:117], v[134:137]
	v_mfma_f32_16x16x32_bf16 v[134:137], v[86:89], v[102:105], v[170:173]
	v_mfma_f32_16x16x32_bf16 v[170:173], v[98:101], v[114:117], v[134:137]
	v_mfma_f32_16x16x32_bf16 v[134:137], v[18:21], v[118:121], v[158:161]
	v_mfma_f32_16x16x32_bf16 v[158:161], v[82:85], v[130:133], v[134:137]
	v_mfma_f32_16x16x32_bf16 v[134:137], v[86:89], v[118:121], v[154:157]
	v_mfma_f32_16x16x32_bf16 v[154:157], v[98:101], v[130:133], v[134:137]
	v_mfma_f32_16x16x32_bf16 v[134:137], v[18:21], v[178:181], v[142:145]
	v_mfma_f32_16x16x32_bf16 v[142:145], v[82:85], v[190:193], v[134:137]
	v_mfma_f32_16x16x32_bf16 v[134:137], v[86:89], v[178:181], v[138:141]
	v_mfma_f32_16x16x32_bf16 v[126:129], v[18:21], v[200:203], v[126:129]
	v_mfma_f32_16x16x32_bf16 v[122:125], v[86:89], v[200:203], v[122:125]
	v_mfma_f32_16x16x32_bf16 v[138:141], v[98:101], v[190:193], v[134:137]
	v_mfma_f32_16x16x32_bf16 v[126:129], v[82:85], v[222:225], v[126:129]
	v_mfma_f32_16x16x32_bf16 v[122:125], v[98:101], v[222:225], v[122:125]
	s_barrier
	s_add_i32 s44, 0, 0x1c000
	v_add_u32_e32 v134, s44, v204
	s_add_i32 s4, s68, s59
	ds_read_b128 v[226:229], v134
	ds_read_b128 v[230:233], v134 offset:1024
	ds_read_b128 v[234:237], v134 offset:2048
	ds_read_b128 v[238:241], v134 offset:3072
	v_lshl_add_u64 v[134:135], v[210:211], 0, s[22:23]
	s_mov_b32 m0, s4
	s_nop 0
	global_load_lds_dwordx4 v[134:135], off
	v_lshl_add_u64 v[134:135], v[214:215], 0, s[22:23]
	s_add_i32 m0, s4, 0x2000
	s_nop 0
	global_load_lds_dwordx4 v[134:135], off
	s_barrier
	s_waitcnt lgkmcnt(0)
	s_waitcnt lgkmcnt(0)
	v_mfma_f32_16x16x32_bf16 v[38:41], v[234:237], v[102:105], v[38:41]
	v_mfma_f32_16x16x32_bf16 v[162:165], v[238:241], v[114:117], v[38:41]
	v_mfma_f32_16x16x32_bf16 v[38:41], v[226:229], v[118:121], v[42:45]
	v_mfma_f32_16x16x32_bf16 v[150:153], v[230:233], v[130:133], v[38:41]
	v_mfma_f32_16x16x32_bf16 v[38:41], v[234:237], v[118:121], v[46:49]
	v_mfma_f32_16x16x32_bf16 v[134:137], v[226:229], v[102:105], v[166:169]
	v_mfma_f32_16x16x32_bf16 v[146:149], v[238:241], v[130:133], v[38:41]
	v_mfma_f32_16x16x32_bf16 v[38:41], v[226:229], v[178:181], v[54:57]
	v_mfma_f32_16x16x32_bf16 v[166:169], v[230:233], v[114:117], v[134:137]
	v_mfma_f32_16x16x32_bf16 v[134:137], v[230:233], v[190:193], v[38:41]
	v_mfma_f32_16x16x32_bf16 v[38:41], v[234:237], v[178:181], v[58:61]
	v_mfma_f32_16x16x32_bf16 v[130:133], v[238:241], v[190:193], v[38:41]
	v_mfma_f32_16x16x32_bf16 v[38:41], v[226:229], v[200:203], v[62:65]
	v_mfma_f32_16x16x32_bf16 v[118:121], v[230:233], v[222:225], v[38:41]
	v_mfma_f32_16x16x32_bf16 v[38:41], v[234:237], v[200:203], v[66:69]
	v_mfma_f32_16x16x32_bf16 v[114:117], v[238:241], v[222:225], v[38:41]
	s_mov_b32 m0, s64
	v_lshl_add_u64 v[102:103], v[242:243], 0, s[22:23]
	s_barrier
	s_nop 2
	ds_read_b128 v[38:41], v209 offset:49152
	ds_read_b128 v[42:45], v209 offset:50176
	ds_read_b128 v[46:49], v209 offset:51200
	ds_read_b128 v[54:57], v209 offset:52224
	ds_read_b128 v[58:61], v209 offset:53248
	ds_read_b128 v[62:65], v209 offset:54272
	ds_read_b128 v[66:69], v209 offset:55296
	ds_read_b128 v[178:181], v209 offset:56320
	global_load_lds_dwordx4 v[102:103], off
	v_lshl_add_u64 v[102:103], v[244:245], 0, s[22:23]
	s_mov_b32 m0, s65
	s_nop 0
	global_load_lds_dwordx4 v[102:103], off
	s_barrier
	s_waitcnt lgkmcnt(0)
	s_waitcnt lgkmcnt(0)
	v_mfma_f32_16x16x32_bf16 v[102:105], v[18:21], v[38:41], v[110:113]
	v_mfma_f32_16x16x32_bf16 v[110:113], v[82:85], v[42:45], v[102:105]
	v_mfma_f32_16x16x32_bf16 v[102:105], v[86:89], v[38:41], v[106:109]
	v_mfma_f32_16x16x32_bf16 v[94:97], v[18:21], v[46:49], v[94:97]
	v_mfma_f32_16x16x32_bf16 v[90:93], v[86:89], v[46:49], v[90:93]
	v_mfma_f32_16x16x32_bf16 v[78:81], v[18:21], v[58:61], v[78:81]
	v_mfma_f32_16x16x32_bf16 v[74:77], v[86:89], v[58:61], v[74:77]
	v_mfma_f32_16x16x32_bf16 v[14:17], v[18:21], v[66:69], v[14:17]
	v_mfma_f32_16x16x32_bf16 v[10:13], v[86:89], v[66:69], v[10:13]
	v_mfma_f32_16x16x32_bf16 v[106:109], v[98:101], v[42:45], v[102:105]
	v_mfma_f32_16x16x32_bf16 v[94:97], v[82:85], v[54:57], v[94:97]
	v_mfma_f32_16x16x32_bf16 v[90:93], v[98:101], v[54:57], v[90:93]
	v_mfma_f32_16x16x32_bf16 v[78:81], v[82:85], v[62:65], v[78:81]
	v_mfma_f32_16x16x32_bf16 v[74:77], v[98:101], v[62:65], v[74:77]
	v_mfma_f32_16x16x32_bf16 v[18:21], v[82:85], v[178:181], v[14:17]
	v_mfma_f32_16x16x32_bf16 v[10:13], v[98:101], v[178:181], v[10:13]
	s_barrier
	s_add_u32 s4, s42, 0x40080
	s_addc_u32 s5, s43, 0
	s_add_i32 s42, s44, s59
	v_lshl_add_u64 v[14:15], s[4:5], 0, v[184:185]
	s_mov_b32 m0, s42
	s_nop 0
	global_load_lds_dwordx4 v[14:15], off
	v_lshl_add_u64 v[14:15], s[4:5], 0, v[182:183]
	s_add_i32 m0, s42, 0x2000
	s_nop 0
	global_load_lds_dwordx4 v[14:15], off
	s_waitcnt vmcnt(6)
	s_barrier
	v_mfma_f32_16x16x32_bf16 v[14:17], v[226:229], v[38:41], v[22:25]
	v_mfma_f32_16x16x32_bf16 v[102:105], v[230:233], v[42:45], v[14:17]
	v_mfma_f32_16x16x32_bf16 v[14:17], v[234:237], v[38:41], v[26:29]
	v_mfma_f32_16x16x32_bf16 v[98:101], v[238:241], v[42:45], v[14:17]
	v_mfma_f32_16x16x32_bf16 v[14:17], v[226:229], v[46:49], v[30:33]
	v_mfma_f32_16x16x32_bf16 v[86:89], v[230:233], v[54:57], v[14:17]
	v_mfma_f32_16x16x32_bf16 v[14:17], v[234:237], v[46:49], v[70:73]
	v_mfma_f32_16x16x32_bf16 v[82:85], v[238:241], v[54:57], v[14:17]
	v_mfma_f32_16x16x32_bf16 v[14:17], v[226:229], v[58:61], v[50:53]
	v_mfma_f32_16x16x32_bf16 v[50:53], v[230:233], v[62:65], v[14:17]
	v_mfma_f32_16x16x32_bf16 v[14:17], v[234:237], v[58:61], v[34:37]
	v_mfma_f32_16x16x32_bf16 v[6:9], v[226:229], v[66:69], v[6:9]
	v_mfma_f32_16x16x32_bf16 v[2:5], v[234:237], v[66:69], v[2:5]
	v_mfma_f32_16x16x32_bf16 v[34:37], v[238:241], v[62:65], v[14:17]
	v_mfma_f32_16x16x32_bf16 v[6:9], v[230:233], v[178:181], v[6:9]
	v_mfma_f32_16x16x32_bf16 v[2:5], v[238:241], v[178:181], v[2:5]
	s_add_i32 s57, s57, 2
	s_add_u32 s55, s55, 0x100
	s_addc_u32 s56, s56, 0
	s_cmp_gt_u32 s57, 13
	s_mov_b64 s[4:5], s[36:37]
	s_barrier
.LBB0_396:
	s_add_u32 s36, s4, 0x100
	s_addc_u32 s37, s5, 0
	s_add_i32 s68, 0, 0x10000
	v_add_u32_e32 v30, s68, v204
	ds_read_b128 v[14:17], v30
	ds_read_b128 v[22:25], v30 offset:1024
	ds_read_b128 v[26:29], v30 offset:2048
	ds_read_b128 v[30:33], v30 offset:3072
	s_cmp_eq_u32 s57, 12
	s_cselect_b32 s45, s46, s37
	s_cselect_b32 s44, s47, s36
	s_cselect_b32 s43, s51, s56
	s_cselect_b32 s42, s54, s55
	v_lshl_add_u64 v[178:179], s[4:5], 0, v[188:189]
	s_add_i32 m0, s60, 0xc000
	ds_read_b128 v[38:41], v209
	ds_read_b128 v[42:45], v209 offset:1024
	ds_read_b128 v[46:49], v209 offset:2048
	ds_read_b128 v[54:57], v209 offset:3072
	ds_read_b128 v[58:61], v209 offset:4096
	ds_read_b128 v[62:65], v209 offset:5120
	ds_read_b128 v[66:69], v209 offset:6144
	ds_read_b128 v[70:73], v209 offset:7168
	global_load_lds_dwordx4 v[178:179], off
	v_lshl_add_u64 v[178:179], s[4:5], 0, v[186:187]
	s_add_i32 m0, s60, 0xe000
	s_nop 0
	global_load_lds_dwordx4 v[178:179], off
	s_waitcnt lgkmcnt(8)
	s_barrier
	s_waitcnt lgkmcnt(0)
	s_waitcnt lgkmcnt(0)
	v_mfma_f32_16x16x32_bf16 v[174:177], v[14:17], v[38:41], v[174:177]
	v_mfma_f32_16x16x32_bf16 v[170:173], v[26:29], v[38:41], v[170:173]
	v_mfma_f32_16x16x32_bf16 v[158:161], v[14:17], v[46:49], v[158:161]
	v_mfma_f32_16x16x32_bf16 v[154:157], v[26:29], v[46:49], v[154:157]
	v_mfma_f32_16x16x32_bf16 v[142:145], v[14:17], v[58:61], v[142:145]
	v_mfma_f32_16x16x32_bf16 v[138:141], v[26:29], v[58:61], v[138:141]
	v_mfma_f32_16x16x32_bf16 v[126:129], v[14:17], v[66:69], v[126:129]
	v_mfma_f32_16x16x32_bf16 v[122:125], v[26:29], v[66:69], v[122:125]
	v_mfma_f32_16x16x32_bf16 v[174:177], v[22:25], v[42:45], v[174:177]
	v_mfma_f32_16x16x32_bf16 v[170:173], v[30:33], v[42:45], v[170:173]
	v_mfma_f32_16x16x32_bf16 v[158:161], v[22:25], v[54:57], v[158:161]
	v_mfma_f32_16x16x32_bf16 v[154:157], v[30:33], v[54:57], v[154:157]
	v_mfma_f32_16x16x32_bf16 v[142:145], v[22:25], v[62:65], v[142:145]
	v_mfma_f32_16x16x32_bf16 v[138:141], v[30:33], v[62:65], v[138:141]
	v_mfma_f32_16x16x32_bf16 v[126:129], v[22:25], v[70:73], v[126:129]
	v_mfma_f32_16x16x32_bf16 v[122:125], v[30:33], v[70:73], v[122:125]
	s_barrier
	s_add_i32 s69, 0, 0x14000
	v_add_u32_e32 v210, s69, v204
	s_add_i32 s4, s68, s59
	ds_read_b128 v[178:181], v210
	ds_read_b128 v[190:193], v210 offset:1024
	ds_read_b128 v[200:203], v210 offset:2048
	ds_read_b128 v[222:225], v210 offset:3072
	v_lshl_add_u64 v[210:211], s[42:43], 0, v[184:185]
	s_mov_b32 m0, s4
	v_lshl_add_u64 v[214:215], s[42:43], 0, v[182:183]
	global_load_lds_dwordx4 v[210:211], off
	s_add_i32 m0, s4, 0x2000
	s_nop 0
	global_load_lds_dwordx4 v[214:215], off
	s_barrier
	s_waitcnt lgkmcnt(0)
	s_waitcnt lgkmcnt(0)
	v_mfma_f32_16x16x32_bf16 v[166:169], v[178:181], v[38:41], v[166:169]
	v_mfma_f32_16x16x32_bf16 v[38:41], v[200:203], v[38:41], v[162:165]
	v_mfma_f32_16x16x32_bf16 v[166:169], v[190:193], v[42:45], v[166:169]
	v_mfma_f32_16x16x32_bf16 v[38:41], v[222:225], v[42:45], v[38:41]
	v_mfma_f32_16x16x32_bf16 v[42:45], v[178:181], v[46:49], v[150:153]
	v_mfma_f32_16x16x32_bf16 v[46:49], v[200:203], v[46:49], v[146:149]
	v_mfma_f32_16x16x32_bf16 v[42:45], v[190:193], v[54:57], v[42:45]
	v_mfma_f32_16x16x32_bf16 v[46:49], v[222:225], v[54:57], v[46:49]
	v_mfma_f32_16x16x32_bf16 v[54:57], v[178:181], v[58:61], v[134:137]
	v_mfma_f32_16x16x32_bf16 v[58:61], v[200:203], v[58:61], v[130:133]
	v_mfma_f32_16x16x32_bf16 v[54:57], v[190:193], v[62:65], v[54:57]
	v_mfma_f32_16x16x32_bf16 v[58:61], v[222:225], v[62:65], v[58:61]
	v_mfma_f32_16x16x32_bf16 v[62:65], v[178:181], v[66:69], v[118:121]
	v_mfma_f32_16x16x32_bf16 v[66:69], v[200:203], v[66:69], v[114:117]
	v_mfma_f32_16x16x32_bf16 v[62:65], v[190:193], v[70:73], v[62:65]
	v_mfma_f32_16x16x32_bf16 v[66:69], v[222:225], v[70:73], v[66:69]
	s_mov_b32 m0, s60
	v_lshl_add_u64 v[242:243], s[44:45], 0, v[184:185]
	s_barrier
	ds_read_b128 v[70:73], v209 offset:16384
	ds_read_b128 v[114:117], v209 offset:17408
	ds_read_b128 v[118:121], v209 offset:18432
	ds_read_b128 v[130:133], v209 offset:19456
	ds_read_b128 v[134:137], v209 offset:20480
	ds_read_b128 v[146:149], v209 offset:21504
	ds_read_b128 v[150:153], v209 offset:22528
	ds_read_b128 v[162:165], v209 offset:23552
	global_load_lds_dwordx4 v[242:243], off
	v_lshl_add_u64 v[244:245], s[44:45], 0, v[182:183]
	s_mov_b32 m0, s61
	s_nop 0
	global_load_lds_dwordx4 v[244:245], off
	s_barrier
	s_waitcnt lgkmcnt(0)
	s_waitcnt lgkmcnt(0)
	v_mfma_f32_16x16x32_bf16 v[110:113], v[14:17], v[70:73], v[110:113]
	v_mfma_f32_16x16x32_bf16 v[106:109], v[26:29], v[70:73], v[106:109]
	v_mfma_f32_16x16x32_bf16 v[94:97], v[14:17], v[118:121], v[94:97]
	v_mfma_f32_16x16x32_bf16 v[90:93], v[26:29], v[118:121], v[90:93]
	v_mfma_f32_16x16x32_bf16 v[78:81], v[14:17], v[134:137], v[78:81]
	v_mfma_f32_16x16x32_bf16 v[74:77], v[26:29], v[134:137], v[74:77]
	v_mfma_f32_16x16x32_bf16 v[10:13], v[26:29], v[150:153], v[10:13]
	v_mfma_f32_16x16x32_bf16 v[110:113], v[22:25], v[114:117], v[110:113]
	v_mfma_f32_16x16x32_bf16 v[106:109], v[30:33], v[114:117], v[106:109]
	v_mfma_f32_16x16x32_bf16 v[94:97], v[22:25], v[130:133], v[94:97]
	v_mfma_f32_16x16x32_bf16 v[90:93], v[30:33], v[130:133], v[90:93]
	v_mfma_f32_16x16x32_bf16 v[78:81], v[22:25], v[146:149], v[78:81]
	v_mfma_f32_16x16x32_bf16 v[74:77], v[30:33], v[146:149], v[74:77]
	v_mfma_f32_16x16x32_bf16 v[14:17], v[14:17], v[150:153], v[18:21]
	v_mfma_f32_16x16x32_bf16 v[10:13], v[30:33], v[162:165], v[10:13]
	v_mfma_f32_16x16x32_bf16 v[14:17], v[22:25], v[162:165], v[14:17]
	s_barrier
	s_add_u32 s4, s42, 0x40000
	s_addc_u32 s5, s43, 0
	s_add_i32 s68, s69, s59
	v_lshl_add_u64 v[18:19], s[4:5], 0, v[184:185]
	s_mov_b32 m0, s68
	s_nop 0
	global_load_lds_dwordx4 v[18:19], off
	v_lshl_add_u64 v[18:19], s[4:5], 0, v[182:183]
	s_add_i32 m0, s68, 0x2000
	s_nop 0
	global_load_lds_dwordx4 v[18:19], off
	s_waitcnt vmcnt(6)
	s_barrier
	v_mfma_f32_16x16x32_bf16 v[18:21], v[178:181], v[70:73], v[102:105]
	v_mfma_f32_16x16x32_bf16 v[22:25], v[190:193], v[114:117], v[18:21]
	v_mfma_f32_16x16x32_bf16 v[18:21], v[200:203], v[70:73], v[98:101]
	v_mfma_f32_16x16x32_bf16 v[26:29], v[222:225], v[114:117], v[18:21]
	v_mfma_f32_16x16x32_bf16 v[18:21], v[178:181], v[118:121], v[86:89]
	v_mfma_f32_16x16x32_bf16 v[30:33], v[190:193], v[130:133], v[18:21]
	v_mfma_f32_16x16x32_bf16 v[18:21], v[200:203], v[118:121], v[82:85]
	v_mfma_f32_16x16x32_bf16 v[70:73], v[222:225], v[130:133], v[18:21]
	v_mfma_f32_16x16x32_bf16 v[18:21], v[178:181], v[134:137], v[50:53]
	v_mfma_f32_16x16x32_bf16 v[50:53], v[190:193], v[146:149], v[18:21]
	v_mfma_f32_16x16x32_bf16 v[18:21], v[200:203], v[134:137], v[34:37]
	v_mfma_f32_16x16x32_bf16 v[6:9], v[178:181], v[150:153], v[6:9]
	v_mfma_f32_16x16x32_bf16 v[2:5], v[200:203], v[150:153], v[2:5]
	v_mfma_f32_16x16x32_bf16 v[34:37], v[222:225], v[146:149], v[18:21]
	v_mfma_f32_16x16x32_bf16 v[6:9], v[190:193], v[162:165], v[6:9]
	v_mfma_f32_16x16x32_bf16 v[2:5], v[222:225], v[162:165], v[2:5]
	s_add_i32 s68, 0, 0x18000
	v_add_u32_e32 v98, s68, v204
	s_barrier
	ds_read_b128 v[18:21], v98
	ds_read_b128 v[82:85], v98 offset:1024
	ds_read_b128 v[86:89], v98 offset:2048
	ds_read_b128 v[98:101], v98 offset:3072
	s_add_u32 s4, s44, 0x40000
	s_addc_u32 s5, s45, 0
	s_mov_b32 m0, s62
	v_lshl_add_u64 v[134:135], s[4:5], 0, v[184:185]
	ds_read_b128 v[102:105], v209 offset:32768
	ds_read_b128 v[114:117], v209 offset:33792
	ds_read_b128 v[118:121], v209 offset:34816
	ds_read_b128 v[130:133], v209 offset:35840
	ds_read_b128 v[178:181], v209 offset:36864
	ds_read_b128 v[190:193], v209 offset:37888
	ds_read_b128 v[200:203], v209 offset:38912
	ds_read_b128 v[222:225], v209 offset:39936
	global_load_lds_dwordx4 v[134:135], off
	v_lshl_add_u64 v[134:135], s[4:5], 0, v[182:183]
	s_mov_b32 m0, s63
	s_nop 0
	global_load_lds_dwordx4 v[134:135], off
	s_waitcnt lgkmcnt(8)
	s_barrier
	s_waitcnt lgkmcnt(0)
	s_waitcnt lgkmcnt(0)
	v_mfma_f32_16x16x32_bf16 v[134:137], v[18:21], v[102:105], v[174:177]
	v_mfma_f32_16x16x32_bf16 v[174:177], v[82:85], v[114:117], v[134:137]
	v_mfma_f32_16x16x32_bf16 v[134:137], v[86:89], v[102:105], v[170:173]
	v_mfma_f32_16x16x32_bf16 v[170:173], v[98:101], v[114:117], v[134:137]
	v_mfma_f32_16x16x32_bf16 v[134:137], v[18:21], v[118:121], v[158:161]
	v_mfma_f32_16x16x32_bf16 v[158:161], v[82:85], v[130:133], v[134:137]
	v_mfma_f32_16x16x32_bf16 v[134:137], v[86:89], v[118:121], v[154:157]
	v_mfma_f32_16x16x32_bf16 v[154:157], v[98:101], v[130:133], v[134:137]
	v_mfma_f32_16x16x32_bf16 v[134:137], v[18:21], v[178:181], v[142:145]
	v_mfma_f32_16x16x32_bf16 v[142:145], v[82:85], v[190:193], v[134:137]
	v_mfma_f32_16x16x32_bf16 v[134:137], v[86:89], v[178:181], v[138:141]
	v_mfma_f32_16x16x32_bf16 v[126:129], v[18:21], v[200:203], v[126:129]
	v_mfma_f32_16x16x32_bf16 v[122:125], v[86:89], v[200:203], v[122:125]
	v_mfma_f32_16x16x32_bf16 v[138:141], v[98:101], v[190:193], v[134:137]
	v_mfma_f32_16x16x32_bf16 v[126:129], v[82:85], v[222:225], v[126:129]
	v_mfma_f32_16x16x32_bf16 v[122:125], v[98:101], v[222:225], v[122:125]
	s_barrier
	s_add_i32 s44, 0, 0x1c000
	v_add_u32_e32 v134, s44, v204
	s_add_i32 s4, s68, s59
	ds_read_b128 v[226:229], v134
	ds_read_b128 v[230:233], v134 offset:1024
	ds_read_b128 v[234:237], v134 offset:2048
	ds_read_b128 v[238:241], v134 offset:3072
	v_lshl_add_u64 v[134:135], v[210:211], 0, s[22:23]
	s_mov_b32 m0, s4
	s_nop 0
	global_load_lds_dwordx4 v[134:135], off
	v_lshl_add_u64 v[134:135], v[214:215], 0, s[22:23]
	s_add_i32 m0, s4, 0x2000
	s_nop 0
	global_load_lds_dwordx4 v[134:135], off
	s_barrier
	s_waitcnt lgkmcnt(0)
	s_waitcnt lgkmcnt(0)
	v_mfma_f32_16x16x32_bf16 v[38:41], v[234:237], v[102:105], v[38:41]
	v_mfma_f32_16x16x32_bf16 v[162:165], v[238:241], v[114:117], v[38:41]
	v_mfma_f32_16x16x32_bf16 v[38:41], v[226:229], v[118:121], v[42:45]
	v_mfma_f32_16x16x32_bf16 v[150:153], v[230:233], v[130:133], v[38:41]
	v_mfma_f32_16x16x32_bf16 v[38:41], v[234:237], v[118:121], v[46:49]
	v_mfma_f32_16x16x32_bf16 v[134:137], v[226:229], v[102:105], v[166:169]
	v_mfma_f32_16x16x32_bf16 v[146:149], v[238:241], v[130:133], v[38:41]
	v_mfma_f32_16x16x32_bf16 v[38:41], v[226:229], v[178:181], v[54:57]
	v_mfma_f32_16x16x32_bf16 v[166:169], v[230:233], v[114:117], v[134:137]
	v_mfma_f32_16x16x32_bf16 v[134:137], v[230:233], v[190:193], v[38:41]
	v_mfma_f32_16x16x32_bf16 v[38:41], v[234:237], v[178:181], v[58:61]
	v_mfma_f32_16x16x32_bf16 v[130:133], v[238:241], v[190:193], v[38:41]
	v_mfma_f32_16x16x32_bf16 v[38:41], v[226:229], v[200:203], v[62:65]
	v_mfma_f32_16x16x32_bf16 v[118:121], v[230:233], v[222:225], v[38:41]
	v_mfma_f32_16x16x32_bf16 v[38:41], v[234:237], v[200:203], v[66:69]
	v_mfma_f32_16x16x32_bf16 v[114:117], v[238:241], v[222:225], v[38:41]
	s_mov_b32 m0, s64
	v_lshl_add_u64 v[102:103], v[242:243], 0, s[22:23]
	s_barrier
	s_nop 2
	ds_read_b128 v[38:41], v209 offset:49152
	ds_read_b128 v[42:45], v209 offset:50176
	ds_read_b128 v[46:49], v209 offset:51200
	ds_read_b128 v[54:57], v209 offset:52224
	ds_read_b128 v[58:61], v209 offset:53248
	ds_read_b128 v[62:65], v209 offset:54272
	ds_read_b128 v[66:69], v209 offset:55296
	ds_read_b128 v[178:181], v209 offset:56320
	global_load_lds_dwordx4 v[102:103], off
	v_lshl_add_u64 v[102:103], v[244:245], 0, s[22:23]
	s_mov_b32 m0, s65
	s_nop 0
	global_load_lds_dwordx4 v[102:103], off
	s_barrier
	s_waitcnt lgkmcnt(0)
	s_waitcnt lgkmcnt(0)
	v_mfma_f32_16x16x32_bf16 v[102:105], v[18:21], v[38:41], v[110:113]
	v_mfma_f32_16x16x32_bf16 v[110:113], v[82:85], v[42:45], v[102:105]
	v_mfma_f32_16x16x32_bf16 v[102:105], v[86:89], v[38:41], v[106:109]
	v_mfma_f32_16x16x32_bf16 v[94:97], v[18:21], v[46:49], v[94:97]
	v_mfma_f32_16x16x32_bf16 v[90:93], v[86:89], v[46:49], v[90:93]
	v_mfma_f32_16x16x32_bf16 v[78:81], v[18:21], v[58:61], v[78:81]
	v_mfma_f32_16x16x32_bf16 v[74:77], v[86:89], v[58:61], v[74:77]
	v_mfma_f32_16x16x32_bf16 v[14:17], v[18:21], v[66:69], v[14:17]
	v_mfma_f32_16x16x32_bf16 v[10:13], v[86:89], v[66:69], v[10:13]
	v_mfma_f32_16x16x32_bf16 v[106:109], v[98:101], v[42:45], v[102:105]
	v_mfma_f32_16x16x32_bf16 v[94:97], v[82:85], v[54:57], v[94:97]
	v_mfma_f32_16x16x32_bf16 v[90:93], v[98:101], v[54:57], v[90:93]
	v_mfma_f32_16x16x32_bf16 v[78:81], v[82:85], v[62:65], v[78:81]
	v_mfma_f32_16x16x32_bf16 v[74:77], v[98:101], v[62:65], v[74:77]
	v_mfma_f32_16x16x32_bf16 v[18:21], v[82:85], v[178:181], v[14:17]
	v_mfma_f32_16x16x32_bf16 v[10:13], v[98:101], v[178:181], v[10:13]
	s_barrier
	s_add_u32 s4, s42, 0x40080
	s_addc_u32 s5, s43, 0
	s_add_i32 s42, s44, s59
	v_lshl_add_u64 v[14:15], s[4:5], 0, v[184:185]
	s_mov_b32 m0, s42
	s_nop 0
	global_load_lds_dwordx4 v[14:15], off
	v_lshl_add_u64 v[14:15], s[4:5], 0, v[182:183]
	s_add_i32 m0, s42, 0x2000
	s_nop 0
	global_load_lds_dwordx4 v[14:15], off
	s_waitcnt vmcnt(6)
	s_barrier
	v_mfma_f32_16x16x32_bf16 v[14:17], v[226:229], v[38:41], v[22:25]
	v_mfma_f32_16x16x32_bf16 v[102:105], v[230:233], v[42:45], v[14:17]
	v_mfma_f32_16x16x32_bf16 v[14:17], v[234:237], v[38:41], v[26:29]
	v_mfma_f32_16x16x32_bf16 v[98:101], v[238:241], v[42:45], v[14:17]
	v_mfma_f32_16x16x32_bf16 v[14:17], v[226:229], v[46:49], v[30:33]
	v_mfma_f32_16x16x32_bf16 v[86:89], v[230:233], v[54:57], v[14:17]
	v_mfma_f32_16x16x32_bf16 v[14:17], v[234:237], v[46:49], v[70:73]
	v_mfma_f32_16x16x32_bf16 v[82:85], v[238:241], v[54:57], v[14:17]
	v_mfma_f32_16x16x32_bf16 v[14:17], v[226:229], v[58:61], v[50:53]
	v_mfma_f32_16x16x32_bf16 v[50:53], v[230:233], v[62:65], v[14:17]
	v_mfma_f32_16x16x32_bf16 v[14:17], v[234:237], v[58:61], v[34:37]
	v_mfma_f32_16x16x32_bf16 v[6:9], v[226:229], v[66:69], v[6:9]
	v_mfma_f32_16x16x32_bf16 v[2:5], v[234:237], v[66:69], v[2:5]
	v_mfma_f32_16x16x32_bf16 v[34:37], v[238:241], v[62:65], v[14:17]
	v_mfma_f32_16x16x32_bf16 v[6:9], v[230:233], v[178:181], v[6:9]
	v_mfma_f32_16x16x32_bf16 v[2:5], v[238:241], v[178:181], v[2:5]
	s_add_i32 s57, s57, 2
	s_add_u32 s55, s55, 0x100
	s_addc_u32 s56, s56, 0
	s_cmp_gt_u32 s57, 13
	s_mov_b64 s[4:5], s[36:37]
	s_barrier
	s_cbranch_scc0 .LBB0_396
	s_setprio 0
	s_lshr_b32 s32, s27, 2
	s_cmp_eq_u32 s32, 0
	s_cbranch_scc1 .Lepi0_seg0
	s_cmp_eq_u32 s32, 1
	s_cbranch_scc1 .Lepi0_seg1
	s_cmp_eq_u32 s32, 2
	s_cbranch_scc1 .Lepi0_seg2
	s_branch .Lepi0_seg3

.LBB0_1098:
	s_cmp_ge_u32 s69, 0x1000
	s_cbranch_scc0 .Lprio_done_2
	s_setprio 1
.Lprio_done_2:
	s_add_i32 s76, s76, 1
	s_mov_b64 s[62:63], s[54:55]
	s_mul_i32 s54, s76, s26
	s_add_i32 s64, s54, s2
	s_cmpk_gt_i32 s64, 0x57f
	s_cselect_b64 s[60:61], -1, 0
	s_lshl_b32 s54, s64, 3
	s_and_b32 s54, s54, 56
	s_bfe_u32 s55, s64, 0x30003
	s_or_b32 s77, s54, s55
	s_ashr_i32 s58, s64, 6
	s_lshl_b32 s54, s77, 19
	s_mov_b64 s[36:37], s[56:57]
	s_add_u32 s56, s52, s54
	s_addc_u32 s57, s53, 0
	s_ashr_i32 s59, s58, 31
	s_lshl_b64 s[54:55], s[58:59], 19
	s_add_u32 s54, s4, s54
	s_addc_u32 s55, s5, s55
	s_cmpk_lt_i32 s64, 0x580
	s_cselect_b32 s59, s57, s37
	s_cselect_b32 s78, s56, s36
	s_cselect_b32 s79, s55, s63
	s_cselect_b32 s80, s54, s62
	s_add_u32 s81, s62, 0x100
	s_addc_u32 s82, s63, 0
	s_mov_b32 s83, -2
	s_add_u32 s62, s36, 0x100
	s_addc_u32 s63, s37, 0
	s_add_i32 s84, 0, 0x10000
	v_add_u32_e32 v70, s84, v170
	ds_read_b128 v[58:61], v70
	ds_read_b128 v[62:65], v70 offset:1024
	ds_read_b128 v[66:69], v70 offset:2048
	ds_read_b128 v[70:73], v70 offset:3072
	s_cmp_eq_u32 s83, 12
	s_cselect_b32 s67, s59, s63
	s_cselect_b32 s66, s78, s62
	s_cselect_b32 s65, s79, s82
	s_cselect_b32 s64, s80, s81
	v_lshl_add_u64 v[192:193], s[36:37], 0, v[168:169]
	s_add_i32 m0, s69, 0xc000
	ds_read_b128 v[78:81], v175
	ds_read_b128 v[86:89], v175 offset:1024
	ds_read_b128 v[90:93], v175 offset:2048
	ds_read_b128 v[94:97], v175 offset:3072
	ds_read_b128 v[176:179], v175 offset:4096
	ds_read_b128 v[180:183], v175 offset:5120
	ds_read_b128 v[184:187], v175 offset:6144
	ds_read_b128 v[188:191], v175 offset:7168
	global_load_lds_dwordx4 v[192:193], off
	v_lshl_add_u64 v[192:193], s[36:37], 0, v[166:167]
	s_add_i32 m0, s69, 0xe000
	s_nop 0
	global_load_lds_dwordx4 v[192:193], off
	s_waitcnt lgkmcnt(8)
	s_barrier
	s_waitcnt lgkmcnt(0)
	s_waitcnt lgkmcnt(0)
	v_mfma_f32_16x16x32_bf16 v[158:161], v[58:61], v[78:81], 0
	v_mfma_f32_16x16x32_bf16 v[150:153], v[66:69], v[78:81], 0
	v_mfma_f32_16x16x32_bf16 v[142:145], v[58:61], v[90:93], 0
	v_mfma_f32_16x16x32_bf16 v[134:137], v[66:69], v[90:93], 0
	v_mfma_f32_16x16x32_bf16 v[126:129], v[58:61], v[176:179], 0
	v_mfma_f32_16x16x32_bf16 v[118:121], v[66:69], v[176:179], 0
	v_mfma_f32_16x16x32_bf16 v[110:113], v[58:61], v[184:187], 0
	v_mfma_f32_16x16x32_bf16 v[102:105], v[66:69], v[184:187], 0
	v_mfma_f32_16x16x32_bf16 v[158:161], v[62:65], v[86:89], v[158:161]
	v_mfma_f32_16x16x32_bf16 v[150:153], v[70:73], v[86:89], v[150:153]
	v_mfma_f32_16x16x32_bf16 v[142:145], v[62:65], v[94:97], v[142:145]
	v_mfma_f32_16x16x32_bf16 v[134:137], v[70:73], v[94:97], v[134:137]
	v_mfma_f32_16x16x32_bf16 v[126:129], v[62:65], v[180:183], v[126:129]
	v_mfma_f32_16x16x32_bf16 v[118:121], v[70:73], v[180:183], v[118:121]
	v_mfma_f32_16x16x32_bf16 v[110:113], v[62:65], v[188:191], v[110:113]
	v_mfma_f32_16x16x32_bf16 v[102:105], v[70:73], v[188:191], v[102:105]
	s_barrier
	v_mbcnt_lo_u32_b32 v250, -1, 0
	v_mbcnt_hi_u32_b32 v250, -1, v250
	v_lshlrev_b32_e32 v250, 4, v250
	s_lshl_b32 s32, s27, 10
	s_add_u32 s90, s46, s32
	s_addc_u32 s91, s47, 0
	s_add_u32 s92, s48, s32
	s_addc_u32 s93, s49, 0
	s_mov_b32 m0, 0x20840
	s_nop 0
	global_load_lds_dwordx4 v250, s[90:91]
	s_mov_b32 m0, 0x20c40
	s_nop 0
	global_load_lds_dwordx4 v250, s[92:93]
	s_add_i32 s85, 0, 0x14000
	v_add_u32_e32 v192, s85, v170
	s_add_i32 s36, s84, s68
	ds_read_b128 v[200:203], v192
	ds_read_b128 v[204:207], v192 offset:1024
	ds_read_b128 v[208:211], v192 offset:2048
	ds_read_b128 v[222:225], v192 offset:3072
	v_lshl_add_u64 v[192:193], s[64:65], 0, v[164:165]
	s_mov_b32 m0, s36
	v_lshl_add_u64 v[214:215], s[64:65], 0, v[162:163]
	global_load_lds_dwordx4 v[192:193], off
	s_add_i32 m0, s36, 0x2000
	s_nop 0
	global_load_lds_dwordx4 v[214:215], off
	s_barrier
	s_waitcnt lgkmcnt(0)
	s_waitcnt lgkmcnt(0)
	v_mfma_f32_16x16x32_bf16 v[154:157], v[200:203], v[78:81], 0
	v_mfma_f32_16x16x32_bf16 v[78:81], v[208:211], v[78:81], 0
	v_mfma_f32_16x16x32_bf16 v[154:157], v[204:207], v[86:89], v[154:157]
	v_mfma_f32_16x16x32_bf16 v[78:81], v[222:225], v[86:89], v[78:81]
	v_mfma_f32_16x16x32_bf16 v[86:89], v[200:203], v[90:93], 0
	v_mfma_f32_16x16x32_bf16 v[90:93], v[208:211], v[90:93], 0
	v_mfma_f32_16x16x32_bf16 v[114:117], v[208:211], v[176:179], 0
	v_mfma_f32_16x16x32_bf16 v[106:109], v[200:203], v[184:187], 0
	v_mfma_f32_16x16x32_bf16 v[98:101], v[208:211], v[184:187], 0
	v_mfma_f32_16x16x32_bf16 v[86:89], v[204:207], v[94:97], v[86:89]
	v_mfma_f32_16x16x32_bf16 v[90:93], v[222:225], v[94:97], v[90:93]
	v_mfma_f32_16x16x32_bf16 v[94:97], v[200:203], v[176:179], 0
	v_mfma_f32_16x16x32_bf16 v[114:117], v[222:225], v[180:183], v[114:117]
	v_mfma_f32_16x16x32_bf16 v[106:109], v[204:207], v[188:191], v[106:109]
	v_mfma_f32_16x16x32_bf16 v[98:101], v[222:225], v[188:191], v[98:101]
	v_mfma_f32_16x16x32_bf16 v[94:97], v[204:207], v[180:183], v[94:97]
	s_mov_b32 m0, s69
	v_lshl_add_u64 v[234:235], s[66:67], 0, v[164:165]
	s_barrier
	ds_read_b128 v[122:125], v175 offset:16384
	ds_read_b128 v[130:133], v175 offset:17408
	ds_read_b128 v[138:141], v175 offset:18432
	ds_read_b128 v[146:149], v175 offset:19456
	ds_read_b128 v[176:179], v175 offset:20480
	ds_read_b128 v[180:183], v175 offset:21504
	ds_read_b128 v[184:187], v175 offset:22528
	ds_read_b128 v[188:191], v175 offset:23552
	global_load_lds_dwordx4 v[234:235], off
	v_lshl_add_u64 v[236:237], s[66:67], 0, v[162:163]
	s_mov_b32 m0, s70
	s_nop 0
	global_load_lds_dwordx4 v[236:237], off
	s_barrier
	s_waitcnt lgkmcnt(0)
	s_waitcnt lgkmcnt(0)
	v_mfma_f32_16x16x32_bf16 v[82:85], v[58:61], v[122:125], 0
	v_mfma_f32_16x16x32_bf16 v[54:57], v[66:69], v[122:125], 0
	v_mfma_f32_16x16x32_bf16 v[46:49], v[58:61], v[138:141], 0
	v_mfma_f32_16x16x32_bf16 v[38:41], v[66:69], v[138:141], 0
	v_mfma_f32_16x16x32_bf16 v[30:33], v[58:61], v[176:179], 0
	v_mfma_f32_16x16x32_bf16 v[22:25], v[66:69], v[176:179], 0
	v_mfma_f32_16x16x32_bf16 v[14:17], v[58:61], v[184:187], 0
	v_mfma_f32_16x16x32_bf16 v[6:9], v[66:69], v[184:187], 0
	v_mfma_f32_16x16x32_bf16 v[82:85], v[62:65], v[130:133], v[82:85]
	v_mfma_f32_16x16x32_bf16 v[54:57], v[70:73], v[130:133], v[54:57]
	v_mfma_f32_16x16x32_bf16 v[46:49], v[62:65], v[146:149], v[46:49]
	v_mfma_f32_16x16x32_bf16 v[38:41], v[70:73], v[146:149], v[38:41]
	v_mfma_f32_16x16x32_bf16 v[30:33], v[62:65], v[180:183], v[30:33]
	v_mfma_f32_16x16x32_bf16 v[22:25], v[70:73], v[180:183], v[22:25]
	v_mfma_f32_16x16x32_bf16 v[14:17], v[62:65], v[188:191], v[14:17]
	v_mfma_f32_16x16x32_bf16 v[6:9], v[70:73], v[188:191], v[6:9]
	s_barrier
	s_add_u32 s36, s64, 0x40000
	s_addc_u32 s37, s65, 0
	s_add_i32 s84, s85, s68
	v_lshl_add_u64 v[58:59], s[36:37], 0, v[164:165]
	s_mov_b32 m0, s84
	s_nop 0
	global_load_lds_dwordx4 v[58:59], off
	v_lshl_add_u64 v[58:59], s[36:37], 0, v[162:163]
	s_add_i32 m0, s84, 0x2000
	s_nop 0
	global_load_lds_dwordx4 v[58:59], off
	s_waitcnt vmcnt(6)
	s_barrier
	v_mfma_f32_16x16x32_bf16 v[50:53], v[208:211], v[122:125], 0
	v_mfma_f32_16x16x32_bf16 v[42:45], v[200:203], v[138:141], 0
	v_mfma_f32_16x16x32_bf16 v[34:37], v[208:211], v[138:141], 0
	v_mfma_f32_16x16x32_bf16 v[26:29], v[200:203], v[176:179], 0
	v_mfma_f32_16x16x32_bf16 v[18:21], v[208:211], v[176:179], 0
	v_mfma_f32_16x16x32_bf16 v[10:13], v[200:203], v[184:187], 0
	v_mfma_f32_16x16x32_bf16 v[2:5], v[208:211], v[184:187], 0
	v_mfma_f32_16x16x32_bf16 v[58:61], v[200:203], v[122:125], 0
	v_mfma_f32_16x16x32_bf16 v[50:53], v[222:225], v[130:133], v[50:53]
	v_mfma_f32_16x16x32_bf16 v[42:45], v[204:207], v[146:149], v[42:45]
	v_mfma_f32_16x16x32_bf16 v[34:37], v[222:225], v[146:149], v[34:37]
	v_mfma_f32_16x16x32_bf16 v[26:29], v[204:207], v[180:183], v[26:29]
	v_mfma_f32_16x16x32_bf16 v[18:21], v[222:225], v[180:183], v[18:21]
	v_mfma_f32_16x16x32_bf16 v[10:13], v[204:207], v[188:191], v[10:13]
	v_mfma_f32_16x16x32_bf16 v[2:5], v[222:225], v[188:191], v[2:5]
	v_mfma_f32_16x16x32_bf16 v[58:61], v[204:207], v[130:133], v[58:61]
	s_add_i32 s84, 0, 0x18000
	v_add_u32_e32 v74, s84, v170
	s_barrier
	ds_read_b128 v[62:65], v74
	ds_read_b128 v[66:69], v74 offset:1024
	ds_read_b128 v[70:73], v74 offset:2048
	ds_read_b128 v[74:77], v74 offset:3072
	s_add_u32 s36, s66, 0x40000
	s_addc_u32 s37, s67, 0
	s_mov_b32 m0, s71
	v_lshl_add_u64 v[138:139], s[36:37], 0, v[164:165]
	ds_read_b128 v[122:125], v175 offset:32768
	ds_read_b128 v[130:133], v175 offset:33792
	ds_read_b128 v[176:179], v175 offset:34816
	ds_read_b128 v[180:183], v175 offset:35840
	ds_read_b128 v[184:187], v175 offset:36864
	ds_read_b128 v[188:191], v175 offset:37888
	ds_read_b128 v[200:203], v175 offset:38912
	ds_read_b128 v[204:207], v175 offset:39936
	global_load_lds_dwordx4 v[138:139], off
	v_lshl_add_u64 v[138:139], s[36:37], 0, v[162:163]
	s_mov_b32 m0, s72
	s_nop 0
	global_load_lds_dwordx4 v[138:139], off
	s_waitcnt lgkmcnt(8)
	s_barrier
	s_waitcnt lgkmcnt(0)
	s_waitcnt lgkmcnt(0)
	v_mfma_f32_16x16x32_bf16 v[138:141], v[62:65], v[122:125], v[158:161]
	v_mfma_f32_16x16x32_bf16 v[158:161], v[66:69], v[130:133], v[138:141]
	v_mfma_f32_16x16x32_bf16 v[138:141], v[70:73], v[122:125], v[150:153]
	v_mfma_f32_16x16x32_bf16 v[150:153], v[74:77], v[130:133], v[138:141]
	v_mfma_f32_16x16x32_bf16 v[138:141], v[62:65], v[176:179], v[142:145]
	v_mfma_f32_16x16x32_bf16 v[134:137], v[70:73], v[176:179], v[134:137]
	v_mfma_f32_16x16x32_bf16 v[126:129], v[62:65], v[184:187], v[126:129]
	v_mfma_f32_16x16x32_bf16 v[118:121], v[70:73], v[184:187], v[118:121]
	v_mfma_f32_16x16x32_bf16 v[110:113], v[62:65], v[200:203], v[110:113]
	v_mfma_f32_16x16x32_bf16 v[102:105], v[70:73], v[200:203], v[102:105]
	v_mfma_f32_16x16x32_bf16 v[142:145], v[66:69], v[180:183], v[138:141]
	v_mfma_f32_16x16x32_bf16 v[134:137], v[74:77], v[180:183], v[134:137]
	v_mfma_f32_16x16x32_bf16 v[126:129], v[66:69], v[188:191], v[126:129]
	v_mfma_f32_16x16x32_bf16 v[118:121], v[74:77], v[188:191], v[118:121]
	v_mfma_f32_16x16x32_bf16 v[110:113], v[66:69], v[204:207], v[110:113]
	v_mfma_f32_16x16x32_bf16 v[102:105], v[74:77], v[204:207], v[102:105]
	s_barrier
	s_add_i32 s66, 0, 0x1c000
	v_add_u32_e32 v138, s66, v170
	s_add_i32 s36, s84, s68
	ds_read_b128 v[208:211], v138
	ds_read_b128 v[222:225], v138 offset:1024
	ds_read_b128 v[226:229], v138 offset:2048
	ds_read_b128 v[230:233], v138 offset:3072
	v_lshl_add_u64 v[138:139], v[192:193], 0, s[22:23]
	s_mov_b32 m0, s36
	s_nop 0
	global_load_lds_dwordx4 v[138:139], off
	v_lshl_add_u64 v[138:139], v[214:215], 0, s[22:23]
	s_add_i32 m0, s36, 0x2000
	s_nop 0
	global_load_lds_dwordx4 v[138:139], off
	s_barrier
	s_waitcnt lgkmcnt(0)
	s_waitcnt lgkmcnt(0)
	v_mfma_f32_16x16x32_bf16 v[78:81], v[226:229], v[122:125], v[78:81]
	v_mfma_f32_16x16x32_bf16 v[138:141], v[208:211], v[122:125], v[154:157]
	v_mfma_f32_16x16x32_bf16 v[146:149], v[230:233], v[130:133], v[78:81]
	v_mfma_f32_16x16x32_bf16 v[78:81], v[208:211], v[176:179], v[86:89]
	v_mfma_f32_16x16x32_bf16 v[154:157], v[222:225], v[130:133], v[138:141]
	v_mfma_f32_16x16x32_bf16 v[138:141], v[222:225], v[180:183], v[78:81]
	v_mfma_f32_16x16x32_bf16 v[78:81], v[226:229], v[176:179], v[90:93]
	v_mfma_f32_16x16x32_bf16 v[130:133], v[230:233], v[180:183], v[78:81]
	v_mfma_f32_16x16x32_bf16 v[78:81], v[208:211], v[184:187], v[94:97]
	v_mfma_f32_16x16x32_bf16 v[122:125], v[222:225], v[188:191], v[78:81]
	v_mfma_f32_16x16x32_bf16 v[78:81], v[226:229], v[184:187], v[114:117]
	v_mfma_f32_16x16x32_bf16 v[114:117], v[230:233], v[188:191], v[78:81]
	v_mfma_f32_16x16x32_bf16 v[78:81], v[208:211], v[200:203], v[106:109]
	v_mfma_f32_16x16x32_bf16 v[106:109], v[222:225], v[204:207], v[78:81]
	v_mfma_f32_16x16x32_bf16 v[78:81], v[226:229], v[200:203], v[98:101]
	v_mfma_f32_16x16x32_bf16 v[98:101], v[230:233], v[204:207], v[78:81]
	s_mov_b32 m0, s73
	v_lshl_add_u64 v[192:193], v[234:235], 0, s[22:23]
	s_barrier
	s_nop 2
	ds_read_b128 v[78:81], v175 offset:49152
	ds_read_b128 v[86:89], v175 offset:50176
	ds_read_b128 v[90:93], v175 offset:51200
	ds_read_b128 v[94:97], v175 offset:52224
	ds_read_b128 v[176:179], v175 offset:53248
	ds_read_b128 v[180:183], v175 offset:54272
	ds_read_b128 v[184:187], v175 offset:55296
	ds_read_b128 v[188:191], v175 offset:56320
	global_load_lds_dwordx4 v[192:193], off
	v_lshl_add_u64 v[192:193], v[236:237], 0, s[22:23]
	s_mov_b32 m0, s75
	s_nop 0
	global_load_lds_dwordx4 v[192:193], off
	s_barrier
	s_waitcnt lgkmcnt(0)
	s_waitcnt lgkmcnt(0)
	v_mfma_f32_16x16x32_bf16 v[82:85], v[62:65], v[78:81], v[82:85]
	v_mfma_f32_16x16x32_bf16 v[54:57], v[70:73], v[78:81], v[54:57]
	v_mfma_f32_16x16x32_bf16 v[46:49], v[62:65], v[90:93], v[46:49]
	v_mfma_f32_16x16x32_bf16 v[38:41], v[70:73], v[90:93], v[38:41]
	v_mfma_f32_16x16x32_bf16 v[30:33], v[62:65], v[176:179], v[30:33]
	v_mfma_f32_16x16x32_bf16 v[22:25], v[70:73], v[176:179], v[22:25]
	v_mfma_f32_16x16x32_bf16 v[14:17], v[62:65], v[184:187], v[14:17]
	v_mfma_f32_16x16x32_bf16 v[6:9], v[70:73], v[184:187], v[6:9]
	v_mfma_f32_16x16x32_bf16 v[82:85], v[66:69], v[86:89], v[82:85]
	v_mfma_f32_16x16x32_bf16 v[54:57], v[74:77], v[86:89], v[54:57]
	v_mfma_f32_16x16x32_bf16 v[46:49], v[66:69], v[94:97], v[46:49]
	v_mfma_f32_16x16x32_bf16 v[38:41], v[74:77], v[94:97], v[38:41]
	v_mfma_f32_16x16x32_bf16 v[30:33], v[66:69], v[180:183], v[30:33]
	v_mfma_f32_16x16x32_bf16 v[22:25], v[74:77], v[180:183], v[22:25]
	v_mfma_f32_16x16x32_bf16 v[14:17], v[66:69], v[188:191], v[14:17]
	v_mfma_f32_16x16x32_bf16 v[6:9], v[74:77], v[188:191], v[6:9]
	s_barrier
	s_add_u32 s36, s64, 0x40080
	s_addc_u32 s37, s65, 0
	s_add_i32 s64, s66, s68
	v_lshl_add_u64 v[62:63], s[36:37], 0, v[164:165]
	s_mov_b32 m0, s64
	s_nop 0
	global_load_lds_dwordx4 v[62:63], off
	v_lshl_add_u64 v[62:63], s[36:37], 0, v[162:163]
	s_add_i32 m0, s64, 0x2000
	s_nop 0
	global_load_lds_dwordx4 v[62:63], off
	s_waitcnt vmcnt(6)
	s_barrier
	v_mfma_f32_16x16x32_bf16 v[58:61], v[208:211], v[78:81], v[58:61]
	v_mfma_f32_16x16x32_bf16 v[50:53], v[226:229], v[78:81], v[50:53]
	v_mfma_f32_16x16x32_bf16 v[42:45], v[208:211], v[90:93], v[42:45]
	v_mfma_f32_16x16x32_bf16 v[34:37], v[226:229], v[90:93], v[34:37]
	v_mfma_f32_16x16x32_bf16 v[26:29], v[208:211], v[176:179], v[26:29]
	v_mfma_f32_16x16x32_bf16 v[18:21], v[226:229], v[176:179], v[18:21]
	v_mfma_f32_16x16x32_bf16 v[10:13], v[208:211], v[184:187], v[10:13]
	v_mfma_f32_16x16x32_bf16 v[2:5], v[226:229], v[184:187], v[2:5]
	v_mfma_f32_16x16x32_bf16 v[74:77], v[222:225], v[86:89], v[58:61]
	v_mfma_f32_16x16x32_bf16 v[50:53], v[230:233], v[86:89], v[50:53]
	v_mfma_f32_16x16x32_bf16 v[42:45], v[222:225], v[94:97], v[42:45]
	v_mfma_f32_16x16x32_bf16 v[34:37], v[230:233], v[94:97], v[34:37]
	v_mfma_f32_16x16x32_bf16 v[26:29], v[222:225], v[180:183], v[26:29]
	v_mfma_f32_16x16x32_bf16 v[18:21], v[230:233], v[180:183], v[18:21]
	v_mfma_f32_16x16x32_bf16 v[10:13], v[222:225], v[188:191], v[10:13]
	v_mfma_f32_16x16x32_bf16 v[2:5], v[230:233], v[188:191], v[2:5]
	s_add_i32 s83, s83, 2
	s_add_u32 s81, s81, 0x100
	s_addc_u32 s82, s82, 0
	s_cmp_gt_u32 s83, 13
	s_mov_b64 s[36:37], s[62:63]
	s_barrier
.LBB0_1099:
	s_add_u32 s62, s36, 0x100
	s_addc_u32 s63, s37, 0
	s_add_i32 s84, 0, 0x10000
	v_add_u32_e32 v70, s84, v170
	ds_read_b128 v[58:61], v70
	ds_read_b128 v[62:65], v70 offset:1024
	ds_read_b128 v[66:69], v70 offset:2048
	ds_read_b128 v[70:73], v70 offset:3072
	s_cmp_eq_u32 s83, 12
	s_cselect_b32 s67, s59, s63
	s_cselect_b32 s66, s78, s62
	s_cselect_b32 s65, s79, s82
	s_cselect_b32 s64, s80, s81
	v_lshl_add_u64 v[192:193], s[36:37], 0, v[168:169]
	s_add_i32 m0, s69, 0xc000
	ds_read_b128 v[78:81], v175
	ds_read_b128 v[86:89], v175 offset:1024
	ds_read_b128 v[90:93], v175 offset:2048
	ds_read_b128 v[94:97], v175 offset:3072
	ds_read_b128 v[176:179], v175 offset:4096
	ds_read_b128 v[180:183], v175 offset:5120
	ds_read_b128 v[184:187], v175 offset:6144
	ds_read_b128 v[188:191], v175 offset:7168
	global_load_lds_dwordx4 v[192:193], off
	v_lshl_add_u64 v[192:193], s[36:37], 0, v[166:167]
	s_add_i32 m0, s69, 0xe000
	s_nop 0
	global_load_lds_dwordx4 v[192:193], off
	s_waitcnt lgkmcnt(8)
	s_barrier
	s_waitcnt lgkmcnt(0)
	s_waitcnt lgkmcnt(0)
	v_mfma_f32_16x16x32_bf16 v[158:161], v[58:61], v[78:81], v[158:161]
	v_mfma_f32_16x16x32_bf16 v[150:153], v[66:69], v[78:81], v[150:153]
	v_mfma_f32_16x16x32_bf16 v[142:145], v[58:61], v[90:93], v[142:145]
	v_mfma_f32_16x16x32_bf16 v[134:137], v[66:69], v[90:93], v[134:137]
	v_mfma_f32_16x16x32_bf16 v[126:129], v[58:61], v[176:179], v[126:129]
	v_mfma_f32_16x16x32_bf16 v[118:121], v[66:69], v[176:179], v[118:121]
	v_mfma_f32_16x16x32_bf16 v[110:113], v[58:61], v[184:187], v[110:113]
	v_mfma_f32_16x16x32_bf16 v[102:105], v[66:69], v[184:187], v[102:105]
	v_mfma_f32_16x16x32_bf16 v[158:161], v[62:65], v[86:89], v[158:161]
	v_mfma_f32_16x16x32_bf16 v[150:153], v[70:73], v[86:89], v[150:153]
	v_mfma_f32_16x16x32_bf16 v[142:145], v[62:65], v[94:97], v[142:145]
	v_mfma_f32_16x16x32_bf16 v[134:137], v[70:73], v[94:97], v[134:137]
	v_mfma_f32_16x16x32_bf16 v[126:129], v[62:65], v[180:183], v[126:129]
	v_mfma_f32_16x16x32_bf16 v[118:121], v[70:73], v[180:183], v[118:121]
	v_mfma_f32_16x16x32_bf16 v[110:113], v[62:65], v[188:191], v[110:113]
	v_mfma_f32_16x16x32_bf16 v[102:105], v[70:73], v[188:191], v[102:105]
	s_barrier
	s_add_i32 s85, 0, 0x14000
	v_add_u32_e32 v192, s85, v170
	s_add_i32 s36, s84, s68
	ds_read_b128 v[200:203], v192
	ds_read_b128 v[204:207], v192 offset:1024
	ds_read_b128 v[208:211], v192 offset:2048
	ds_read_b128 v[222:225], v192 offset:3072
	v_lshl_add_u64 v[192:193], s[64:65], 0, v[164:165]
	s_mov_b32 m0, s36
	v_lshl_add_u64 v[214:215], s[64:65], 0, v[162:163]
	global_load_lds_dwordx4 v[192:193], off
	s_add_i32 m0, s36, 0x2000
	s_nop 0
	global_load_lds_dwordx4 v[214:215], off
	s_barrier
	s_waitcnt lgkmcnt(0)
	s_waitcnt lgkmcnt(0)
	v_mfma_f32_16x16x32_bf16 v[154:157], v[200:203], v[78:81], v[154:157]
	v_mfma_f32_16x16x32_bf16 v[78:81], v[208:211], v[78:81], v[146:149]
	v_mfma_f32_16x16x32_bf16 v[154:157], v[204:207], v[86:89], v[154:157]
	v_mfma_f32_16x16x32_bf16 v[78:81], v[222:225], v[86:89], v[78:81]
	v_mfma_f32_16x16x32_bf16 v[86:89], v[200:203], v[90:93], v[138:141]
	v_mfma_f32_16x16x32_bf16 v[90:93], v[208:211], v[90:93], v[130:133]
	v_mfma_f32_16x16x32_bf16 v[114:117], v[208:211], v[176:179], v[114:117]
	v_mfma_f32_16x16x32_bf16 v[106:109], v[200:203], v[184:187], v[106:109]
	v_mfma_f32_16x16x32_bf16 v[98:101], v[208:211], v[184:187], v[98:101]
	v_mfma_f32_16x16x32_bf16 v[86:89], v[204:207], v[94:97], v[86:89]
	v_mfma_f32_16x16x32_bf16 v[90:93], v[222:225], v[94:97], v[90:93]
	v_mfma_f32_16x16x32_bf16 v[94:97], v[200:203], v[176:179], v[122:125]
	v_mfma_f32_16x16x32_bf16 v[114:117], v[222:225], v[180:183], v[114:117]
	v_mfma_f32_16x16x32_bf16 v[106:109], v[204:207], v[188:191], v[106:109]
	v_mfma_f32_16x16x32_bf16 v[98:101], v[222:225], v[188:191], v[98:101]
	v_mfma_f32_16x16x32_bf16 v[94:97], v[204:207], v[180:183], v[94:97]
	s_mov_b32 m0, s69
	v_lshl_add_u64 v[234:235], s[66:67], 0, v[164:165]
	s_barrier
	ds_read_b128 v[122:125], v175 offset:16384
	ds_read_b128 v[130:133], v175 offset:17408
	ds_read_b128 v[138:141], v175 offset:18432
	ds_read_b128 v[146:149], v175 offset:19456
	ds_read_b128 v[176:179], v175 offset:20480
	ds_read_b128 v[180:183], v175 offset:21504
	ds_read_b128 v[184:187], v175 offset:22528
	ds_read_b128 v[188:191], v175 offset:23552
	global_load_lds_dwordx4 v[234:235], off
	v_lshl_add_u64 v[236:237], s[66:67], 0, v[162:163]
	s_mov_b32 m0, s70
	s_nop 0
	global_load_lds_dwordx4 v[236:237], off
	s_barrier
	s_waitcnt lgkmcnt(0)
	s_waitcnt lgkmcnt(0)
	v_mfma_f32_16x16x32_bf16 v[82:85], v[58:61], v[122:125], v[82:85]
	v_mfma_f32_16x16x32_bf16 v[54:57], v[66:69], v[122:125], v[54:57]
	v_mfma_f32_16x16x32_bf16 v[46:49], v[58:61], v[138:141], v[46:49]
	v_mfma_f32_16x16x32_bf16 v[38:41], v[66:69], v[138:141], v[38:41]
	v_mfma_f32_16x16x32_bf16 v[30:33], v[58:61], v[176:179], v[30:33]
	v_mfma_f32_16x16x32_bf16 v[22:25], v[66:69], v[176:179], v[22:25]
	v_mfma_f32_16x16x32_bf16 v[14:17], v[58:61], v[184:187], v[14:17]
	v_mfma_f32_16x16x32_bf16 v[6:9], v[66:69], v[184:187], v[6:9]
	v_mfma_f32_16x16x32_bf16 v[82:85], v[62:65], v[130:133], v[82:85]
	v_mfma_f32_16x16x32_bf16 v[54:57], v[70:73], v[130:133], v[54:57]
	v_mfma_f32_16x16x32_bf16 v[46:49], v[62:65], v[146:149], v[46:49]
	v_mfma_f32_16x16x32_bf16 v[38:41], v[70:73], v[146:149], v[38:41]
	v_mfma_f32_16x16x32_bf16 v[30:33], v[62:65], v[180:183], v[30:33]
	v_mfma_f32_16x16x32_bf16 v[22:25], v[70:73], v[180:183], v[22:25]
	v_mfma_f32_16x16x32_bf16 v[14:17], v[62:65], v[188:191], v[14:17]
	v_mfma_f32_16x16x32_bf16 v[6:9], v[70:73], v[188:191], v[6:9]
	s_barrier
	s_add_u32 s36, s64, 0x40000
	s_addc_u32 s37, s65, 0
	s_add_i32 s84, s85, s68
	v_lshl_add_u64 v[58:59], s[36:37], 0, v[164:165]
	s_mov_b32 m0, s84
	s_nop 0
	global_load_lds_dwordx4 v[58:59], off
	v_lshl_add_u64 v[58:59], s[36:37], 0, v[162:163]
	s_add_i32 m0, s84, 0x2000
	s_nop 0
	global_load_lds_dwordx4 v[58:59], off
	s_waitcnt vmcnt(6)
	s_barrier
	v_mfma_f32_16x16x32_bf16 v[50:53], v[208:211], v[122:125], v[50:53]
	v_mfma_f32_16x16x32_bf16 v[42:45], v[200:203], v[138:141], v[42:45]
	v_mfma_f32_16x16x32_bf16 v[34:37], v[208:211], v[138:141], v[34:37]
	v_mfma_f32_16x16x32_bf16 v[26:29], v[200:203], v[176:179], v[26:29]
	v_mfma_f32_16x16x32_bf16 v[18:21], v[208:211], v[176:179], v[18:21]
	v_mfma_f32_16x16x32_bf16 v[10:13], v[200:203], v[184:187], v[10:13]
	v_mfma_f32_16x16x32_bf16 v[2:5], v[208:211], v[184:187], v[2:5]
	v_mfma_f32_16x16x32_bf16 v[58:61], v[200:203], v[122:125], v[74:77]
	v_mfma_f32_16x16x32_bf16 v[50:53], v[222:225], v[130:133], v[50:53]
	v_mfma_f32_16x16x32_bf16 v[42:45], v[204:207], v[146:149], v[42:45]
	v_mfma_f32_16x16x32_bf16 v[34:37], v[222:225], v[146:149], v[34:37]
	v_mfma_f32_16x16x32_bf16 v[26:29], v[204:207], v[180:183], v[26:29]
	v_mfma_f32_16x16x32_bf16 v[18:21], v[222:225], v[180:183], v[18:21]
	v_mfma_f32_16x16x32_bf16 v[10:13], v[204:207], v[188:191], v[10:13]
	v_mfma_f32_16x16x32_bf16 v[2:5], v[222:225], v[188:191], v[2:5]
	v_mfma_f32_16x16x32_bf16 v[58:61], v[204:207], v[130:133], v[58:61]
	s_add_i32 s84, 0, 0x18000
	v_add_u32_e32 v74, s84, v170
	s_barrier
	ds_read_b128 v[62:65], v74
	ds_read_b128 v[66:69], v74 offset:1024
	ds_read_b128 v[70:73], v74 offset:2048
	ds_read_b128 v[74:77], v74 offset:3072
	s_add_u32 s36, s66, 0x40000
	s_addc_u32 s37, s67, 0
	s_mov_b32 m0, s71
	v_lshl_add_u64 v[138:139], s[36:37], 0, v[164:165]
	ds_read_b128 v[122:125], v175 offset:32768
	ds_read_b128 v[130:133], v175 offset:33792
	ds_read_b128 v[176:179], v175 offset:34816
	ds_read_b128 v[180:183], v175 offset:35840
	ds_read_b128 v[184:187], v175 offset:36864
	ds_read_b128 v[188:191], v175 offset:37888
	ds_read_b128 v[200:203], v175 offset:38912
	ds_read_b128 v[204:207], v175 offset:39936
	global_load_lds_dwordx4 v[138:139], off
	v_lshl_add_u64 v[138:139], s[36:37], 0, v[162:163]
	s_mov_b32 m0, s72
	s_nop 0
	global_load_lds_dwordx4 v[138:139], off
	s_waitcnt lgkmcnt(8)
	s_barrier
	s_waitcnt lgkmcnt(0)
	s_waitcnt lgkmcnt(0)
	v_mfma_f32_16x16x32_bf16 v[138:141], v[62:65], v[122:125], v[158:161]
	v_mfma_f32_16x16x32_bf16 v[158:161], v[66:69], v[130:133], v[138:141]
	v_mfma_f32_16x16x32_bf16 v[138:141], v[70:73], v[122:125], v[150:153]
	v_mfma_f32_16x16x32_bf16 v[150:153], v[74:77], v[130:133], v[138:141]
	v_mfma_f32_16x16x32_bf16 v[138:141], v[62:65], v[176:179], v[142:145]
	v_mfma_f32_16x16x32_bf16 v[134:137], v[70:73], v[176:179], v[134:137]
	v_mfma_f32_16x16x32_bf16 v[126:129], v[62:65], v[184:187], v[126:129]
	v_mfma_f32_16x16x32_bf16 v[118:121], v[70:73], v[184:187], v[118:121]
	v_mfma_f32_16x16x32_bf16 v[110:113], v[62:65], v[200:203], v[110:113]
	v_mfma_f32_16x16x32_bf16 v[102:105], v[70:73], v[200:203], v[102:105]
	v_mfma_f32_16x16x32_bf16 v[142:145], v[66:69], v[180:183], v[138:141]
	v_mfma_f32_16x16x32_bf16 v[134:137], v[74:77], v[180:183], v[134:137]
	v_mfma_f32_16x16x32_bf16 v[126:129], v[66:69], v[188:191], v[126:129]
	v_mfma_f32_16x16x32_bf16 v[118:121], v[74:77], v[188:191], v[118:121]
	v_mfma_f32_16x16x32_bf16 v[110:113], v[66:69], v[204:207], v[110:113]
	v_mfma_f32_16x16x32_bf16 v[102:105], v[74:77], v[204:207], v[102:105]
	s_barrier
	s_add_i32 s66, 0, 0x1c000
	v_add_u32_e32 v138, s66, v170
	s_add_i32 s36, s84, s68
	ds_read_b128 v[208:211], v138
	ds_read_b128 v[222:225], v138 offset:1024
	ds_read_b128 v[226:229], v138 offset:2048
	ds_read_b128 v[230:233], v138 offset:3072
	v_lshl_add_u64 v[138:139], v[192:193], 0, s[22:23]
	s_mov_b32 m0, s36
	s_nop 0
	global_load_lds_dwordx4 v[138:139], off
	v_lshl_add_u64 v[138:139], v[214:215], 0, s[22:23]
	s_add_i32 m0, s36, 0x2000
	s_nop 0
	global_load_lds_dwordx4 v[138:139], off
	s_barrier
	s_waitcnt lgkmcnt(0)
	s_waitcnt lgkmcnt(0)
	v_mfma_f32_16x16x32_bf16 v[78:81], v[226:229], v[122:125], v[78:81]
	v_mfma_f32_16x16x32_bf16 v[138:141], v[208:211], v[122:125], v[154:157]
	v_mfma_f32_16x16x32_bf16 v[146:149], v[230:233], v[130:133], v[78:81]
	v_mfma_f32_16x16x32_bf16 v[78:81], v[208:211], v[176:179], v[86:89]
	v_mfma_f32_16x16x32_bf16 v[154:157], v[222:225], v[130:133], v[138:141]
	v_mfma_f32_16x16x32_bf16 v[138:141], v[222:225], v[180:183], v[78:81]
	v_mfma_f32_16x16x32_bf16 v[78:81], v[226:229], v[176:179], v[90:93]
	v_mfma_f32_16x16x32_bf16 v[130:133], v[230:233], v[180:183], v[78:81]
	v_mfma_f32_16x16x32_bf16 v[78:81], v[208:211], v[184:187], v[94:97]
	v_mfma_f32_16x16x32_bf16 v[122:125], v[222:225], v[188:191], v[78:81]
	v_mfma_f32_16x16x32_bf16 v[78:81], v[226:229], v[184:187], v[114:117]
	v_mfma_f32_16x16x32_bf16 v[114:117], v[230:233], v[188:191], v[78:81]
	v_mfma_f32_16x16x32_bf16 v[78:81], v[208:211], v[200:203], v[106:109]
	v_mfma_f32_16x16x32_bf16 v[106:109], v[222:225], v[204:207], v[78:81]
	v_mfma_f32_16x16x32_bf16 v[78:81], v[226:229], v[200:203], v[98:101]
	v_mfma_f32_16x16x32_bf16 v[98:101], v[230:233], v[204:207], v[78:81]
	s_mov_b32 m0, s73
	v_lshl_add_u64 v[192:193], v[234:235], 0, s[22:23]
	s_barrier
	s_nop 2
	ds_read_b128 v[78:81], v175 offset:49152
	ds_read_b128 v[86:89], v175 offset:50176
	ds_read_b128 v[90:93], v175 offset:51200
	ds_read_b128 v[94:97], v175 offset:52224
	ds_read_b128 v[176:179], v175 offset:53248
	ds_read_b128 v[180:183], v175 offset:54272
	ds_read_b128 v[184:187], v175 offset:55296
	ds_read_b128 v[188:191], v175 offset:56320
	global_load_lds_dwordx4 v[192:193], off
	v_lshl_add_u64 v[192:193], v[236:237], 0, s[22:23]
	s_mov_b32 m0, s75
	s_nop 0
	global_load_lds_dwordx4 v[192:193], off
	s_barrier
	s_waitcnt lgkmcnt(0)
	s_waitcnt lgkmcnt(0)
	v_mfma_f32_16x16x32_bf16 v[82:85], v[62:65], v[78:81], v[82:85]
	v_mfma_f32_16x16x32_bf16 v[54:57], v[70:73], v[78:81], v[54:57]
	v_mfma_f32_16x16x32_bf16 v[46:49], v[62:65], v[90:93], v[46:49]
	v_mfma_f32_16x16x32_bf16 v[38:41], v[70:73], v[90:93], v[38:41]
	v_mfma_f32_16x16x32_bf16 v[30:33], v[62:65], v[176:179], v[30:33]
	v_mfma_f32_16x16x32_bf16 v[22:25], v[70:73], v[176:179], v[22:25]
	v_mfma_f32_16x16x32_bf16 v[14:17], v[62:65], v[184:187], v[14:17]
	v_mfma_f32_16x16x32_bf16 v[6:9], v[70:73], v[184:187], v[6:9]
	v_mfma_f32_16x16x32_bf16 v[82:85], v[66:69], v[86:89], v[82:85]
	v_mfma_f32_16x16x32_bf16 v[54:57], v[74:77], v[86:89], v[54:57]
	v_mfma_f32_16x16x32_bf16 v[46:49], v[66:69], v[94:97], v[46:49]
	v_mfma_f32_16x16x32_bf16 v[38:41], v[74:77], v[94:97], v[38:41]
	v_mfma_f32_16x16x32_bf16 v[30:33], v[66:69], v[180:183], v[30:33]
	v_mfma_f32_16x16x32_bf16 v[22:25], v[74:77], v[180:183], v[22:25]
	v_mfma_f32_16x16x32_bf16 v[14:17], v[66:69], v[188:191], v[14:17]
	v_mfma_f32_16x16x32_bf16 v[6:9], v[74:77], v[188:191], v[6:9]
	s_barrier
	s_add_u32 s36, s64, 0x40080
	s_addc_u32 s37, s65, 0
	s_add_i32 s64, s66, s68
	v_lshl_add_u64 v[62:63], s[36:37], 0, v[164:165]
	s_mov_b32 m0, s64
	s_nop 0
	global_load_lds_dwordx4 v[62:63], off
	v_lshl_add_u64 v[62:63], s[36:37], 0, v[162:163]
	s_add_i32 m0, s64, 0x2000
	s_nop 0
	global_load_lds_dwordx4 v[62:63], off
	s_waitcnt vmcnt(6)
	s_barrier
	v_mfma_f32_16x16x32_bf16 v[58:61], v[208:211], v[78:81], v[58:61]
	v_mfma_f32_16x16x32_bf16 v[50:53], v[226:229], v[78:81], v[50:53]
	v_mfma_f32_16x16x32_bf16 v[42:45], v[208:211], v[90:93], v[42:45]
	v_mfma_f32_16x16x32_bf16 v[34:37], v[226:229], v[90:93], v[34:37]
	v_mfma_f32_16x16x32_bf16 v[26:29], v[208:211], v[176:179], v[26:29]
	v_mfma_f32_16x16x32_bf16 v[18:21], v[226:229], v[176:179], v[18:21]
	v_mfma_f32_16x16x32_bf16 v[10:13], v[208:211], v[184:187], v[10:13]
	v_mfma_f32_16x16x32_bf16 v[2:5], v[226:229], v[184:187], v[2:5]
	v_mfma_f32_16x16x32_bf16 v[74:77], v[222:225], v[86:89], v[58:61]
	v_mfma_f32_16x16x32_bf16 v[50:53], v[230:233], v[86:89], v[50:53]
	v_mfma_f32_16x16x32_bf16 v[42:45], v[222:225], v[94:97], v[42:45]
	v_mfma_f32_16x16x32_bf16 v[34:37], v[230:233], v[94:97], v[34:37]
	v_mfma_f32_16x16x32_bf16 v[26:29], v[222:225], v[180:183], v[26:29]
	v_mfma_f32_16x16x32_bf16 v[18:21], v[230:233], v[180:183], v[18:21]
	v_mfma_f32_16x16x32_bf16 v[10:13], v[222:225], v[188:191], v[10:13]
	v_mfma_f32_16x16x32_bf16 v[2:5], v[230:233], v[188:191], v[2:5]
	s_add_i32 s83, s83, 2
	s_add_u32 s81, s81, 0x100
	s_addc_u32 s82, s82, 0
	s_cmp_gt_u32 s83, 13
	s_mov_b64 s[36:37], s[62:63]
	s_barrier
	s_cbranch_scc0 .LBB0_1099
	s_setprio 0
	v_lshl_or_b32 v58, s27, 8, v174
	v_mov_b32_e32 v177, v1
	v_ashrrev_i32_e32 v59, 31, v58
	v_lshlrev_b64 v[58:59], 2, v[58:59]
	v_lshl_add_u64 v[66:67], s[46:47], 0, v[58:59]
	v_lshl_add_u64 v[70:71], s[48:49], 0, v[58:59]
	v_lshlrev_b32_e32 v250, 2, v174
	v_add_u32_e32 v250, 0x20840, v250
	ds_read_b128 v[86:89], v250
	ds_read_b128 v[78:81], v250 offset:1024
	ds_read_b128 v[62:65], v250 offset:16
	ds_read_b128 v[58:61], v250 offset:1040
	ds_read_b128 v[94:97], v250 offset:512
	ds_read_b128 v[90:93], v250 offset:1536
	s_nop 0
	ds_read_b128 v[66:69], v250 offset:528
	s_nop 0
	ds_read_b128 v[70:73], v250 offset:1552
	s_lshl_b32 s3, s3, 8
	v_lshl_or_b32 v176, s27, 7, v174
	v_add_u32_e32 v184, s3, v177
	v_lshl_add_u32 v177, v177, 3, s33
	ds_read_b64 v[178:179], v177
	s_movk_i32 s27, 0xb00
	s_and_b64 vcc, exec, s[60:61]
	s_waitcnt lgkmcnt(0)
	v_xor_b32_e32 v89, 0x80000000, v89
	v_xor_b32_e32 v88, 0x80000000, v88
	v_pk_fma_f32 v[160:161], v[88:89], v[178:179], v[160:161] op_sel_hi:[1,0,1]
	v_pk_fma_f32 v[158:159], v[86:87], v[178:179], v[158:159] op_sel_hi:[1,0,1] neg_lo:[1,0,0] neg_hi:[1,0,0]
	v_pk_fma_f32 v[160:161], v[178:179], v[160:161], v[80:81] op_sel:[1,0,0]
	v_pk_fma_f32 v[158:159], v[178:179], v[158:159], v[78:79] op_sel:[1,0,0]
	v_pk_fma_f32 v[154:155], v[94:95], v[178:179], v[154:155] op_sel_hi:[1,0,1] neg_lo:[1,0,0] neg_hi:[1,0,0]
	v_mul_f32_e32 v182, 0xbfb8aa3b, v160
	v_pk_fma_f32 v[180:181], v[178:179], v[154:155], v[90:91] op_sel:[1,0,0]
	v_mul_f32_e32 v154, 0xbfb8aa3b, v158
	v_mul_f32_e32 v155, 0xbfb8aa3b, v159
	v_mul_f32_e32 v183, 0xbfb8aa3b, v161
	v_exp_f32_e32 v154, v154
	v_exp_f32_e32 v155, v155
	v_exp_f32_e32 v182, v182
	v_exp_f32_e32 v183, v183
	v_add_f32_e32 v154, 1.0, v154
	v_add_f32_e32 v155, 1.0, v155
	v_add_f32_e32 v182, 1.0, v182
	v_add_f32_e32 v183, 1.0, v183
	v_rcp_f32_e32 v154, v154
	v_rcp_f32_e32 v155, v155
	v_rcp_f32_e32 v182, v182
	v_rcp_f32_e32 v183, v183
	v_xor_b32_e32 v97, 0x80000000, v97
	v_xor_b32_e32 v96, 0x80000000, v96
	v_xor_b32_e32 v65, 0x80000000, v65
	v_xor_b32_e32 v64, 0x80000000, v64
	v_pk_fma_f32 v[156:157], v[96:97], v[178:179], v[156:157] op_sel_hi:[1,0,1]
	v_pk_fma_f32 v[152:153], v[64:65], v[178:179], v[152:153] op_sel_hi:[1,0,1]
	v_pk_fma_f32 v[150:151], v[62:63], v[178:179], v[150:151] op_sel_hi:[1,0,1] neg_lo:[1,0,0] neg_hi:[1,0,0]
	v_pk_fma_f32 v[156:157], v[178:179], v[156:157], v[92:93] op_sel:[1,0,0]
	v_pk_mul_f32 v[160:161], v[160:161], v[182:183]
	v_pk_mul_f32 v[158:159], v[158:159], v[154:155]
	v_pk_fma_f32 v[152:153], v[178:179], v[152:153], v[60:61] op_sel:[1,0,0]
	v_pk_fma_f32 v[150:151], v[178:179], v[150:151], v[58:59] op_sel:[1,0,0]
	v_pk_mul_f32 v[154:155], v[156:157], v[160:161]
	v_pk_mul_f32 v[156:157], v[180:181], v[158:159]
	v_mul_f32_e32 v158, 0xbfb8aa3b, v150
	v_mul_f32_e32 v159, 0xbfb8aa3b, v151
	v_mul_f32_e32 v160, 0xbfb8aa3b, v152
	v_mul_f32_e32 v161, 0xbfb8aa3b, v153
	v_exp_f32_e32 v158, v158
	v_exp_f32_e32 v159, v159
	v_exp_f32_e32 v160, v160
	v_exp_f32_e32 v161, v161
	v_add_f32_e32 v158, 1.0, v158
	v_add_f32_e32 v159, 1.0, v159
	v_add_f32_e32 v160, 1.0, v160
	v_add_f32_e32 v161, 1.0, v161
	v_rcp_f32_e32 v158, v158
	v_rcp_f32_e32 v159, v159
	v_rcp_f32_e32 v160, v160
	v_rcp_f32_e32 v161, v161
	v_xor_b32_e32 v69, 0x80000000, v69
	v_xor_b32_e32 v68, 0x80000000, v68
	v_pk_fma_f32 v[148:149], v[68:69], v[178:179], v[148:149] op_sel_hi:[1,0,1]
	v_pk_fma_f32 v[146:147], v[66:67], v[178:179], v[146:147] op_sel_hi:[1,0,1] neg_lo:[1,0,0] neg_hi:[1,0,0]
	v_pk_fma_f32 v[148:149], v[178:179], v[148:149], v[72:73] op_sel:[1,0,0]
	v_pk_fma_f32 v[146:147], v[178:179], v[146:147], v[70:71] op_sel:[1,0,0]
	v_pk_mul_f32 v[152:153], v[152:153], v[160:161]
	v_pk_mul_f32 v[150:151], v[150:151], v[158:159]
	v_mul_lo_u32 v158, v184, s27
	v_pk_mul_f32 v[152:153], v[148:149], v[152:153]
	v_pk_mul_f32 v[148:149], v[146:147], v[150:151]
	v_add_lshl_u32 v150, v158, v176, 1
	v_cvt_pk_bf16_f32 v146, v156, v157
	v_cvt_pk_bf16_f32 v147, v154, v155
	v_cvt_pk_bf16_f32 v148, v148, v149
	v_cvt_pk_bf16_f32 v149, v152, v153
	buffer_store_dwordx4 v[146:149], v150, s[28:31], 0 offen sc1
	ds_read_b64 v[146:147], v177 offset:128
	s_waitcnt lgkmcnt(0)
	v_pk_fma_f32 v[142:143], v[86:87], v[146:147], v[142:143] op_sel_hi:[1,0,1] neg_lo:[1,0,0] neg_hi:[1,0,0]
	s_nop 0
	v_pk_fma_f32 v[142:143], v[146:147], v[142:143], v[78:79] op_sel:[1,0,0]
	v_pk_fma_f32 v[144:145], v[88:89], v[146:147], v[144:145] op_sel_hi:[1,0,1]
	v_mul_f32_e32 v148, 0xbfb8aa3b, v142
	v_mul_f32_e32 v149, 0xbfb8aa3b, v143
	v_pk_fma_f32 v[144:145], v[146:147], v[144:145], v[80:81] op_sel:[1,0,0]
	v_exp_f32_e32 v148, v148
	v_exp_f32_e32 v149, v149
	v_mul_f32_e32 v150, 0xbfb8aa3b, v144
	v_mul_f32_e32 v151, 0xbfb8aa3b, v145
	v_exp_f32_e32 v150, v150
	v_exp_f32_e32 v151, v151
	v_add_f32_e32 v148, 1.0, v148
	v_add_f32_e32 v149, 1.0, v149
	v_rcp_f32_e32 v148, v148
	v_rcp_f32_e32 v149, v149
	v_add_f32_e32 v150, 1.0, v150
	v_add_f32_e32 v151, 1.0, v151
	v_rcp_f32_e32 v150, v150
	v_rcp_f32_e32 v151, v151
	v_pk_fma_f32 v[138:139], v[94:95], v[146:147], v[138:139] op_sel_hi:[1,0,1] neg_lo:[1,0,0] neg_hi:[1,0,0]
	v_pk_fma_f32 v[134:135], v[62:63], v[146:147], v[134:135] op_sel_hi:[1,0,1] neg_lo:[1,0,0] neg_hi:[1,0,0]
	v_pk_fma_f32 v[138:139], v[146:147], v[138:139], v[90:91] op_sel:[1,0,0]
	v_pk_mul_f32 v[142:143], v[142:143], v[148:149]
	v_pk_fma_f32 v[134:135], v[146:147], v[134:135], v[58:59] op_sel:[1,0,0]
	v_pk_fma_f32 v[140:141], v[96:97], v[146:147], v[140:141] op_sel_hi:[1,0,1]
	v_pk_mul_f32 v[138:139], v[138:139], v[142:143]
	v_pk_fma_f32 v[136:137], v[64:65], v[146:147], v[136:137] op_sel_hi:[1,0,1]
	v_mul_f32_e32 v142, 0xbfb8aa3b, v134
	v_mul_f32_e32 v143, 0xbfb8aa3b, v135
	v_pk_fma_f32 v[140:141], v[146:147], v[140:141], v[92:93] op_sel:[1,0,0]
	v_pk_mul_f32 v[144:145], v[144:145], v[150:151]
	v_pk_fma_f32 v[136:137], v[146:147], v[136:137], v[60:61] op_sel:[1,0,0]
	v_exp_f32_e32 v142, v142
	v_exp_f32_e32 v143, v143
	v_pk_mul_f32 v[140:141], v[140:141], v[144:145]
	v_mul_f32_e32 v144, 0xbfb8aa3b, v136
	v_mul_f32_e32 v145, 0xbfb8aa3b, v137
	v_exp_f32_e32 v144, v144
	v_exp_f32_e32 v145, v145
	v_add_f32_e32 v142, 1.0, v142
	v_add_f32_e32 v143, 1.0, v143
	v_rcp_f32_e32 v142, v142
	v_rcp_f32_e32 v143, v143
	v_add_f32_e32 v144, 1.0, v144
	v_add_f32_e32 v145, 1.0, v145
	v_rcp_f32_e32 v144, v144
	v_rcp_f32_e32 v145, v145
	v_pk_fma_f32 v[130:131], v[66:67], v[146:147], v[130:131] op_sel_hi:[1,0,1] neg_lo:[1,0,0] neg_hi:[1,0,0]
	v_pk_mul_f32 v[134:135], v[134:135], v[142:143]
	v_pk_fma_f32 v[130:131], v[146:147], v[130:131], v[70:71] op_sel:[1,0,0]
	v_pk_fma_f32 v[132:133], v[68:69], v[146:147], v[132:133] op_sel_hi:[1,0,1]
	v_pk_mul_f32 v[134:135], v[130:131], v[134:135]
	v_add_u32_e32 v130, 0xb000, v176
	v_pk_fma_f32 v[132:133], v[146:147], v[132:133], v[72:73] op_sel:[1,0,0]
	v_pk_mul_f32 v[136:137], v[136:137], v[144:145]
	v_add_lshl_u32 v131, v158, v130, 1
	v_pk_mul_f32 v[136:137], v[132:133], v[136:137]
	v_cvt_pk_bf16_f32 v132, v138, v139
	v_cvt_pk_bf16_f32 v133, v140, v141
	v_cvt_pk_bf16_f32 v134, v134, v135
	s_nop 0
	v_cvt_pk_bf16_f32 v135, v136, v137
	buffer_store_dwordx4 v[132:135], v131, s[28:31], 0 offen sc1
	v_mov_b32_e32 v131, v171
	s_nop 0
	v_add_u32_e32 v138, s3, v131
	v_lshl_add_u32 v131, v131, 3, s33
	ds_read_b64 v[132:133], v131
	s_waitcnt lgkmcnt(0)
	v_pk_fma_f32 v[128:129], v[88:89], v[132:133], v[128:129] op_sel_hi:[1,0,1]
	v_pk_fma_f32 v[126:127], v[86:87], v[132:133], v[126:127] op_sel_hi:[1,0,1] neg_lo:[1,0,0] neg_hi:[1,0,0]
	v_pk_fma_f32 v[128:129], v[132:133], v[128:129], v[80:81] op_sel:[1,0,0]
	v_pk_fma_f32 v[126:127], v[132:133], v[126:127], v[78:79] op_sel:[1,0,0]
	v_mul_f32_e32 v136, 0xbfb8aa3b, v128
	v_mul_f32_e32 v134, 0xbfb8aa3b, v126
	v_mul_f32_e32 v135, 0xbfb8aa3b, v127
	v_mul_f32_e32 v137, 0xbfb8aa3b, v129
	v_exp_f32_e32 v134, v134
	v_exp_f32_e32 v135, v135
	v_exp_f32_e32 v136, v136
	v_exp_f32_e32 v137, v137
	v_add_f32_e32 v134, 1.0, v134
	v_add_f32_e32 v135, 1.0, v135
	v_add_f32_e32 v136, 1.0, v136
	v_add_f32_e32 v137, 1.0, v137
	v_rcp_f32_e32 v134, v134
	v_rcp_f32_e32 v135, v135
	v_rcp_f32_e32 v136, v136
	v_rcp_f32_e32 v137, v137
	v_pk_fma_f32 v[124:125], v[96:97], v[132:133], v[124:125] op_sel_hi:[1,0,1]
	v_pk_fma_f32 v[122:123], v[94:95], v[132:133], v[122:123] op_sel_hi:[1,0,1] neg_lo:[1,0,0] neg_hi:[1,0,0]
	v_pk_fma_f32 v[120:121], v[64:65], v[132:133], v[120:121] op_sel_hi:[1,0,1]
	v_pk_fma_f32 v[118:119], v[62:63], v[132:133], v[118:119] op_sel_hi:[1,0,1] neg_lo:[1,0,0] neg_hi:[1,0,0]
	v_pk_fma_f32 v[124:125], v[132:133], v[124:125], v[92:93] op_sel:[1,0,0]
	v_pk_fma_f32 v[122:123], v[132:133], v[122:123], v[90:91] op_sel:[1,0,0]
	v_pk_mul_f32 v[128:129], v[128:129], v[136:137]
	v_pk_mul_f32 v[126:127], v[126:127], v[134:135]
	v_pk_fma_f32 v[120:121], v[132:133], v[120:121], v[60:61] op_sel:[1,0,0]
	v_pk_fma_f32 v[118:119], v[132:133], v[118:119], v[58:59] op_sel:[1,0,0]
	v_pk_mul_f32 v[124:125], v[124:125], v[128:129]
	v_pk_mul_f32 v[122:123], v[122:123], v[126:127]
	v_mul_f32_e32 v126, 0xbfb8aa3b, v118
	v_mul_f32_e32 v127, 0xbfb8aa3b, v119
	v_mul_f32_e32 v128, 0xbfb8aa3b, v120
	v_mul_f32_e32 v129, 0xbfb8aa3b, v121
	v_exp_f32_e32 v126, v126
	v_exp_f32_e32 v127, v127
	v_exp_f32_e32 v128, v128
	v_exp_f32_e32 v129, v129
	v_add_f32_e32 v126, 1.0, v126
	v_add_f32_e32 v127, 1.0, v127
	v_add_f32_e32 v128, 1.0, v128
	v_add_f32_e32 v129, 1.0, v129
	v_rcp_f32_e32 v126, v126
	v_rcp_f32_e32 v127, v127
	v_rcp_f32_e32 v128, v128
	v_rcp_f32_e32 v129, v129
	v_pk_fma_f32 v[116:117], v[68:69], v[132:133], v[116:117] op_sel_hi:[1,0,1]
	v_pk_fma_f32 v[114:115], v[66:67], v[132:133], v[114:115] op_sel_hi:[1,0,1] neg_lo:[1,0,0] neg_hi:[1,0,0]
	v_pk_fma_f32 v[116:117], v[132:133], v[116:117], v[72:73] op_sel:[1,0,0]
	v_pk_fma_f32 v[114:115], v[132:133], v[114:115], v[70:71] op_sel:[1,0,0]
	v_pk_mul_f32 v[120:121], v[120:121], v[128:129]
	v_pk_mul_f32 v[118:119], v[118:119], v[126:127]
	v_mul_lo_u32 v126, v138, s27
	v_pk_mul_f32 v[120:121], v[116:117], v[120:121]
	v_pk_mul_f32 v[116:117], v[114:115], v[118:119]
	v_add_lshl_u32 v118, v126, v176, 1
	v_cvt_pk_bf16_f32 v114, v122, v123
	v_cvt_pk_bf16_f32 v115, v124, v125
	v_cvt_pk_bf16_f32 v116, v116, v117
	v_cvt_pk_bf16_f32 v117, v120, v121
	buffer_store_dwordx4 v[114:117], v118, s[28:31], 0 offen sc1
	ds_read_b64 v[114:115], v131 offset:128
	s_waitcnt lgkmcnt(0)
	v_pk_fma_f32 v[112:113], v[88:89], v[114:115], v[112:113] op_sel_hi:[1,0,1]
	v_pk_fma_f32 v[110:111], v[86:87], v[114:115], v[110:111] op_sel_hi:[1,0,1] neg_lo:[1,0,0] neg_hi:[1,0,0]
	v_pk_fma_f32 v[112:113], v[114:115], v[112:113], v[80:81] op_sel:[1,0,0]
	v_pk_fma_f32 v[110:111], v[114:115], v[110:111], v[78:79] op_sel:[1,0,0]
	v_mul_f32_e32 v118, 0xbfb8aa3b, v112
	v_mul_f32_e32 v116, 0xbfb8aa3b, v110
	v_mul_f32_e32 v117, 0xbfb8aa3b, v111
	v_mul_f32_e32 v119, 0xbfb8aa3b, v113
	v_exp_f32_e32 v116, v116
	v_exp_f32_e32 v117, v117
	v_exp_f32_e32 v118, v118
	v_exp_f32_e32 v119, v119
	v_add_f32_e32 v116, 1.0, v116
	v_add_f32_e32 v117, 1.0, v117
	v_add_f32_e32 v118, 1.0, v118
	v_add_f32_e32 v119, 1.0, v119
	v_rcp_f32_e32 v116, v116
	v_rcp_f32_e32 v117, v117
	v_rcp_f32_e32 v118, v118
	v_rcp_f32_e32 v119, v119
	v_pk_fma_f32 v[108:109], v[96:97], v[114:115], v[108:109] op_sel_hi:[1,0,1]
	v_pk_fma_f32 v[106:107], v[94:95], v[114:115], v[106:107] op_sel_hi:[1,0,1] neg_lo:[1,0,0] neg_hi:[1,0,0]
	v_pk_fma_f32 v[104:105], v[64:65], v[114:115], v[104:105] op_sel_hi:[1,0,1]
	v_pk_fma_f32 v[102:103], v[62:63], v[114:115], v[102:103] op_sel_hi:[1,0,1] neg_lo:[1,0,0] neg_hi:[1,0,0]
	v_pk_fma_f32 v[108:109], v[114:115], v[108:109], v[92:93] op_sel:[1,0,0]
	v_pk_fma_f32 v[106:107], v[114:115], v[106:107], v[90:91] op_sel:[1,0,0]
	v_pk_mul_f32 v[112:113], v[112:113], v[118:119]
	v_pk_mul_f32 v[110:111], v[110:111], v[116:117]
	v_pk_fma_f32 v[104:105], v[114:115], v[104:105], v[60:61] op_sel:[1,0,0]
	v_pk_fma_f32 v[102:103], v[114:115], v[102:103], v[58:59] op_sel:[1,0,0]
	v_pk_mul_f32 v[108:109], v[108:109], v[112:113]
	v_pk_mul_f32 v[106:107], v[106:107], v[110:111]
	v_mul_f32_e32 v110, 0xbfb8aa3b, v102
	v_mul_f32_e32 v111, 0xbfb8aa3b, v103
	v_mul_f32_e32 v112, 0xbfb8aa3b, v104
	v_mul_f32_e32 v113, 0xbfb8aa3b, v105
	v_exp_f32_e32 v110, v110
	v_exp_f32_e32 v111, v111
	v_exp_f32_e32 v112, v112
	v_exp_f32_e32 v113, v113
	v_add_f32_e32 v110, 1.0, v110
	v_add_f32_e32 v111, 1.0, v111
	v_add_f32_e32 v112, 1.0, v112
	v_add_f32_e32 v113, 1.0, v113
	v_rcp_f32_e32 v110, v110
	v_rcp_f32_e32 v111, v111
	v_rcp_f32_e32 v112, v112
	v_rcp_f32_e32 v113, v113
	v_pk_fma_f32 v[100:101], v[68:69], v[114:115], v[100:101] op_sel_hi:[1,0,1]
	v_pk_fma_f32 v[98:99], v[66:67], v[114:115], v[98:99] op_sel_hi:[1,0,1] neg_lo:[1,0,0] neg_hi:[1,0,0]
	v_pk_fma_f32 v[100:101], v[114:115], v[100:101], v[72:73] op_sel:[1,0,0]
	v_pk_fma_f32 v[98:99], v[114:115], v[98:99], v[70:71] op_sel:[1,0,0]
	v_pk_mul_f32 v[104:105], v[104:105], v[112:113]
	v_pk_mul_f32 v[102:103], v[102:103], v[110:111]
	v_pk_mul_f32 v[104:105], v[100:101], v[104:105]
	v_pk_mul_f32 v[100:101], v[98:99], v[102:103]
	v_add_lshl_u32 v102, v126, v130, 1
	v_cvt_pk_bf16_f32 v98, v106, v107
	v_cvt_pk_bf16_f32 v99, v108, v109
	v_cvt_pk_bf16_f32 v100, v100, v101
	v_cvt_pk_bf16_f32 v101, v104, v105
	buffer_store_dwordx4 v[98:101], v102, s[28:31], 0 offen sc1
	s_nop 1
	v_mov_b32_e32 v98, v172
	s_nop 0
	v_lshl_add_u32 v105, v98, 3, s33
	v_add_u32_e32 v104, s3, v98
	ds_read_b64 v[98:99], v105
	s_waitcnt lgkmcnt(0)
	v_pk_fma_f32 v[84:85], v[88:89], v[98:99], v[84:85] op_sel_hi:[1,0,1]
	v_pk_fma_f32 v[82:83], v[86:87], v[98:99], v[82:83] op_sel_hi:[1,0,1] neg_lo:[1,0,0] neg_hi:[1,0,0]
	v_pk_fma_f32 v[84:85], v[98:99], v[84:85], v[80:81] op_sel:[1,0,0]
	v_pk_fma_f32 v[82:83], v[98:99], v[82:83], v[78:79] op_sel:[1,0,0]
	v_mul_f32_e32 v102, 0xbfb8aa3b, v84
	v_mul_f32_e32 v100, 0xbfb8aa3b, v82
	v_mul_f32_e32 v101, 0xbfb8aa3b, v83
	v_mul_f32_e32 v103, 0xbfb8aa3b, v85
	v_exp_f32_e32 v100, v100
	v_exp_f32_e32 v101, v101
	v_exp_f32_e32 v102, v102
	v_exp_f32_e32 v103, v103
	v_add_f32_e32 v100, 1.0, v100
	v_add_f32_e32 v101, 1.0, v101
	v_add_f32_e32 v102, 1.0, v102
	v_add_f32_e32 v103, 1.0, v103
	v_rcp_f32_e32 v100, v100
	v_rcp_f32_e32 v101, v101
	v_rcp_f32_e32 v102, v102
	v_rcp_f32_e32 v103, v103
	v_pk_fma_f32 v[76:77], v[96:97], v[98:99], v[76:77] op_sel_hi:[1,0,1]
	v_pk_fma_f32 v[74:75], v[94:95], v[98:99], v[74:75] op_sel_hi:[1,0,1] neg_lo:[1,0,0] neg_hi:[1,0,0]
	v_pk_fma_f32 v[56:57], v[64:65], v[98:99], v[56:57] op_sel_hi:[1,0,1]
	v_pk_fma_f32 v[54:55], v[62:63], v[98:99], v[54:55] op_sel_hi:[1,0,1] neg_lo:[1,0,0] neg_hi:[1,0,0]
	v_pk_fma_f32 v[76:77], v[98:99], v[76:77], v[92:93] op_sel:[1,0,0]
	v_pk_fma_f32 v[74:75], v[98:99], v[74:75], v[90:91] op_sel:[1,0,0]
	v_pk_mul_f32 v[84:85], v[84:85], v[102:103]
	v_pk_mul_f32 v[82:83], v[82:83], v[100:101]
	v_pk_fma_f32 v[56:57], v[98:99], v[56:57], v[60:61] op_sel:[1,0,0]
	v_pk_fma_f32 v[54:55], v[98:99], v[54:55], v[58:59] op_sel:[1,0,0]
	v_pk_mul_f32 v[76:77], v[76:77], v[84:85]
	v_pk_mul_f32 v[74:75], v[74:75], v[82:83]
	v_mul_f32_e32 v82, 0xbfb8aa3b, v54
	v_mul_f32_e32 v83, 0xbfb8aa3b, v55
	v_mul_f32_e32 v84, 0xbfb8aa3b, v56
	v_mul_f32_e32 v85, 0xbfb8aa3b, v57
	v_exp_f32_e32 v82, v82
	v_exp_f32_e32 v83, v83
	v_exp_f32_e32 v84, v84
	v_exp_f32_e32 v85, v85
	v_add_f32_e32 v82, 1.0, v82
	v_add_f32_e32 v83, 1.0, v83
	v_add_f32_e32 v84, 1.0, v84
	v_add_f32_e32 v85, 1.0, v85
	v_rcp_f32_e32 v82, v82
	v_rcp_f32_e32 v83, v83
	v_rcp_f32_e32 v84, v84
	v_rcp_f32_e32 v85, v85
	v_pk_fma_f32 v[52:53], v[68:69], v[98:99], v[52:53] op_sel_hi:[1,0,1]
	v_pk_fma_f32 v[50:51], v[66:67], v[98:99], v[50:51] op_sel_hi:[1,0,1] neg_lo:[1,0,0] neg_hi:[1,0,0]
	v_pk_fma_f32 v[52:53], v[98:99], v[52:53], v[72:73] op_sel:[1,0,0]
	v_pk_fma_f32 v[50:51], v[98:99], v[50:51], v[70:71] op_sel:[1,0,0]
	v_pk_mul_f32 v[56:57], v[56:57], v[84:85]
	v_pk_mul_f32 v[54:55], v[54:55], v[82:83]
	v_mul_lo_u32 v82, v104, s27
	v_pk_mul_f32 v[56:57], v[52:53], v[56:57]
	v_pk_mul_f32 v[52:53], v[50:51], v[54:55]
	v_add_lshl_u32 v54, v82, v176, 1
	v_cvt_pk_bf16_f32 v50, v74, v75
	v_cvt_pk_bf16_f32 v51, v76, v77
	v_cvt_pk_bf16_f32 v52, v52, v53
	v_cvt_pk_bf16_f32 v53, v56, v57
	buffer_store_dwordx4 v[50:53], v54, s[28:31], 0 offen sc1
	ds_read_b64 v[50:51], v105 offset:128
	s_waitcnt lgkmcnt(0)
	v_pk_fma_f32 v[48:49], v[88:89], v[50:51], v[48:49] op_sel_hi:[1,0,1]
	v_pk_fma_f32 v[46:47], v[86:87], v[50:51], v[46:47] op_sel_hi:[1,0,1] neg_lo:[1,0,0] neg_hi:[1,0,0]
	v_pk_fma_f32 v[48:49], v[50:51], v[48:49], v[80:81] op_sel:[1,0,0]
	v_pk_fma_f32 v[46:47], v[50:51], v[46:47], v[78:79] op_sel:[1,0,0]
	v_mul_f32_e32 v54, 0xbfb8aa3b, v48
	v_mul_f32_e32 v52, 0xbfb8aa3b, v46
	v_mul_f32_e32 v53, 0xbfb8aa3b, v47
	v_mul_f32_e32 v55, 0xbfb8aa3b, v49
	v_exp_f32_e32 v52, v52
	v_exp_f32_e32 v53, v53
	v_exp_f32_e32 v54, v54
	v_exp_f32_e32 v55, v55
	v_add_f32_e32 v52, 1.0, v52
	v_add_f32_e32 v53, 1.0, v53
	v_add_f32_e32 v54, 1.0, v54
	v_add_f32_e32 v55, 1.0, v55
	v_rcp_f32_e32 v52, v52
	v_rcp_f32_e32 v53, v53
	v_rcp_f32_e32 v54, v54
	v_rcp_f32_e32 v55, v55
	v_pk_fma_f32 v[44:45], v[96:97], v[50:51], v[44:45] op_sel_hi:[1,0,1]
	v_pk_fma_f32 v[42:43], v[94:95], v[50:51], v[42:43] op_sel_hi:[1,0,1] neg_lo:[1,0,0] neg_hi:[1,0,0]
	v_pk_fma_f32 v[40:41], v[64:65], v[50:51], v[40:41] op_sel_hi:[1,0,1]
	v_pk_fma_f32 v[38:39], v[62:63], v[50:51], v[38:39] op_sel_hi:[1,0,1] neg_lo:[1,0,0] neg_hi:[1,0,0]
	v_pk_fma_f32 v[44:45], v[50:51], v[44:45], v[92:93] op_sel:[1,0,0]
	v_pk_fma_f32 v[42:43], v[50:51], v[42:43], v[90:91] op_sel:[1,0,0]
	v_pk_mul_f32 v[48:49], v[48:49], v[54:55]
	v_pk_mul_f32 v[46:47], v[46:47], v[52:53]
	v_pk_fma_f32 v[40:41], v[50:51], v[40:41], v[60:61] op_sel:[1,0,0]
	v_pk_fma_f32 v[38:39], v[50:51], v[38:39], v[58:59] op_sel:[1,0,0]
	v_pk_mul_f32 v[44:45], v[44:45], v[48:49]
	v_pk_mul_f32 v[42:43], v[42:43], v[46:47]
	v_mul_f32_e32 v46, 0xbfb8aa3b, v38
	v_mul_f32_e32 v47, 0xbfb8aa3b, v39
	v_mul_f32_e32 v48, 0xbfb8aa3b, v40
	v_mul_f32_e32 v49, 0xbfb8aa3b, v41
	v_exp_f32_e32 v46, v46
	v_exp_f32_e32 v47, v47
	v_exp_f32_e32 v48, v48
	v_exp_f32_e32 v49, v49
	v_add_f32_e32 v46, 1.0, v46
	v_add_f32_e32 v47, 1.0, v47
	v_add_f32_e32 v48, 1.0, v48
	v_add_f32_e32 v49, 1.0, v49
	v_rcp_f32_e32 v46, v46
	v_rcp_f32_e32 v47, v47
	v_rcp_f32_e32 v48, v48
	v_rcp_f32_e32 v49, v49
	v_pk_fma_f32 v[36:37], v[68:69], v[50:51], v[36:37] op_sel_hi:[1,0,1]
	v_pk_fma_f32 v[34:35], v[66:67], v[50:51], v[34:35] op_sel_hi:[1,0,1] neg_lo:[1,0,0] neg_hi:[1,0,0]
	v_pk_fma_f32 v[36:37], v[50:51], v[36:37], v[72:73] op_sel:[1,0,0]
	v_pk_fma_f32 v[34:35], v[50:51], v[34:35], v[70:71] op_sel:[1,0,0]
	v_pk_mul_f32 v[40:41], v[40:41], v[48:49]
	v_pk_mul_f32 v[38:39], v[38:39], v[46:47]
	v_pk_mul_f32 v[40:41], v[36:37], v[40:41]
	v_pk_mul_f32 v[36:37], v[34:35], v[38:39]
	v_add_lshl_u32 v38, v82, v130, 1
	v_cvt_pk_bf16_f32 v34, v42, v43
	v_cvt_pk_bf16_f32 v35, v44, v45
	v_cvt_pk_bf16_f32 v36, v36, v37
	v_cvt_pk_bf16_f32 v37, v40, v41
	buffer_store_dwordx4 v[34:37], v38, s[28:31], 0 offen sc1
	s_nop 1
	v_mov_b32_e32 v34, v173
	s_nop 0
	v_lshl_add_u32 v41, v34, 3, s33
	v_add_u32_e32 v40, s3, v34
	ds_read_b64 v[34:35], v41
	s_mov_b32 s3, s77
	s_waitcnt lgkmcnt(0)
	v_pk_fma_f32 v[32:33], v[88:89], v[34:35], v[32:33] op_sel_hi:[1,0,1]
	v_pk_fma_f32 v[30:31], v[86:87], v[34:35], v[30:31] op_sel_hi:[1,0,1] neg_lo:[1,0,0] neg_hi:[1,0,0]
	v_pk_fma_f32 v[32:33], v[34:35], v[32:33], v[80:81] op_sel:[1,0,0]
	v_pk_fma_f32 v[30:31], v[34:35], v[30:31], v[78:79] op_sel:[1,0,0]
	v_mul_f32_e32 v38, 0xbfb8aa3b, v32
	v_mul_f32_e32 v36, 0xbfb8aa3b, v30
	v_mul_f32_e32 v37, 0xbfb8aa3b, v31
	v_mul_f32_e32 v39, 0xbfb8aa3b, v33
	v_exp_f32_e32 v36, v36
	v_exp_f32_e32 v37, v37
	v_exp_f32_e32 v38, v38
	v_exp_f32_e32 v39, v39
	v_add_f32_e32 v36, 1.0, v36
	v_add_f32_e32 v37, 1.0, v37
	v_add_f32_e32 v38, 1.0, v38
	v_add_f32_e32 v39, 1.0, v39
	v_rcp_f32_e32 v36, v36
	v_rcp_f32_e32 v37, v37
	v_rcp_f32_e32 v38, v38
	v_rcp_f32_e32 v39, v39
	v_pk_fma_f32 v[28:29], v[96:97], v[34:35], v[28:29] op_sel_hi:[1,0,1]
	v_pk_fma_f32 v[26:27], v[94:95], v[34:35], v[26:27] op_sel_hi:[1,0,1] neg_lo:[1,0,0] neg_hi:[1,0,0]
	v_pk_fma_f32 v[24:25], v[64:65], v[34:35], v[24:25] op_sel_hi:[1,0,1]
	v_pk_fma_f32 v[22:23], v[62:63], v[34:35], v[22:23] op_sel_hi:[1,0,1] neg_lo:[1,0,0] neg_hi:[1,0,0]
	v_pk_fma_f32 v[28:29], v[34:35], v[28:29], v[92:93] op_sel:[1,0,0]
	v_pk_fma_f32 v[26:27], v[34:35], v[26:27], v[90:91] op_sel:[1,0,0]
	v_pk_mul_f32 v[32:33], v[32:33], v[38:39]
	v_pk_mul_f32 v[30:31], v[30:31], v[36:37]
	v_pk_fma_f32 v[24:25], v[34:35], v[24:25], v[60:61] op_sel:[1,0,0]
	v_pk_fma_f32 v[22:23], v[34:35], v[22:23], v[58:59] op_sel:[1,0,0]
	v_pk_mul_f32 v[28:29], v[28:29], v[32:33]
	v_pk_mul_f32 v[26:27], v[26:27], v[30:31]
	v_mul_f32_e32 v30, 0xbfb8aa3b, v22
	v_mul_f32_e32 v31, 0xbfb8aa3b, v23
	v_mul_f32_e32 v32, 0xbfb8aa3b, v24
	v_mul_f32_e32 v33, 0xbfb8aa3b, v25
	v_exp_f32_e32 v30, v30
	v_exp_f32_e32 v31, v31
	v_exp_f32_e32 v32, v32
	v_exp_f32_e32 v33, v33
	v_add_f32_e32 v30, 1.0, v30
	v_add_f32_e32 v31, 1.0, v31
	v_add_f32_e32 v32, 1.0, v32
	v_add_f32_e32 v33, 1.0, v33
	v_rcp_f32_e32 v30, v30
	v_rcp_f32_e32 v31, v31
	v_rcp_f32_e32 v32, v32
	v_rcp_f32_e32 v33, v33
	v_pk_fma_f32 v[20:21], v[68:69], v[34:35], v[20:21] op_sel_hi:[1,0,1]
	v_pk_fma_f32 v[18:19], v[66:67], v[34:35], v[18:19] op_sel_hi:[1,0,1] neg_lo:[1,0,0] neg_hi:[1,0,0]
	v_pk_fma_f32 v[20:21], v[34:35], v[20:21], v[72:73] op_sel:[1,0,0]
	v_pk_fma_f32 v[18:19], v[34:35], v[18:19], v[70:71] op_sel:[1,0,0]
	v_pk_mul_f32 v[24:25], v[24:25], v[32:33]
	v_pk_mul_f32 v[22:23], v[22:23], v[30:31]
	v_mul_lo_u32 v30, v40, s27
	v_pk_mul_f32 v[24:25], v[20:21], v[24:25]
	v_pk_mul_f32 v[20:21], v[18:19], v[22:23]
	v_add_lshl_u32 v22, v30, v176, 1
	v_cvt_pk_bf16_f32 v18, v26, v27
	v_cvt_pk_bf16_f32 v19, v28, v29
	v_cvt_pk_bf16_f32 v20, v20, v21
	v_cvt_pk_bf16_f32 v21, v24, v25
	buffer_store_dwordx4 v[18:21], v22, s[28:31], 0 offen sc1
	ds_read_b64 v[18:19], v41 offset:128
	s_mov_b32 s27, s58
	s_waitcnt lgkmcnt(0)
	v_pk_fma_f32 v[16:17], v[88:89], v[18:19], v[16:17] op_sel_hi:[1,0,1]
	v_pk_fma_f32 v[14:15], v[86:87], v[18:19], v[14:15] op_sel_hi:[1,0,1] neg_lo:[1,0,0] neg_hi:[1,0,0]
	v_pk_fma_f32 v[16:17], v[18:19], v[16:17], v[80:81] op_sel:[1,0,0]
	v_pk_fma_f32 v[14:15], v[18:19], v[14:15], v[78:79] op_sel:[1,0,0]
	v_mul_f32_e32 v22, 0xbfb8aa3b, v16
	v_mul_f32_e32 v20, 0xbfb8aa3b, v14
	v_mul_f32_e32 v21, 0xbfb8aa3b, v15
	v_mul_f32_e32 v23, 0xbfb8aa3b, v17
	v_exp_f32_e32 v20, v20
	v_exp_f32_e32 v21, v21
	v_exp_f32_e32 v22, v22
	v_exp_f32_e32 v23, v23
	v_add_f32_e32 v20, 1.0, v20
	v_add_f32_e32 v21, 1.0, v21
	v_add_f32_e32 v22, 1.0, v22
	v_add_f32_e32 v23, 1.0, v23
	v_rcp_f32_e32 v20, v20
	v_rcp_f32_e32 v21, v21
	v_rcp_f32_e32 v22, v22
	v_rcp_f32_e32 v23, v23
	v_pk_fma_f32 v[12:13], v[96:97], v[18:19], v[12:13] op_sel_hi:[1,0,1]
	v_pk_fma_f32 v[10:11], v[94:95], v[18:19], v[10:11] op_sel_hi:[1,0,1] neg_lo:[1,0,0] neg_hi:[1,0,0]
	v_pk_fma_f32 v[8:9], v[64:65], v[18:19], v[8:9] op_sel_hi:[1,0,1]
	v_pk_fma_f32 v[6:7], v[62:63], v[18:19], v[6:7] op_sel_hi:[1,0,1] neg_lo:[1,0,0] neg_hi:[1,0,0]
	v_pk_fma_f32 v[12:13], v[18:19], v[12:13], v[92:93] op_sel:[1,0,0]
	v_pk_fma_f32 v[10:11], v[18:19], v[10:11], v[90:91] op_sel:[1,0,0]
	v_pk_mul_f32 v[16:17], v[16:17], v[22:23]
	v_pk_mul_f32 v[14:15], v[14:15], v[20:21]
	v_pk_fma_f32 v[8:9], v[18:19], v[8:9], v[60:61] op_sel:[1,0,0]
	v_pk_fma_f32 v[6:7], v[18:19], v[6:7], v[58:59] op_sel:[1,0,0]
	v_pk_mul_f32 v[12:13], v[12:13], v[16:17]
	v_pk_mul_f32 v[10:11], v[10:11], v[14:15]
	v_mul_f32_e32 v14, 0xbfb8aa3b, v6
	v_mul_f32_e32 v15, 0xbfb8aa3b, v7
	v_mul_f32_e32 v16, 0xbfb8aa3b, v8
	v_mul_f32_e32 v17, 0xbfb8aa3b, v9
	v_exp_f32_e32 v14, v14
	v_exp_f32_e32 v15, v15
	v_exp_f32_e32 v16, v16
	v_exp_f32_e32 v17, v17
	v_add_f32_e32 v14, 1.0, v14
	v_add_f32_e32 v15, 1.0, v15
	v_add_f32_e32 v16, 1.0, v16
	v_add_f32_e32 v17, 1.0, v17
	v_rcp_f32_e32 v14, v14
	v_rcp_f32_e32 v15, v15
	v_rcp_f32_e32 v16, v16
	v_rcp_f32_e32 v17, v17
	v_pk_fma_f32 v[4:5], v[68:69], v[18:19], v[4:5] op_sel_hi:[1,0,1]
	v_pk_fma_f32 v[2:3], v[66:67], v[18:19], v[2:3] op_sel_hi:[1,0,1] neg_lo:[1,0,0] neg_hi:[1,0,0]
	v_pk_fma_f32 v[4:5], v[18:19], v[4:5], v[72:73] op_sel:[1,0,0]
	v_pk_fma_f32 v[2:3], v[18:19], v[2:3], v[70:71] op_sel:[1,0,0]
	v_pk_mul_f32 v[8:9], v[8:9], v[16:17]
	v_pk_mul_f32 v[6:7], v[6:7], v[14:15]
	v_pk_mul_f32 v[8:9], v[4:5], v[8:9]
	v_pk_mul_f32 v[4:5], v[2:3], v[6:7]
	v_add_lshl_u32 v6, v30, v130, 1
	v_cvt_pk_bf16_f32 v2, v10, v11
	v_cvt_pk_bf16_f32 v3, v12, v13
	v_cvt_pk_bf16_f32 v4, v4, v5
	v_cvt_pk_bf16_f32 v5, v8, v9
	buffer_store_dwordx4 v[2:5], v6, s[28:31], 0 offen sc1
	s_cbranch_vccz .LBB0_1098
	s_waitcnt vmcnt(0)
	v_readlane_b32 s76, v255, 13
	s_cmpk_gt_u32 s38, 0xff
	v_readlane_b32 s77, v255, 14
	s_cbranch_scc1 .LBB0_1103
	s_barrier

.LBB0_1174:
	s_cmp_ge_u32 s79, 0x1000
	s_cbranch_scc0 .Lprio_done_1
	s_setprio 1

.LBB0_1178:
	s_add_u32 s27, s36, 0x100
	s_addc_u32 s91, s37, 0
	s_add_u32 s36, s42, 0x80
	s_addc_u32 s37, s43, 0
	s_mov_b32 s42, 0
	s_waitcnt lgkmcnt(0)
	s_add_i32 s92, s42, 2
	s_add_u32 s72, s36, 0x80
	s_addc_u32 s43, s37, 0
	s_add_i32 s93, 0, 0x10000
	v_add_u32_e32 v1, s93, v223
	ds_read_b128 v[50:53], v1
	ds_read_b128 v[54:57], v1 offset:1024
	ds_read_b128 v[58:61], v1 offset:2048
	ds_read_b128 v[62:65], v1 offset:3072
	s_cmp_eq_u32 s88, s42
	s_cselect_b32 s42, s66, s72
	s_cselect_b32 s43, s67, s43
	s_cselect_b32 s73, s71, s91
	s_cselect_b32 s72, s70, s27
	v_lshl_add_u64 v[178:179], s[36:37], 0, v[206:207]
	s_add_i32 m0, s79, 0xc000
	ds_read_b128 v[66:69], v230
	ds_read_b128 v[70:73], v230 offset:1024
	ds_read_b128 v[74:77], v230 offset:2048
	ds_read_b128 v[78:81], v230 offset:3072
	ds_read_b128 v[146:149], v230 offset:4096
	ds_read_b128 v[154:157], v230 offset:5120
	ds_read_b128 v[170:173], v230 offset:6144
	ds_read_b128 v[174:177], v230 offset:7168
	global_load_lds_dwordx4 v[178:179], off
	v_lshl_add_u64 v[178:179], s[36:37], 0, v[204:205]
	s_add_i32 m0, s79, 0xe000
	s_nop 0
	global_load_lds_dwordx4 v[178:179], off
	s_waitcnt lgkmcnt(8)
	s_barrier
	s_waitcnt lgkmcnt(0)
	s_waitcnt lgkmcnt(0)
	v_mfma_f32_16x16x32_bf16 v[166:169], v[50:53], v[66:69], 0
	v_mfma_f32_16x16x32_bf16 v[162:165], v[58:61], v[66:69], 0
	v_mfma_f32_16x16x32_bf16 v[142:145], v[50:53], v[74:77], 0
	v_mfma_f32_16x16x32_bf16 v[138:141], v[58:61], v[74:77], 0
	v_mfma_f32_16x16x32_bf16 v[126:129], v[50:53], v[146:149], 0
	v_mfma_f32_16x16x32_bf16 v[122:125], v[58:61], v[146:149], 0
	v_mfma_f32_16x16x32_bf16 v[110:113], v[50:53], v[170:173], 0
	v_mfma_f32_16x16x32_bf16 v[106:109], v[58:61], v[170:173], 0
	v_mfma_f32_16x16x32_bf16 v[166:169], v[54:57], v[70:73], v[166:169]
	v_mfma_f32_16x16x32_bf16 v[162:165], v[62:65], v[70:73], v[162:165]
	v_mfma_f32_16x16x32_bf16 v[142:145], v[54:57], v[78:81], v[142:145]
	v_mfma_f32_16x16x32_bf16 v[138:141], v[62:65], v[78:81], v[138:141]
	v_mfma_f32_16x16x32_bf16 v[126:129], v[54:57], v[154:157], v[126:129]
	v_mfma_f32_16x16x32_bf16 v[122:125], v[62:65], v[154:157], v[122:125]
	v_mfma_f32_16x16x32_bf16 v[110:113], v[54:57], v[174:177], v[110:113]
	v_mfma_f32_16x16x32_bf16 v[106:109], v[62:65], v[174:177], v[106:109]
	s_barrier
	s_add_i32 s94, 0, 0x14000
	s_add_i32 s93, s93, s78
	v_add_u32_e32 v1, s94, v223
	v_lshl_add_u64 v[214:215], s[72:73], 0, v[202:203]
	s_mov_b32 m0, s93
	ds_read_b128 v[178:181], v1
	ds_read_b128 v[182:185], v1 offset:1024
	ds_read_b128 v[186:189], v1 offset:2048
	ds_read_b128 v[190:193], v1 offset:3072
	global_load_lds_dwordx4 v[214:215], off
	v_lshl_add_u64 v[236:237], s[72:73], 0, v[200:201]
	s_add_i32 m0, s93, 0x2000
	s_nop 0
	global_load_lds_dwordx4 v[236:237], off
	s_barrier
	s_waitcnt lgkmcnt(0)
	s_waitcnt lgkmcnt(0)
	v_mfma_f32_16x16x32_bf16 v[158:161], v[178:181], v[66:69], 0
	v_mfma_f32_16x16x32_bf16 v[66:69], v[186:189], v[66:69], 0
	v_mfma_f32_16x16x32_bf16 v[158:161], v[182:185], v[70:73], v[158:161]
	v_mfma_f32_16x16x32_bf16 v[66:69], v[190:193], v[70:73], v[66:69]
	v_mfma_f32_16x16x32_bf16 v[70:73], v[178:181], v[74:77], 0
	v_mfma_f32_16x16x32_bf16 v[74:77], v[186:189], v[74:77], 0
	v_mfma_f32_16x16x32_bf16 v[114:117], v[186:189], v[146:149], 0
	v_mfma_f32_16x16x32_bf16 v[102:105], v[178:181], v[170:173], 0
	v_mfma_f32_16x16x32_bf16 v[98:101], v[186:189], v[170:173], 0
	v_mfma_f32_16x16x32_bf16 v[70:73], v[182:185], v[78:81], v[70:73]
	v_mfma_f32_16x16x32_bf16 v[74:77], v[190:193], v[78:81], v[74:77]
	v_mfma_f32_16x16x32_bf16 v[78:81], v[178:181], v[146:149], 0
	v_mfma_f32_16x16x32_bf16 v[114:117], v[190:193], v[154:157], v[114:117]
	v_mfma_f32_16x16x32_bf16 v[102:105], v[182:185], v[174:177], v[102:105]
	v_mfma_f32_16x16x32_bf16 v[98:101], v[190:193], v[174:177], v[98:101]
	v_mfma_f32_16x16x32_bf16 v[78:81], v[182:185], v[154:157], v[78:81]
	s_mov_b32 m0, s79
	v_lshl_add_u64 v[238:239], s[42:43], 0, v[202:203]
	s_barrier
	ds_read_b128 v[118:121], v230 offset:16384
	ds_read_b128 v[130:133], v230 offset:17408
	ds_read_b128 v[134:137], v230 offset:18432
	ds_read_b128 v[146:149], v230 offset:19456
	ds_read_b128 v[150:153], v230 offset:20480
	ds_read_b128 v[154:157], v230 offset:21504
	ds_read_b128 v[170:173], v230 offset:22528
	ds_read_b128 v[174:177], v230 offset:23552
	global_load_lds_dwordx4 v[238:239], off
	v_lshl_add_u64 v[240:241], s[42:43], 0, v[200:201]
	s_mov_b32 m0, s80
	s_nop 0
	global_load_lds_dwordx4 v[240:241], off
	s_barrier
	s_waitcnt lgkmcnt(0)
	s_waitcnt lgkmcnt(0)
	v_mfma_f32_16x16x32_bf16 v[94:97], v[50:53], v[118:121], 0
	v_mfma_f32_16x16x32_bf16 v[90:93], v[58:61], v[118:121], 0
	v_mfma_f32_16x16x32_bf16 v[46:49], v[50:53], v[134:137], 0
	v_mfma_f32_16x16x32_bf16 v[42:45], v[58:61], v[134:137], 0
	v_mfma_f32_16x16x32_bf16 v[30:33], v[50:53], v[150:153], 0
	v_mfma_f32_16x16x32_bf16 v[26:29], v[58:61], v[150:153], 0
	v_mfma_f32_16x16x32_bf16 v[14:17], v[50:53], v[170:173], 0
	v_mfma_f32_16x16x32_bf16 v[10:13], v[58:61], v[170:173], 0
	v_mfma_f32_16x16x32_bf16 v[94:97], v[54:57], v[130:133], v[94:97]
	v_mfma_f32_16x16x32_bf16 v[90:93], v[62:65], v[130:133], v[90:93]
	v_mfma_f32_16x16x32_bf16 v[46:49], v[54:57], v[146:149], v[46:49]
	v_mfma_f32_16x16x32_bf16 v[42:45], v[62:65], v[146:149], v[42:45]
	v_mfma_f32_16x16x32_bf16 v[30:33], v[54:57], v[154:157], v[30:33]
	v_mfma_f32_16x16x32_bf16 v[26:29], v[62:65], v[154:157], v[26:29]
	v_mfma_f32_16x16x32_bf16 v[14:17], v[54:57], v[174:177], v[14:17]
	v_mfma_f32_16x16x32_bf16 v[10:13], v[62:65], v[174:177], v[10:13]
	s_barrier
	s_add_u32 s72, s72, s4
	s_addc_u32 s73, s73, 0
	s_add_i32 s93, s94, s78
	v_lshl_add_u64 v[242:243], s[72:73], 0, v[202:203]
	s_mov_b32 m0, s93
	v_lshl_add_u64 v[244:245], s[72:73], 0, v[200:201]
	global_load_lds_dwordx4 v[242:243], off
	s_add_i32 m0, s93, 0x2000
	s_nop 0
	global_load_lds_dwordx4 v[244:245], off
	s_waitcnt vmcnt(6)
	s_barrier
	v_mfma_f32_16x16x32_bf16 v[38:41], v[178:181], v[134:137], 0
	v_mfma_f32_16x16x32_bf16 v[34:37], v[186:189], v[134:137], 0
	v_mfma_f32_16x16x32_bf16 v[22:25], v[178:181], v[150:153], 0
	v_mfma_f32_16x16x32_bf16 v[18:21], v[186:189], v[150:153], 0
	v_mfma_f32_16x16x32_bf16 v[6:9], v[178:181], v[170:173], 0
	v_mfma_f32_16x16x32_bf16 v[2:5], v[186:189], v[170:173], 0
	v_mfma_f32_16x16x32_bf16 v[50:53], v[178:181], v[118:121], 0
	v_mfma_f32_16x16x32_bf16 v[54:57], v[186:189], v[118:121], 0
	v_mfma_f32_16x16x32_bf16 v[38:41], v[182:185], v[146:149], v[38:41]
	v_mfma_f32_16x16x32_bf16 v[34:37], v[190:193], v[146:149], v[34:37]
	v_mfma_f32_16x16x32_bf16 v[22:25], v[182:185], v[154:157], v[22:25]
	v_mfma_f32_16x16x32_bf16 v[18:21], v[190:193], v[154:157], v[18:21]
	v_mfma_f32_16x16x32_bf16 v[6:9], v[182:185], v[174:177], v[6:9]
	v_mfma_f32_16x16x32_bf16 v[2:5], v[190:193], v[174:177], v[2:5]
	v_mfma_f32_16x16x32_bf16 v[50:53], v[182:185], v[130:133], v[50:53]
	v_mfma_f32_16x16x32_bf16 v[54:57], v[190:193], v[130:133], v[54:57]
	s_add_i32 s72, 0, 0x18000
	v_add_u32_e32 v1, s72, v223
	s_barrier
	ds_read_b128 v[58:61], v1
	ds_read_b128 v[62:65], v1 offset:1024
	ds_read_b128 v[82:85], v1 offset:2048
	ds_read_b128 v[86:89], v1 offset:3072
	s_add_u32 s42, s42, s4
	s_addc_u32 s43, s43, 0
	s_mov_b32 m0, s81
	v_lshl_add_u64 v[134:135], s[42:43], 0, v[202:203]
	ds_read_b128 v[118:121], v230 offset:32768
	ds_read_b128 v[130:133], v230 offset:33792
	ds_read_b128 v[146:149], v230 offset:34816
	ds_read_b128 v[154:157], v230 offset:35840
	ds_read_b128 v[170:173], v230 offset:36864
	ds_read_b128 v[174:177], v230 offset:37888
	ds_read_b128 v[178:181], v230 offset:38912
	ds_read_b128 v[182:185], v230 offset:39936
	global_load_lds_dwordx4 v[134:135], off
	v_lshl_add_u64 v[134:135], s[42:43], 0, v[200:201]
	s_mov_b32 m0, s82
	s_nop 0
	global_load_lds_dwordx4 v[134:135], off
	s_waitcnt lgkmcnt(8)
	s_barrier
	s_waitcnt lgkmcnt(0)
	s_waitcnt lgkmcnt(0)
	v_mfma_f32_16x16x32_bf16 v[134:137], v[58:61], v[118:121], v[166:169]
	v_mfma_f32_16x16x32_bf16 v[166:169], v[62:65], v[130:133], v[134:137]
	v_mfma_f32_16x16x32_bf16 v[134:137], v[82:85], v[118:121], v[162:165]
	v_mfma_f32_16x16x32_bf16 v[162:165], v[86:89], v[130:133], v[134:137]
	v_mfma_f32_16x16x32_bf16 v[134:137], v[58:61], v[146:149], v[142:145]
	v_mfma_f32_16x16x32_bf16 v[142:145], v[62:65], v[154:157], v[134:137]
	v_mfma_f32_16x16x32_bf16 v[134:137], v[82:85], v[146:149], v[138:141]
	v_mfma_f32_16x16x32_bf16 v[126:129], v[58:61], v[170:173], v[126:129]
	v_mfma_f32_16x16x32_bf16 v[122:125], v[82:85], v[170:173], v[122:125]
	v_mfma_f32_16x16x32_bf16 v[110:113], v[58:61], v[178:181], v[110:113]
	v_mfma_f32_16x16x32_bf16 v[106:109], v[82:85], v[178:181], v[106:109]
	v_mfma_f32_16x16x32_bf16 v[138:141], v[86:89], v[154:157], v[134:137]
	v_mfma_f32_16x16x32_bf16 v[126:129], v[62:65], v[174:177], v[126:129]
	v_mfma_f32_16x16x32_bf16 v[122:125], v[86:89], v[174:177], v[122:125]
	v_mfma_f32_16x16x32_bf16 v[110:113], v[62:65], v[182:185], v[110:113]
	v_mfma_f32_16x16x32_bf16 v[106:109], v[86:89], v[182:185], v[106:109]
	s_barrier
	s_add_i32 s42, 0, 0x1c000
	s_add_i32 s43, s72, s78
	v_add_u32_e32 v1, s42, v223
	v_lshl_add_u64 v[134:135], v[214:215], 0, s[22:23]
	s_mov_b32 m0, s43
	ds_read_b128 v[186:189], v1
	ds_read_b128 v[190:193], v1 offset:1024
	ds_read_b128 v[208:211], v1 offset:2048
	ds_read_b128 v[232:235], v1 offset:3072
	global_load_lds_dwordx4 v[134:135], off
	v_lshl_add_u64 v[134:135], v[236:237], 0, s[22:23]
	s_add_i32 m0, s43, 0x2000
	s_nop 0
	global_load_lds_dwordx4 v[134:135], off
	s_barrier
	s_waitcnt lgkmcnt(0)
	s_waitcnt lgkmcnt(0)
	v_mfma_f32_16x16x32_bf16 v[66:69], v[208:211], v[118:121], v[66:69]
	v_mfma_f32_16x16x32_bf16 v[134:137], v[186:189], v[118:121], v[158:161]
	v_mfma_f32_16x16x32_bf16 v[150:153], v[232:235], v[130:133], v[66:69]
	v_mfma_f32_16x16x32_bf16 v[66:69], v[186:189], v[146:149], v[70:73]
	v_mfma_f32_16x16x32_bf16 v[158:161], v[190:193], v[130:133], v[134:137]
	v_mfma_f32_16x16x32_bf16 v[134:137], v[190:193], v[154:157], v[66:69]
	v_mfma_f32_16x16x32_bf16 v[66:69], v[208:211], v[146:149], v[74:77]
	v_mfma_f32_16x16x32_bf16 v[130:133], v[232:235], v[154:157], v[66:69]
	v_mfma_f32_16x16x32_bf16 v[66:69], v[186:189], v[170:173], v[78:81]
	v_mfma_f32_16x16x32_bf16 v[118:121], v[190:193], v[174:177], v[66:69]
	v_mfma_f32_16x16x32_bf16 v[66:69], v[208:211], v[170:173], v[114:117]
	v_mfma_f32_16x16x32_bf16 v[114:117], v[232:235], v[174:177], v[66:69]
	v_mfma_f32_16x16x32_bf16 v[66:69], v[186:189], v[178:181], v[102:105]
	v_mfma_f32_16x16x32_bf16 v[102:105], v[190:193], v[182:185], v[66:69]
	v_mfma_f32_16x16x32_bf16 v[66:69], v[208:211], v[178:181], v[98:101]
	v_mfma_f32_16x16x32_bf16 v[98:101], v[232:235], v[182:185], v[66:69]
	s_mov_b32 m0, s86
	v_lshl_add_u64 v[178:179], v[238:239], 0, s[22:23]
	s_barrier
	s_nop 2
	ds_read_b128 v[66:69], v230 offset:49152
	ds_read_b128 v[70:73], v230 offset:50176
	ds_read_b128 v[74:77], v230 offset:51200
	ds_read_b128 v[78:81], v230 offset:52224
	ds_read_b128 v[146:149], v230 offset:53248
	ds_read_b128 v[154:157], v230 offset:54272
	ds_read_b128 v[170:173], v230 offset:55296
	ds_read_b128 v[174:177], v230 offset:56320
	global_load_lds_dwordx4 v[178:179], off
	v_lshl_add_u64 v[178:179], v[240:241], 0, s[22:23]
	s_mov_b32 m0, s87
	s_nop 0
	global_load_lds_dwordx4 v[178:179], off
	s_barrier
	s_waitcnt lgkmcnt(0)
	s_waitcnt lgkmcnt(0)
	v_mfma_f32_16x16x32_bf16 v[94:97], v[58:61], v[66:69], v[94:97]
	v_mfma_f32_16x16x32_bf16 v[90:93], v[82:85], v[66:69], v[90:93]
	v_mfma_f32_16x16x32_bf16 v[46:49], v[58:61], v[74:77], v[46:49]
	v_mfma_f32_16x16x32_bf16 v[42:45], v[82:85], v[74:77], v[42:45]
	v_mfma_f32_16x16x32_bf16 v[30:33], v[58:61], v[146:149], v[30:33]
	v_mfma_f32_16x16x32_bf16 v[26:29], v[82:85], v[146:149], v[26:29]
	v_mfma_f32_16x16x32_bf16 v[14:17], v[58:61], v[170:173], v[14:17]
	v_mfma_f32_16x16x32_bf16 v[10:13], v[82:85], v[170:173], v[10:13]
	v_mfma_f32_16x16x32_bf16 v[94:97], v[62:65], v[70:73], v[94:97]
	v_mfma_f32_16x16x32_bf16 v[90:93], v[86:89], v[70:73], v[90:93]
	v_mfma_f32_16x16x32_bf16 v[46:49], v[62:65], v[78:81], v[46:49]
	v_mfma_f32_16x16x32_bf16 v[42:45], v[86:89], v[78:81], v[42:45]
	v_mfma_f32_16x16x32_bf16 v[30:33], v[62:65], v[154:157], v[30:33]
	v_mfma_f32_16x16x32_bf16 v[26:29], v[86:89], v[154:157], v[26:29]
	v_mfma_f32_16x16x32_bf16 v[14:17], v[62:65], v[174:177], v[14:17]
	v_mfma_f32_16x16x32_bf16 v[10:13], v[86:89], v[174:177], v[10:13]
	s_barrier
	s_add_i32 s42, s42, s78
	v_lshl_add_u64 v[58:59], v[242:243], 0, s[22:23]
	s_mov_b32 m0, s42
	s_nop 0
	global_load_lds_dwordx4 v[58:59], off
	v_lshl_add_u64 v[58:59], v[244:245], 0, s[22:23]
	s_add_i32 m0, s42, 0x2000
	s_nop 0
	global_load_lds_dwordx4 v[58:59], off
	s_waitcnt vmcnt(6)
	s_barrier
	v_mfma_f32_16x16x32_bf16 v[50:53], v[186:189], v[66:69], v[50:53]
	v_mfma_f32_16x16x32_bf16 v[86:89], v[190:193], v[70:73], v[50:53]
	v_mfma_f32_16x16x32_bf16 v[50:53], v[208:211], v[66:69], v[54:57]
	v_mfma_f32_16x16x32_bf16 v[38:41], v[186:189], v[74:77], v[38:41]
	v_mfma_f32_16x16x32_bf16 v[34:37], v[208:211], v[74:77], v[34:37]
	v_mfma_f32_16x16x32_bf16 v[22:25], v[186:189], v[146:149], v[22:25]
	v_mfma_f32_16x16x32_bf16 v[18:21], v[208:211], v[146:149], v[18:21]
	v_mfma_f32_16x16x32_bf16 v[6:9], v[186:189], v[170:173], v[6:9]
	v_mfma_f32_16x16x32_bf16 v[2:5], v[208:211], v[170:173], v[2:5]
	v_mfma_f32_16x16x32_bf16 v[82:85], v[232:235], v[70:73], v[50:53]
	v_mfma_f32_16x16x32_bf16 v[38:41], v[190:193], v[78:81], v[38:41]
	v_mfma_f32_16x16x32_bf16 v[34:37], v[232:235], v[78:81], v[34:37]
	v_mfma_f32_16x16x32_bf16 v[22:25], v[190:193], v[154:157], v[22:25]
	v_mfma_f32_16x16x32_bf16 v[18:21], v[232:235], v[154:157], v[18:21]
	v_mfma_f32_16x16x32_bf16 v[6:9], v[190:193], v[174:177], v[6:9]
	v_mfma_f32_16x16x32_bf16 v[2:5], v[232:235], v[174:177], v[2:5]
	s_add_u32 s27, s27, 0x100
	s_addc_u32 s91, s91, 0
	s_add_u32 s36, s36, 0x100
	s_addc_u32 s37, s37, 0
	s_cmp_ge_u32 s92, s84
	s_mov_b32 s42, s92
	s_barrier
.LBB0_1179:
	s_add_i32 s92, s42, 2
	s_add_u32 s72, s36, 0x80
	s_addc_u32 s43, s37, 0
	s_add_i32 s93, 0, 0x10000
	v_add_u32_e32 v1, s93, v223
	ds_read_b128 v[50:53], v1
	ds_read_b128 v[54:57], v1 offset:1024
	ds_read_b128 v[58:61], v1 offset:2048
	ds_read_b128 v[62:65], v1 offset:3072
	s_cmp_eq_u32 s88, s42
	s_cselect_b32 s42, s66, s72
	s_cselect_b32 s43, s67, s43
	s_cselect_b32 s73, s71, s91
	s_cselect_b32 s72, s70, s27
	v_lshl_add_u64 v[178:179], s[36:37], 0, v[206:207]
	s_add_i32 m0, s79, 0xc000
	ds_read_b128 v[66:69], v230
	ds_read_b128 v[70:73], v230 offset:1024
	ds_read_b128 v[74:77], v230 offset:2048
	ds_read_b128 v[78:81], v230 offset:3072
	ds_read_b128 v[146:149], v230 offset:4096
	ds_read_b128 v[154:157], v230 offset:5120
	ds_read_b128 v[170:173], v230 offset:6144
	ds_read_b128 v[174:177], v230 offset:7168
	global_load_lds_dwordx4 v[178:179], off
	v_lshl_add_u64 v[178:179], s[36:37], 0, v[204:205]
	s_add_i32 m0, s79, 0xe000
	s_nop 0
	global_load_lds_dwordx4 v[178:179], off
	s_waitcnt lgkmcnt(8)
	s_barrier
	s_waitcnt lgkmcnt(0)
	s_waitcnt lgkmcnt(0)
	v_mfma_f32_16x16x32_bf16 v[166:169], v[50:53], v[66:69], v[166:169]
	v_mfma_f32_16x16x32_bf16 v[162:165], v[58:61], v[66:69], v[162:165]
	v_mfma_f32_16x16x32_bf16 v[142:145], v[50:53], v[74:77], v[142:145]
	v_mfma_f32_16x16x32_bf16 v[138:141], v[58:61], v[74:77], v[138:141]
	v_mfma_f32_16x16x32_bf16 v[126:129], v[50:53], v[146:149], v[126:129]
	v_mfma_f32_16x16x32_bf16 v[122:125], v[58:61], v[146:149], v[122:125]
	v_mfma_f32_16x16x32_bf16 v[110:113], v[50:53], v[170:173], v[110:113]
	v_mfma_f32_16x16x32_bf16 v[106:109], v[58:61], v[170:173], v[106:109]
	v_mfma_f32_16x16x32_bf16 v[166:169], v[54:57], v[70:73], v[166:169]
	v_mfma_f32_16x16x32_bf16 v[162:165], v[62:65], v[70:73], v[162:165]
	v_mfma_f32_16x16x32_bf16 v[142:145], v[54:57], v[78:81], v[142:145]
	v_mfma_f32_16x16x32_bf16 v[138:141], v[62:65], v[78:81], v[138:141]
	v_mfma_f32_16x16x32_bf16 v[126:129], v[54:57], v[154:157], v[126:129]
	v_mfma_f32_16x16x32_bf16 v[122:125], v[62:65], v[154:157], v[122:125]
	v_mfma_f32_16x16x32_bf16 v[110:113], v[54:57], v[174:177], v[110:113]
	v_mfma_f32_16x16x32_bf16 v[106:109], v[62:65], v[174:177], v[106:109]
	s_barrier
	s_add_i32 s94, 0, 0x14000
	s_add_i32 s93, s93, s78
	v_add_u32_e32 v1, s94, v223
	v_lshl_add_u64 v[214:215], s[72:73], 0, v[202:203]
	s_mov_b32 m0, s93
	ds_read_b128 v[178:181], v1
	ds_read_b128 v[182:185], v1 offset:1024
	ds_read_b128 v[186:189], v1 offset:2048
	ds_read_b128 v[190:193], v1 offset:3072
	global_load_lds_dwordx4 v[214:215], off
	v_lshl_add_u64 v[236:237], s[72:73], 0, v[200:201]
	s_add_i32 m0, s93, 0x2000
	s_nop 0
	global_load_lds_dwordx4 v[236:237], off
	s_barrier
	s_waitcnt lgkmcnt(0)
	s_waitcnt lgkmcnt(0)
	v_mfma_f32_16x16x32_bf16 v[158:161], v[178:181], v[66:69], v[158:161]
	v_mfma_f32_16x16x32_bf16 v[66:69], v[186:189], v[66:69], v[150:153]
	v_mfma_f32_16x16x32_bf16 v[158:161], v[182:185], v[70:73], v[158:161]
	v_mfma_f32_16x16x32_bf16 v[66:69], v[190:193], v[70:73], v[66:69]
	v_mfma_f32_16x16x32_bf16 v[70:73], v[178:181], v[74:77], v[134:137]
	v_mfma_f32_16x16x32_bf16 v[74:77], v[186:189], v[74:77], v[130:133]
	v_mfma_f32_16x16x32_bf16 v[114:117], v[186:189], v[146:149], v[114:117]
	v_mfma_f32_16x16x32_bf16 v[102:105], v[178:181], v[170:173], v[102:105]
	v_mfma_f32_16x16x32_bf16 v[98:101], v[186:189], v[170:173], v[98:101]
	v_mfma_f32_16x16x32_bf16 v[70:73], v[182:185], v[78:81], v[70:73]
	v_mfma_f32_16x16x32_bf16 v[74:77], v[190:193], v[78:81], v[74:77]
	v_mfma_f32_16x16x32_bf16 v[78:81], v[178:181], v[146:149], v[118:121]
	v_mfma_f32_16x16x32_bf16 v[114:117], v[190:193], v[154:157], v[114:117]
	v_mfma_f32_16x16x32_bf16 v[102:105], v[182:185], v[174:177], v[102:105]
	v_mfma_f32_16x16x32_bf16 v[98:101], v[190:193], v[174:177], v[98:101]
	v_mfma_f32_16x16x32_bf16 v[78:81], v[182:185], v[154:157], v[78:81]
	s_mov_b32 m0, s79
	v_lshl_add_u64 v[238:239], s[42:43], 0, v[202:203]
	s_barrier
	ds_read_b128 v[118:121], v230 offset:16384
	ds_read_b128 v[130:133], v230 offset:17408
	ds_read_b128 v[134:137], v230 offset:18432
	ds_read_b128 v[146:149], v230 offset:19456
	ds_read_b128 v[150:153], v230 offset:20480
	ds_read_b128 v[154:157], v230 offset:21504
	ds_read_b128 v[170:173], v230 offset:22528
	ds_read_b128 v[174:177], v230 offset:23552
	global_load_lds_dwordx4 v[238:239], off
	v_lshl_add_u64 v[240:241], s[42:43], 0, v[200:201]
	s_mov_b32 m0, s80
	s_nop 0
	global_load_lds_dwordx4 v[240:241], off
	s_barrier
	s_waitcnt lgkmcnt(0)
	s_waitcnt lgkmcnt(0)
	v_mfma_f32_16x16x32_bf16 v[94:97], v[50:53], v[118:121], v[94:97]
	v_mfma_f32_16x16x32_bf16 v[90:93], v[58:61], v[118:121], v[90:93]
	v_mfma_f32_16x16x32_bf16 v[46:49], v[50:53], v[134:137], v[46:49]
	v_mfma_f32_16x16x32_bf16 v[42:45], v[58:61], v[134:137], v[42:45]
	v_mfma_f32_16x16x32_bf16 v[30:33], v[50:53], v[150:153], v[30:33]
	v_mfma_f32_16x16x32_bf16 v[26:29], v[58:61], v[150:153], v[26:29]
	v_mfma_f32_16x16x32_bf16 v[14:17], v[50:53], v[170:173], v[14:17]
	v_mfma_f32_16x16x32_bf16 v[10:13], v[58:61], v[170:173], v[10:13]
	v_mfma_f32_16x16x32_bf16 v[94:97], v[54:57], v[130:133], v[94:97]
	v_mfma_f32_16x16x32_bf16 v[90:93], v[62:65], v[130:133], v[90:93]
	v_mfma_f32_16x16x32_bf16 v[46:49], v[54:57], v[146:149], v[46:49]
	v_mfma_f32_16x16x32_bf16 v[42:45], v[62:65], v[146:149], v[42:45]
	v_mfma_f32_16x16x32_bf16 v[30:33], v[54:57], v[154:157], v[30:33]
	v_mfma_f32_16x16x32_bf16 v[26:29], v[62:65], v[154:157], v[26:29]
	v_mfma_f32_16x16x32_bf16 v[14:17], v[54:57], v[174:177], v[14:17]
	v_mfma_f32_16x16x32_bf16 v[10:13], v[62:65], v[174:177], v[10:13]
	s_barrier
	s_add_u32 s72, s72, s4
	s_addc_u32 s73, s73, 0
	s_add_i32 s93, s94, s78
	v_lshl_add_u64 v[242:243], s[72:73], 0, v[202:203]
	s_mov_b32 m0, s93
	v_lshl_add_u64 v[244:245], s[72:73], 0, v[200:201]
	global_load_lds_dwordx4 v[242:243], off
	s_add_i32 m0, s93, 0x2000
	s_nop 0
	global_load_lds_dwordx4 v[244:245], off
	s_waitcnt vmcnt(6)
	s_barrier
	v_mfma_f32_16x16x32_bf16 v[38:41], v[178:181], v[134:137], v[38:41]
	v_mfma_f32_16x16x32_bf16 v[34:37], v[186:189], v[134:137], v[34:37]
	v_mfma_f32_16x16x32_bf16 v[22:25], v[178:181], v[150:153], v[22:25]
	v_mfma_f32_16x16x32_bf16 v[18:21], v[186:189], v[150:153], v[18:21]
	v_mfma_f32_16x16x32_bf16 v[6:9], v[178:181], v[170:173], v[6:9]
	v_mfma_f32_16x16x32_bf16 v[2:5], v[186:189], v[170:173], v[2:5]
	v_mfma_f32_16x16x32_bf16 v[50:53], v[178:181], v[118:121], v[86:89]
	v_mfma_f32_16x16x32_bf16 v[54:57], v[186:189], v[118:121], v[82:85]
	v_mfma_f32_16x16x32_bf16 v[38:41], v[182:185], v[146:149], v[38:41]
	v_mfma_f32_16x16x32_bf16 v[34:37], v[190:193], v[146:149], v[34:37]
	v_mfma_f32_16x16x32_bf16 v[22:25], v[182:185], v[154:157], v[22:25]
	v_mfma_f32_16x16x32_bf16 v[18:21], v[190:193], v[154:157], v[18:21]
	v_mfma_f32_16x16x32_bf16 v[6:9], v[182:185], v[174:177], v[6:9]
	v_mfma_f32_16x16x32_bf16 v[2:5], v[190:193], v[174:177], v[2:5]
	v_mfma_f32_16x16x32_bf16 v[50:53], v[182:185], v[130:133], v[50:53]
	v_mfma_f32_16x16x32_bf16 v[54:57], v[190:193], v[130:133], v[54:57]
	s_add_i32 s72, 0, 0x18000
	v_add_u32_e32 v1, s72, v223
	s_barrier
	ds_read_b128 v[58:61], v1
	ds_read_b128 v[62:65], v1 offset:1024
	ds_read_b128 v[82:85], v1 offset:2048
	ds_read_b128 v[86:89], v1 offset:3072
	s_add_u32 s42, s42, s4
	s_addc_u32 s43, s43, 0
	s_mov_b32 m0, s81
	v_lshl_add_u64 v[134:135], s[42:43], 0, v[202:203]
	ds_read_b128 v[118:121], v230 offset:32768
	ds_read_b128 v[130:133], v230 offset:33792
	ds_read_b128 v[146:149], v230 offset:34816
	ds_read_b128 v[154:157], v230 offset:35840
	ds_read_b128 v[170:173], v230 offset:36864
	ds_read_b128 v[174:177], v230 offset:37888
	ds_read_b128 v[178:181], v230 offset:38912
	ds_read_b128 v[182:185], v230 offset:39936
	global_load_lds_dwordx4 v[134:135], off
	v_lshl_add_u64 v[134:135], s[42:43], 0, v[200:201]
	s_mov_b32 m0, s82
	s_nop 0
	global_load_lds_dwordx4 v[134:135], off
	s_waitcnt lgkmcnt(8)
	s_barrier
	s_waitcnt lgkmcnt(0)
	s_waitcnt lgkmcnt(0)
	v_mfma_f32_16x16x32_bf16 v[134:137], v[58:61], v[118:121], v[166:169]
	v_mfma_f32_16x16x32_bf16 v[166:169], v[62:65], v[130:133], v[134:137]
	v_mfma_f32_16x16x32_bf16 v[134:137], v[82:85], v[118:121], v[162:165]
	v_mfma_f32_16x16x32_bf16 v[162:165], v[86:89], v[130:133], v[134:137]
	v_mfma_f32_16x16x32_bf16 v[134:137], v[58:61], v[146:149], v[142:145]
	v_mfma_f32_16x16x32_bf16 v[142:145], v[62:65], v[154:157], v[134:137]
	v_mfma_f32_16x16x32_bf16 v[134:137], v[82:85], v[146:149], v[138:141]
	v_mfma_f32_16x16x32_bf16 v[126:129], v[58:61], v[170:173], v[126:129]
	v_mfma_f32_16x16x32_bf16 v[122:125], v[82:85], v[170:173], v[122:125]
	v_mfma_f32_16x16x32_bf16 v[110:113], v[58:61], v[178:181], v[110:113]
	v_mfma_f32_16x16x32_bf16 v[106:109], v[82:85], v[178:181], v[106:109]
	v_mfma_f32_16x16x32_bf16 v[138:141], v[86:89], v[154:157], v[134:137]
	v_mfma_f32_16x16x32_bf16 v[126:129], v[62:65], v[174:177], v[126:129]
	v_mfma_f32_16x16x32_bf16 v[122:125], v[86:89], v[174:177], v[122:125]
	v_mfma_f32_16x16x32_bf16 v[110:113], v[62:65], v[182:185], v[110:113]
	v_mfma_f32_16x16x32_bf16 v[106:109], v[86:89], v[182:185], v[106:109]
	s_barrier
	s_add_i32 s42, 0, 0x1c000
	s_add_i32 s43, s72, s78
	v_add_u32_e32 v1, s42, v223
	v_lshl_add_u64 v[134:135], v[214:215], 0, s[22:23]
	s_mov_b32 m0, s43
	ds_read_b128 v[186:189], v1
	ds_read_b128 v[190:193], v1 offset:1024
	ds_read_b128 v[208:211], v1 offset:2048
	ds_read_b128 v[232:235], v1 offset:3072
	global_load_lds_dwordx4 v[134:135], off
	v_lshl_add_u64 v[134:135], v[236:237], 0, s[22:23]
	s_add_i32 m0, s43, 0x2000
	s_nop 0
	global_load_lds_dwordx4 v[134:135], off
	s_barrier
	s_waitcnt lgkmcnt(0)
	s_waitcnt lgkmcnt(0)
	v_mfma_f32_16x16x32_bf16 v[66:69], v[208:211], v[118:121], v[66:69]
	v_mfma_f32_16x16x32_bf16 v[134:137], v[186:189], v[118:121], v[158:161]
	v_mfma_f32_16x16x32_bf16 v[150:153], v[232:235], v[130:133], v[66:69]
	v_mfma_f32_16x16x32_bf16 v[66:69], v[186:189], v[146:149], v[70:73]
	v_mfma_f32_16x16x32_bf16 v[158:161], v[190:193], v[130:133], v[134:137]
	v_mfma_f32_16x16x32_bf16 v[134:137], v[190:193], v[154:157], v[66:69]
	v_mfma_f32_16x16x32_bf16 v[66:69], v[208:211], v[146:149], v[74:77]
	v_mfma_f32_16x16x32_bf16 v[130:133], v[232:235], v[154:157], v[66:69]
	v_mfma_f32_16x16x32_bf16 v[66:69], v[186:189], v[170:173], v[78:81]
	v_mfma_f32_16x16x32_bf16 v[118:121], v[190:193], v[174:177], v[66:69]
	v_mfma_f32_16x16x32_bf16 v[66:69], v[208:211], v[170:173], v[114:117]
	v_mfma_f32_16x16x32_bf16 v[114:117], v[232:235], v[174:177], v[66:69]
	v_mfma_f32_16x16x32_bf16 v[66:69], v[186:189], v[178:181], v[102:105]
	v_mfma_f32_16x16x32_bf16 v[102:105], v[190:193], v[182:185], v[66:69]
	v_mfma_f32_16x16x32_bf16 v[66:69], v[208:211], v[178:181], v[98:101]
	v_mfma_f32_16x16x32_bf16 v[98:101], v[232:235], v[182:185], v[66:69]
	s_mov_b32 m0, s86
	v_lshl_add_u64 v[178:179], v[238:239], 0, s[22:23]
	s_barrier
	s_nop 2
	ds_read_b128 v[66:69], v230 offset:49152
	ds_read_b128 v[70:73], v230 offset:50176
	ds_read_b128 v[74:77], v230 offset:51200
	ds_read_b128 v[78:81], v230 offset:52224
	ds_read_b128 v[146:149], v230 offset:53248
	ds_read_b128 v[154:157], v230 offset:54272
	ds_read_b128 v[170:173], v230 offset:55296
	ds_read_b128 v[174:177], v230 offset:56320
	global_load_lds_dwordx4 v[178:179], off
	v_lshl_add_u64 v[178:179], v[240:241], 0, s[22:23]
	s_mov_b32 m0, s87
	s_nop 0
	global_load_lds_dwordx4 v[178:179], off
	s_barrier
	s_waitcnt lgkmcnt(0)
	s_waitcnt lgkmcnt(0)
	v_mfma_f32_16x16x32_bf16 v[94:97], v[58:61], v[66:69], v[94:97]
	v_mfma_f32_16x16x32_bf16 v[90:93], v[82:85], v[66:69], v[90:93]
	v_mfma_f32_16x16x32_bf16 v[46:49], v[58:61], v[74:77], v[46:49]
	v_mfma_f32_16x16x32_bf16 v[42:45], v[82:85], v[74:77], v[42:45]
	v_mfma_f32_16x16x32_bf16 v[30:33], v[58:61], v[146:149], v[30:33]
	v_mfma_f32_16x16x32_bf16 v[26:29], v[82:85], v[146:149], v[26:29]
	v_mfma_f32_16x16x32_bf16 v[14:17], v[58:61], v[170:173], v[14:17]
	v_mfma_f32_16x16x32_bf16 v[10:13], v[82:85], v[170:173], v[10:13]
	v_mfma_f32_16x16x32_bf16 v[94:97], v[62:65], v[70:73], v[94:97]
	v_mfma_f32_16x16x32_bf16 v[90:93], v[86:89], v[70:73], v[90:93]
	v_mfma_f32_16x16x32_bf16 v[46:49], v[62:65], v[78:81], v[46:49]
	v_mfma_f32_16x16x32_bf16 v[42:45], v[86:89], v[78:81], v[42:45]
	v_mfma_f32_16x16x32_bf16 v[30:33], v[62:65], v[154:157], v[30:33]
	v_mfma_f32_16x16x32_bf16 v[26:29], v[86:89], v[154:157], v[26:29]
	v_mfma_f32_16x16x32_bf16 v[14:17], v[62:65], v[174:177], v[14:17]
	v_mfma_f32_16x16x32_bf16 v[10:13], v[86:89], v[174:177], v[10:13]
	s_barrier
	s_add_i32 s42, s42, s78
	v_lshl_add_u64 v[58:59], v[242:243], 0, s[22:23]
	s_mov_b32 m0, s42
	s_nop 0
	global_load_lds_dwordx4 v[58:59], off
	v_lshl_add_u64 v[58:59], v[244:245], 0, s[22:23]
	s_add_i32 m0, s42, 0x2000
	s_nop 0
	global_load_lds_dwordx4 v[58:59], off
	s_waitcnt vmcnt(6)
	s_barrier
	v_mfma_f32_16x16x32_bf16 v[50:53], v[186:189], v[66:69], v[50:53]
	v_mfma_f32_16x16x32_bf16 v[86:89], v[190:193], v[70:73], v[50:53]
	v_mfma_f32_16x16x32_bf16 v[50:53], v[208:211], v[66:69], v[54:57]
	v_mfma_f32_16x16x32_bf16 v[38:41], v[186:189], v[74:77], v[38:41]
	v_mfma_f32_16x16x32_bf16 v[34:37], v[208:211], v[74:77], v[34:37]
	v_mfma_f32_16x16x32_bf16 v[22:25], v[186:189], v[146:149], v[22:25]
	v_mfma_f32_16x16x32_bf16 v[18:21], v[208:211], v[146:149], v[18:21]
	v_mfma_f32_16x16x32_bf16 v[6:9], v[186:189], v[170:173], v[6:9]
	v_mfma_f32_16x16x32_bf16 v[2:5], v[208:211], v[170:173], v[2:5]
	v_mfma_f32_16x16x32_bf16 v[82:85], v[232:235], v[70:73], v[50:53]
	v_mfma_f32_16x16x32_bf16 v[38:41], v[190:193], v[78:81], v[38:41]
	v_mfma_f32_16x16x32_bf16 v[34:37], v[232:235], v[78:81], v[34:37]
	v_mfma_f32_16x16x32_bf16 v[22:25], v[190:193], v[154:157], v[22:25]
	v_mfma_f32_16x16x32_bf16 v[18:21], v[232:235], v[154:157], v[18:21]
	v_mfma_f32_16x16x32_bf16 v[6:9], v[190:193], v[174:177], v[6:9]
	v_mfma_f32_16x16x32_bf16 v[2:5], v[232:235], v[174:177], v[2:5]
	s_add_u32 s27, s27, 0x100
	s_addc_u32 s91, s91, 0
	s_add_u32 s36, s36, 0x100
	s_addc_u32 s37, s37, 0
	s_cmp_ge_u32 s92, s84
	s_mov_b32 s42, s92
	s_barrier
	s_cbranch_scc0 .LBB0_1179
	s_setprio 0
	s_lshl_b32 s3, s3, 8
	s_add_i32 s27, s3, s85
	v_lshl_or_b32 v210, s38, 8, v224
	v_or_b32_e32 v146, s27, v221
	v_ashrrev_i32_e32 v147, 31, v146
	v_ashrrev_i32_e32 v211, 31, v210
	v_lshlrev_b64 v[50:51], 2, v[210:211]
	v_lshl_add_u64 v[208:209], v[210:211], 1, s[48:49]
	v_lshlrev_b64 v[148:149], 11, v[146:147]
	v_lshl_add_u64 v[52:53], s[52:53], 0, v[50:51]
	v_lshl_add_u64 v[54:55], s[54:55], 0, v[50:51]
	v_lshl_add_u64 v[148:149], v[208:209], 0, v[148:149]
	global_load_dwordx4 v[74:77], v[52:53], off
	global_load_dwordx4 v[66:69], v[52:53], off offset:16
	global_load_dwordx4 v[78:81], v[54:55], off
	global_load_dwordx4 v[70:73], v[54:55], off offset:16
	global_load_dwordx4 v[58:61], v[52:53], off offset:512
	s_nop 0
	global_load_dwordx4 v[50:53], v[52:53], off offset:528
	s_nop 0
	global_load_dwordx4 v[62:65], v[54:55], off offset:512
	s_nop 0
	global_load_dwordx4 v[54:57], v[54:55], off offset:528
	global_load_dwordx4 v[190:193], v[148:149], off
	global_load_dwordx4 v[186:189], v[148:149], off offset:256
	v_or_b32_e32 v148, 16, v146
	v_ashrrev_i32_e32 v149, 31, v148
	v_lshlrev_b64 v[148:149], 11, v[148:149]
	v_lshl_add_u64 v[148:149], v[208:209], 0, v[148:149]
	global_load_dwordx4 v[182:185], v[148:149], off
	global_load_dwordx4 v[178:181], v[148:149], off offset:256
	v_or_b32_e32 v148, 32, v146
	v_or_b32_e32 v146, 48, v146
	v_ashrrev_i32_e32 v149, 31, v148
	v_ashrrev_i32_e32 v147, 31, v146
	v_lshlrev_b64 v[148:149], 11, v[148:149]
	v_lshlrev_b64 v[146:147], 11, v[146:147]
	v_mov_b32_e32 v1, v222
	v_lshl_add_u64 v[148:149], v[208:209], 0, v[148:149]
	v_lshl_add_u64 v[146:147], v[208:209], 0, v[146:147]
	global_load_dwordx4 v[174:177], v[148:149], off
	global_load_dwordx4 v[170:173], v[148:149], off offset:256
	global_load_dwordx4 v[154:157], v[146:147], off
	s_nop 0
	global_load_dwordx4 v[146:149], v[146:147], off offset:256
	v_cndmask_b32_e64 v211, 0, 1, s[56:57]
	v_cmp_ne_u32_e64 s[42:43], 1, v211
	s_andn2_b64 vcc, exec, s[56:57]
	v_lshl_add_u32 v231, v1, 3, s33
	s_cbranch_vccnz .LBB0_1182
	ds_read_b64 v[214:215], v231
	s_waitcnt lgkmcnt(0)
	v_mov_b32_e32 v212, v215
	s_branch .LBB0_1183
